# XB (bf16 residual stream copy) stored K-blocked: CONVERT store, INPROJ/FFN1/BRANCH-gate A operands, FFN2/OUTPROJ register epilogues
# speedup vs baseline: 1.1110x; 1.0325x over previous
; DI int TID() { int t = (int)__builtin_amdgcn_workitem_id_x(); asm volatile("" : "+v"(t)); return t; }
; DI int BID() { int b = (int)__builtin_amdgcn_workgroup_id_x(); asm volatile("" : "+s"(b)); return b; }
; DI unsigned pk2(float a, float b) { f2_t v = {a, b}; bf2_t r = __builtin_convertvector(v, bf2_t); return __builtin_bit_cast(unsigned, r); }
; DI void phase_convert(const Params& p, const Chunk& ck) {
;   const float* xsrc = chunk_xsrc(p, 0, ck);
;   u16* xb = (u16*)(p.ws + OFF_XB); float* ps = (float*)(p.ws + OFF_PSIN);
;   const int tid = TID(), lane = tid & 63, w = tid >> 6;
;   for (int row = BID() * 4 + w; row < CT; row += gridDim.x * 4) {
;     float ss = 0.f;
; #pragma unroll
;     for (int i = 0; i < 2; ++i) {
;       const int c = (lane + 64 * i) * 8;
;       const f32x4 a = *(const f32x4*)(xsrc + (size_t)row * 1024 + c), b = *(const f32x4*)(xsrc + (size_t)row * 1024 + c + 4);
;       ss += a[0] * a[0] + a[1] * a[1] + a[2] * a[2] + a[3] * a[3] + b[0] * b[0] + b[1] * b[1] + b[2] * b[2] + b[3] * b[3];
;       *(u32x4*)(xb + (size_t)row * 1024 + c) = u32x4{pk2(a[0], a[1]), pk2(a[2], a[3]), pk2(b[0], b[1]), pk2(b[2], b[3])};
;     }
; #pragma unroll
;     for (int o = 32; o >= 1; o >>= 1) ss += __shfl_xor(ss, o);
;     if (lane < 16) ps[(size_t)row * 16 + lane] = (lane == 0) ? ss : 0.f;
;   }
; }
; DI void run_phase(const Params& p, int ph, int l, int c, char* smem) {
;     ...
;     case PH_CONVERT: phase_convert(p, ck); break;
.LBB1_188:
	v_readlane_b32 s0, v255, 30
	s_cmp_lt_i32 s0, 5
	s_mov_b64 s[26:27], -1
	s_cbranch_scc1 .LBB1_274
	v_readlane_b32 s0, v255, 30
	s_cmp_lt_i32 s0, 7
	s_cbranch_scc1 .LBB1_258
	v_readlane_b32 s0, v255, 30
	s_cmp_lt_i32 s0, 8
	s_cbranch_scc1 .LBB1_251
	v_readlane_b32 s0, v255, 30
	s_cmp_gt_i32 s0, 9
	s_cbranch_scc0 .LBB1_198
	v_mov_b32_e32 v2, 0x8000
	v_mov_b32_e32 v0, s35
	v_sub_co_u32_e32 v2, vcc, s35, v2
	s_and_b64 s[16:17], vcc, exec
	s_nop 0
	v_cndmask_b32_e32 v0, v2, v0, vcc
	s_cselect_b32 s17, s25, s23
	s_cselect_b32 s16, s24, s22
	v_lshlrev_b64 v[2:3], 12, v[0:1]
	v_lshl_add_u64 v[6:7], s[16:17], 0, v[2:3]
	v_mov_b32_e32 v0, v172
	s_mov_b32 s0, s92
	s_nop 0
	v_ashrrev_i32_e32 v2, 6, v0
	v_lshl_add_u32 v2, s0, 2, v2
	s_movk_i32 s0, 0x4000
	v_cmp_gt_i32_e32 vcc, s0, v2
	s_and_saveexec_b64 s[22:23], vcc
	s_cbranch_execz .LBB1_197
	v_and_b32_e32 v3, 63, v0
	v_lshlrev_b32_e32 v0, 2, v3
	v_lshl_add_u64 v[4:5], s[18:19], 0, v[0:1]
	v_xor_b32_e32 v0, 32, v193
	v_cmp_lt_i32_e64 s[40:41], v0, v194
	s_mov_b64 s[16:17], 0x1e14c000
	v_lshl_add_u64 v[4:5], v[4:5], 0, s[16:17]
	v_cndmask_b32_e64 v0, v193, v0, s[40:41]
	v_cmp_lt_i32_e64 s[40:41], v196, v194
	v_lshlrev_b32_e32 v10, 2, v0
	s_mov_b64 s[16:17], 0x1c14c000
	v_cndmask_b32_e64 v0, v193, v196, s[40:41]
	v_cmp_lt_i32_e64 s[40:41], v197, v194
	v_lshlrev_b32_e32 v11, 2, v0
	v_cmp_gt_u32_e32 vcc, 16, v3
	v_cndmask_b32_e64 v0, v193, v197, s[40:41]
	v_cmp_lt_i32_e64 s[40:41], v198, v194
	v_lshlrev_b32_e32 v12, 2, v0
	v_cmp_eq_u32_e64 s[36:37], 0, v3
	v_cndmask_b32_e64 v0, v193, v198, s[40:41]
	v_cmp_lt_i32_e64 s[40:41], v199, v194
	v_lshlrev_b32_e32 v13, 2, v0
	s_mov_b64 s[24:25], 0
	v_cndmask_b32_e64 v0, v193, v199, s[40:41]
	v_cmp_lt_i32_e64 s[40:41], v200, v194
	v_lshlrev_b32_e32 v14, 2, v0
	s_nop 0
	v_cndmask_b32_e64 v0, v193, v200, s[40:41]
	v_lshlrev_b32_e32 v15, 2, v0
	v_lshlrev_b32_e32 v0, 5, v3
	v_lshl_add_u64 v[6:7], v[6:7], 0, v[0:1]
	v_and_b32_e32 v16, 3, v3
	v_lshlrev_b32_e32 v16, 4, v16
	v_lshrrev_b32_e32 v0, 2, v3
	v_lshl_or_b32 v0, v0, 20, v16
	v_lshl_add_u64 v[8:9], s[18:19], 0, v[0:1]
	v_lshl_add_u64 v[8:9], v[8:9], 0, s[16:17]
	s_mov_b64 s[16:17], 0x1000000
	s_branch .LBB1_195

; DI int BID() { int b = (int)__builtin_amdgcn_workgroup_id_x(); asm volatile("" : "+s"(b)); return b; }
; DI unsigned pk2(float a, float b) { f2_t v = {a, b}; bf2_t r = __builtin_convertvector(v, bf2_t); return __builtin_bit_cast(unsigned, r); }
; DI void phase_convert(const Params& p, const Chunk& ck) {
;     ...
;   for (int row = BID() * 4 + w; row < CT; row += gridDim.x * 4) {
;     float ss = 0.f;
; #pragma unroll
;     for (int i = 0; i < 2; ++i) {
;       const int c = (lane + 64 * i) * 8;
;       const f32x4 a = *(const f32x4*)(xsrc + (size_t)row * 1024 + c), b = *(const f32x4*)(xsrc + (size_t)row * 1024 + c + 4);
;       ss += a[0] * a[0] + a[1] * a[1] + a[2] * a[2] + a[3] * a[3] + b[0] * b[0] + b[1] * b[1] + b[2] * b[2] + b[3] * b[3];
;       *(u32x4*)(xb + (size_t)row * 1024 + c) = u32x4{pk2(a[0], a[1]), pk2(a[2], a[3]), pk2(b[0], b[1]), pk2(b[2], b[3])};
;     }
; #pragma unroll
;     for (int o = 32; o >= 1; o >>= 1) ss += __shfl_xor(ss, o);
;     if (lane < 16) ps[(size_t)row * 16 + lane] = (lane == 0) ? ss : 0.f;
;   }
.LBB1_195:
	v_ashrrev_i32_e32 v3, 31, v2
	s_waitcnt lgkmcnt(0)
	v_lshlrev_b64 v[16:17], 12, v[2:3]
	v_lshl_add_u64 v[24:25], v[6:7], 0, v[16:17]
	global_load_dwordx4 v[16:19], v[24:25], off offset:16
	global_load_dwordx4 v[20:23], v[24:25], off
	s_waitcnt vmcnt(0)
	v_mul_f32_e32 v0, v21, v21
	v_fmac_f32_e32 v0, v20, v20
	v_fmac_f32_e32 v0, v22, v22
	v_fmac_f32_e32 v0, v23, v23
	v_fmac_f32_e32 v0, v16, v16
	v_fmac_f32_e32 v0, v17, v17
	v_cvt_pk_bf16_f32 v20, v20, v21
	v_cvt_pk_bf16_f32 v21, v22, v23
	v_cvt_pk_bf16_f32 v22, v16, v17
	v_lshlrev_b64 v[16:17], 6, v[2:3]
	v_cvt_pk_bf16_f32 v23, v18, v19
	v_lshl_add_u64 v[26:27], v[8:9], 0, v[16:17]
	v_fmac_f32_e32 v0, v18, v18
	global_store_dwordx4 v[26:27], v[20:23], off
	v_fmac_f32_e32 v0, v19, v19
	global_load_dwordx4 v[16:19], v[24:25], off offset:2064
	global_load_dwordx4 v[20:23], v[24:25], off offset:2048
	s_waitcnt vmcnt(0)
	v_mul_f32_e32 v24, v21, v21
	v_fmac_f32_e32 v24, v20, v20
	v_fmac_f32_e32 v24, v22, v22
	v_fmac_f32_e32 v24, v23, v23
	v_fmac_f32_e32 v24, v16, v16
	v_fmac_f32_e32 v24, v17, v17
	v_fmac_f32_e32 v24, v18, v18
	v_fmac_f32_e32 v24, v19, v19
	v_add_f32_e32 v0, v0, v24
	v_cvt_pk_bf16_f32 v20, v20, v21
	v_cvt_pk_bf16_f32 v21, v22, v23
	v_cvt_pk_bf16_f32 v22, v16, v17
	ds_bpermute_b32 v16, v10, v0
	v_cvt_pk_bf16_f32 v23, v18, v19
	v_lshl_add_u64 v[26:27], v[26:27], 0, s[16:17]
	global_store_dwordx4 v[26:27], v[20:23], off
	s_waitcnt lgkmcnt(0)
	v_add_f32_e32 v0, v0, v16
	ds_bpermute_b32 v16, v11, v0
	s_waitcnt lgkmcnt(0)
	v_add_f32_e32 v0, v0, v16
	ds_bpermute_b32 v16, v12, v0
	s_waitcnt lgkmcnt(0)
	v_add_f32_e32 v0, v0, v16
	ds_bpermute_b32 v16, v13, v0
	s_waitcnt lgkmcnt(0)
	v_add_f32_e32 v0, v0, v16
	ds_bpermute_b32 v16, v14, v0
	s_waitcnt lgkmcnt(0)
	v_add_f32_e32 v0, v0, v16
	ds_bpermute_b32 v16, v15, v0
	s_and_saveexec_b64 s[26:27], vcc
	s_cbranch_execz .LBB1_194
	v_lshlrev_b64 v[18:19], 6, v[2:3]
	s_waitcnt lgkmcnt(0)
	v_add_f32_e32 v0, v0, v16
	v_lshl_add_u64 v[18:19], v[4:5], 0, v[18:19]
	v_cndmask_b32_e64 v0, 0, v0, s[36:37]
	global_store_dword v[18:19], v0, off
	s_branch .LBB1_194

; DI u32x4 pack8(const float (&v)[8]) { u32x4 r = {pk2(v[0], v[1]), pk2(v[2], v[3]), pk2(v[4], v[5]), pk2(v[6], v[7])}; return r; }
; DI void tile_ffn2(const Params& p, int l, const Chunk& ck, int tile, int next, PF& pf, char* smem) {
;     ...
;   const int row = tid >> 1, half = tid & 1; float ssq = 0.f;
;   float* xd = p.out + (size_t)(ck.tok0 + m0 + row) * 1024 + n0 + half * 64;
;   u16* xb = (u16*)(p.ws + OFF_XB) + (size_t)(m0 + row) * 1024 + n0 + half * 64;
; #pragma unroll
;   for (int c8 = 0; c8 < 8; ++c8) {
;     float v[8], x[8]; cs_ld8(Cs, row, half * 64 + c8 * 8, v); unpack8(*(const u32x4*)(xb + c8 * 8), x);
; #pragma unroll
;     for (int j = 0; j < 8; ++j) { v[j] += x[j]; ssq += v[j] * v[j]; }
;     if (l == 0) *(u32x4*)(xb + c8 * 8) = pack8(v);
;     else { *(f32x4*)(xd + c8 * 8) = f32x4{v[0], v[1], v[2], v[3]}; *(f32x4*)(xd + c8 * 8 + 4) = f32x4{v[4], v[5], v[6], v[7]}; }
;   }
;   if (l == 0) ((float*)(p.ws + OFF_PSIN))[(size_t)(m0 + row) * 16 + ni * 2 + half] = ssq;
.LBB1_208:
	s_and_b32 s0, s24, 0x3f80
	v_and_b32_e32 v160, 63, v172
	v_lshrrev_b32_e32 v161, 6, v172
	v_and_b32_e32 v162, 15, v160
	v_lshrrev_b32_e32 v163, 4, v160
	v_lshrrev_b32_e32 v167, 1, v161
	v_lshl_add_u32 v167, v167, 6, v162
	v_and_b32_e32 v168, 1, v161
	v_lshlrev_b32_e32 v169, 6, v168
	v_lshl_add_u32 v169, v163, 2, v169
	v_add_u32_e32 v169, s36, v169
	v_add_u32_e32 v170, s0, v167
	v_lshlrev_b32_e32 v164, 6, v170
	v_lshl_add_u32 v164, v163, 3, v164
	v_lshrrev_b32_e32 v122, 5, v169
	v_lshl_add_u32 v164, v122, 20, v164
	v_add_u32_e32 v122, 0x100000, v164
	v_lshlrev_b32_e32 v165, 12, v167
	v_lshl_add_u32 v165, v169, 2, v165
	v_lshlrev_b32_e32 v166, 6, v170
	v_lshl_add_u32 v166, v168, 2, v166
	s_add_i32 s0, s0, s35
	s_lshl_b32 s0, s0, 12
	s_add_u32 s12, s20, s0
	s_addc_u32 s13, s21, 0
	s_lshr_b32 s0, s36, 4
	s_add_u32 s14, s52, s0
	s_addc_u32 s15, s53, 0
	s_and_b64 vcc, exec, s[22:23]
	s_cbranch_vccnz .Lffn2_l1
	global_load_dwordx2 v[224:225], v164, s[50:51] offset:0
	global_load_dwordx2 v[226:227], v164, s[50:51] offset:32
	global_load_dwordx2 v[228:229], v122, s[50:51] offset:0
	global_load_dwordx2 v[230:231], v122, s[50:51] offset:32
	global_load_dwordx2 v[232:233], v164, s[50:51] offset:1024
	global_load_dwordx2 v[234:235], v164, s[50:51] offset:1056
	global_load_dwordx2 v[236:237], v122, s[50:51] offset:1024
	global_load_dwordx2 v[238:239], v122, s[50:51] offset:1056
	global_load_dwordx2 v[240:241], v164, s[50:51] offset:2048
	global_load_dwordx2 v[242:243], v164, s[50:51] offset:2080
	global_load_dwordx2 v[244:245], v122, s[50:51] offset:2048
	global_load_dwordx2 v[246:247], v122, s[50:51] offset:2080
	global_load_dwordx2 v[248:249], v164, s[50:51] offset:3072
	global_load_dwordx2 v[250:251], v164, s[50:51] offset:3104
	global_load_dwordx2 v[156:157], v122, s[50:51] offset:3072
	global_load_dwordx2 v[158:159], v122, s[50:51] offset:3104
	s_waitcnt vmcnt(0)
	v_mov_b32_e32 v171, 0
	v_lshlrev_b32_e32 v167, 16, v224
	v_and_b32_e32 v168, 0xffff0000, v224
	v_lshlrev_b32_e32 v169, 16, v225
	v_and_b32_e32 v170, 0xffff0000, v225
	v_add_f32_e32 v2, v2, v167
	v_add_f32_e32 v3, v3, v168
	v_add_f32_e32 v4, v4, v169
	v_add_f32_e32 v5, v5, v170
	v_fma_f32 v171, v2, v2, v171
	v_fma_f32 v171, v3, v3, v171
	v_fma_f32 v171, v4, v4, v171
	v_fma_f32 v171, v5, v5, v171
	v_cvt_pk_bf16_f32 v2, v2, v3
	v_cvt_pk_bf16_f32 v3, v4, v5
	global_store_dwordx2 v164, v[2:3], s[50:51]
	v_lshlrev_b32_e32 v167, 16, v226
	v_and_b32_e32 v168, 0xffff0000, v226
	v_lshlrev_b32_e32 v169, 16, v227
	v_and_b32_e32 v170, 0xffff0000, v227
	v_add_f32_e32 v6, v6, v167
	v_add_f32_e32 v7, v7, v168
	v_add_f32_e32 v8, v8, v169
	v_add_f32_e32 v9, v9, v170
	v_fma_f32 v171, v6, v6, v171
	v_fma_f32 v171, v7, v7, v171
	v_fma_f32 v171, v8, v8, v171
	v_fma_f32 v171, v9, v9, v171
	v_cvt_pk_bf16_f32 v6, v6, v7
	v_cvt_pk_bf16_f32 v7, v8, v9
	global_store_dwordx2 v164, v[6:7], s[50:51] offset:32
	v_lshlrev_b32_e32 v167, 16, v228
	v_and_b32_e32 v168, 0xffff0000, v228
	v_lshlrev_b32_e32 v169, 16, v229
	v_and_b32_e32 v170, 0xffff0000, v229
	v_add_f32_e32 v10, v10, v167
	v_add_f32_e32 v11, v11, v168
	v_add_f32_e32 v12, v12, v169
	v_add_f32_e32 v13, v13, v170
	v_fma_f32 v171, v10, v10, v171
	v_fma_f32 v171, v11, v11, v171
	v_fma_f32 v171, v12, v12, v171
	v_fma_f32 v171, v13, v13, v171
	v_cvt_pk_bf16_f32 v10, v10, v11
	v_cvt_pk_bf16_f32 v11, v12, v13
	global_store_dwordx2 v122, v[10:11], s[50:51]
	v_lshlrev_b32_e32 v167, 16, v230
	v_and_b32_e32 v168, 0xffff0000, v230
	v_lshlrev_b32_e32 v169, 16, v231
	v_and_b32_e32 v170, 0xffff0000, v231
	v_add_f32_e32 v14, v14, v167
	v_add_f32_e32 v15, v15, v168
	v_add_f32_e32 v16, v16, v169
	v_add_f32_e32 v17, v17, v170
	v_fma_f32 v171, v14, v14, v171
	v_fma_f32 v171, v15, v15, v171
	v_fma_f32 v171, v16, v16, v171
	v_fma_f32 v171, v17, v17, v171
	v_cvt_pk_bf16_f32 v14, v14, v15
	v_cvt_pk_bf16_f32 v15, v16, v17
	global_store_dwordx2 v122, v[14:15], s[50:51] offset:32
	v_mov_b32_e32 v167, v171
	s_nop 1
	v_permlane32_swap_b32_e32 v171, v167
	v_add_f32_e32 v171, v171, v167
	ds_swizzle_b32 v167, v171 offset:0x401f
	s_waitcnt lgkmcnt(0)
	v_add_f32_e32 v171, v171, v167
	v_cmp_gt_u32_e32 vcc, 16, v160
	s_and_saveexec_b64 s[98:99], vcc
	global_store_dword v166, v171, s[14:15] offset:0
	s_or_b64 exec, exec, s[98:99]
	v_mov_b32_e32 v171, 0
	v_lshlrev_b32_e32 v167, 16, v232
	v_and_b32_e32 v168, 0xffff0000, v232
	v_lshlrev_b32_e32 v169, 16, v233
	v_and_b32_e32 v170, 0xffff0000, v233
	v_add_f32_e32 v18, v18, v167
	v_add_f32_e32 v19, v19, v168
	v_add_f32_e32 v20, v20, v169
	v_add_f32_e32 v21, v21, v170
	v_fma_f32 v171, v18, v18, v171
	v_fma_f32 v171, v19, v19, v171
	v_fma_f32 v171, v20, v20, v171
	v_fma_f32 v171, v21, v21, v171
	v_cvt_pk_bf16_f32 v18, v18, v19
	v_cvt_pk_bf16_f32 v19, v20, v21
	global_store_dwordx2 v164, v[18:19], s[50:51] offset:1024
	v_lshlrev_b32_e32 v167, 16, v234
	v_and_b32_e32 v168, 0xffff0000, v234
	v_lshlrev_b32_e32 v169, 16, v235
	v_and_b32_e32 v170, 0xffff0000, v235
	v_add_f32_e32 v22, v22, v167
	v_add_f32_e32 v23, v23, v168
	v_add_f32_e32 v24, v24, v169
	v_add_f32_e32 v25, v25, v170
	v_fma_f32 v171, v22, v22, v171
	v_fma_f32 v171, v23, v23, v171
	v_fma_f32 v171, v24, v24, v171
	v_fma_f32 v171, v25, v25, v171
	v_cvt_pk_bf16_f32 v22, v22, v23
	v_cvt_pk_bf16_f32 v23, v24, v25
	global_store_dwordx2 v164, v[22:23], s[50:51] offset:1056
	v_lshlrev_b32_e32 v167, 16, v236
	v_and_b32_e32 v168, 0xffff0000, v236
	v_lshlrev_b32_e32 v169, 16, v237
	v_and_b32_e32 v170, 0xffff0000, v237
	v_add_f32_e32 v26, v26, v167
	v_add_f32_e32 v27, v27, v168
	v_add_f32_e32 v28, v28, v169
	v_add_f32_e32 v29, v29, v170
	v_fma_f32 v171, v26, v26, v171
	v_fma_f32 v171, v27, v27, v171
	v_fma_f32 v171, v28, v28, v171
	v_fma_f32 v171, v29, v29, v171
	v_cvt_pk_bf16_f32 v26, v26, v27
	v_cvt_pk_bf16_f32 v27, v28, v29
	global_store_dwordx2 v122, v[26:27], s[50:51] offset:1024
	v_lshlrev_b32_e32 v167, 16, v238
	v_and_b32_e32 v168, 0xffff0000, v238
	v_lshlrev_b32_e32 v169, 16, v239
	v_and_b32_e32 v170, 0xffff0000, v239
	v_add_f32_e32 v30, v30, v167
	v_add_f32_e32 v31, v31, v168
	v_add_f32_e32 v32, v32, v169
	v_add_f32_e32 v33, v33, v170
	v_fma_f32 v171, v30, v30, v171
	v_fma_f32 v171, v31, v31, v171
	v_fma_f32 v171, v32, v32, v171
	v_fma_f32 v171, v33, v33, v171
	v_cvt_pk_bf16_f32 v30, v30, v31
	v_cvt_pk_bf16_f32 v31, v32, v33
	global_store_dwordx2 v122, v[30:31], s[50:51] offset:1056
	v_mov_b32_e32 v167, v171
	s_nop 1
	v_permlane32_swap_b32_e32 v171, v167
	v_add_f32_e32 v171, v171, v167
	ds_swizzle_b32 v167, v171 offset:0x401f
	s_waitcnt lgkmcnt(0)
; DI u32x4 pack8(const float (&v)[8]) { u32x4 r = {pk2(v[0], v[1]), pk2(v[2], v[3]), pk2(v[4], v[5]), pk2(v[6], v[7])}; return r; }
; DI void tile_ffn2(const Params& p, int l, const Chunk& ck, int tile, int next, PF& pf, char* smem) {
;     ...
;   const int row = tid >> 1, half = tid & 1; float ssq = 0.f;
;   float* xd = p.out + (size_t)(ck.tok0 + m0 + row) * 1024 + n0 + half * 64;
;   u16* xb = (u16*)(p.ws + OFF_XB) + (size_t)(m0 + row) * 1024 + n0 + half * 64;
; #pragma unroll
;   for (int c8 = 0; c8 < 8; ++c8) {
;     float v[8], x[8]; cs_ld8(Cs, row, half * 64 + c8 * 8, v); unpack8(*(const u32x4*)(xb + c8 * 8), x);
; #pragma unroll
;     for (int j = 0; j < 8; ++j) { v[j] += x[j]; ssq += v[j] * v[j]; }
;     if (l == 0) *(u32x4*)(xb + c8 * 8) = pack8(v);
;     else { *(f32x4*)(xd + c8 * 8) = f32x4{v[0], v[1], v[2], v[3]}; *(f32x4*)(xd + c8 * 8 + 4) = f32x4{v[4], v[5], v[6], v[7]}; }
;   }
;   if (l == 0) ((float*)(p.ws + OFF_PSIN))[(size_t)(m0 + row) * 16 + ni * 2 + half] = ssq;
	v_add_f32_e32 v171, v171, v167
	v_cmp_gt_u32_e32 vcc, 16, v160
	s_and_saveexec_b64 s[98:99], vcc
	global_store_dword v166, v171, s[14:15] offset:1024
	s_or_b64 exec, exec, s[98:99]
	v_mov_b32_e32 v171, 0
	v_lshlrev_b32_e32 v167, 16, v240
	v_and_b32_e32 v168, 0xffff0000, v240
	v_lshlrev_b32_e32 v169, 16, v241
	v_and_b32_e32 v170, 0xffff0000, v241
	v_add_f32_e32 v34, v34, v167
	v_add_f32_e32 v35, v35, v168
	v_add_f32_e32 v36, v36, v169
	v_add_f32_e32 v37, v37, v170
	v_fma_f32 v171, v34, v34, v171
	v_fma_f32 v171, v35, v35, v171
	v_fma_f32 v171, v36, v36, v171
	v_fma_f32 v171, v37, v37, v171
	v_cvt_pk_bf16_f32 v34, v34, v35
	v_cvt_pk_bf16_f32 v35, v36, v37
	global_store_dwordx2 v164, v[34:35], s[50:51] offset:2048
	v_lshlrev_b32_e32 v167, 16, v242
	v_and_b32_e32 v168, 0xffff0000, v242
	v_lshlrev_b32_e32 v169, 16, v243
	v_and_b32_e32 v170, 0xffff0000, v243
	v_add_f32_e32 v38, v38, v167
	v_add_f32_e32 v39, v39, v168
	v_add_f32_e32 v40, v40, v169
	v_add_f32_e32 v41, v41, v170
	v_fma_f32 v171, v38, v38, v171
	v_fma_f32 v171, v39, v39, v171
	v_fma_f32 v171, v40, v40, v171
	v_fma_f32 v171, v41, v41, v171
	v_cvt_pk_bf16_f32 v38, v38, v39
	v_cvt_pk_bf16_f32 v39, v40, v41
	global_store_dwordx2 v164, v[38:39], s[50:51] offset:2080
	v_lshlrev_b32_e32 v167, 16, v244
	v_and_b32_e32 v168, 0xffff0000, v244
	v_lshlrev_b32_e32 v169, 16, v245
	v_and_b32_e32 v170, 0xffff0000, v245
	v_add_f32_e32 v42, v42, v167
	v_add_f32_e32 v43, v43, v168
	v_add_f32_e32 v44, v44, v169
	v_add_f32_e32 v45, v45, v170
	v_fma_f32 v171, v42, v42, v171
	v_fma_f32 v171, v43, v43, v171
	v_fma_f32 v171, v44, v44, v171
	v_fma_f32 v171, v45, v45, v171
	v_cvt_pk_bf16_f32 v42, v42, v43
	v_cvt_pk_bf16_f32 v43, v44, v45
	global_store_dwordx2 v122, v[42:43], s[50:51] offset:2048
	v_lshlrev_b32_e32 v167, 16, v246
	v_and_b32_e32 v168, 0xffff0000, v246
	v_lshlrev_b32_e32 v169, 16, v247
	v_and_b32_e32 v170, 0xffff0000, v247
	v_add_f32_e32 v46, v46, v167
	v_add_f32_e32 v47, v47, v168
	v_add_f32_e32 v48, v48, v169
	v_add_f32_e32 v49, v49, v170
	v_fma_f32 v171, v46, v46, v171
	v_fma_f32 v171, v47, v47, v171
	v_fma_f32 v171, v48, v48, v171
	v_fma_f32 v171, v49, v49, v171
	v_cvt_pk_bf16_f32 v46, v46, v47
	v_cvt_pk_bf16_f32 v47, v48, v49
	global_store_dwordx2 v122, v[46:47], s[50:51] offset:2080
	v_mov_b32_e32 v167, v171
	s_nop 1
	v_permlane32_swap_b32_e32 v171, v167
	v_add_f32_e32 v171, v171, v167
	ds_swizzle_b32 v167, v171 offset:0x401f
	s_waitcnt lgkmcnt(0)
	v_add_f32_e32 v171, v171, v167
	v_cmp_gt_u32_e32 vcc, 16, v160
	s_and_saveexec_b64 s[98:99], vcc
	global_store_dword v166, v171, s[14:15] offset:2048
	s_or_b64 exec, exec, s[98:99]
	v_mov_b32_e32 v171, 0
	v_lshlrev_b32_e32 v167, 16, v248
	v_and_b32_e32 v168, 0xffff0000, v248
	v_lshlrev_b32_e32 v169, 16, v249
	v_and_b32_e32 v170, 0xffff0000, v249
	v_add_f32_e32 v50, v50, v167
	v_add_f32_e32 v51, v51, v168
	v_add_f32_e32 v52, v52, v169
	v_add_f32_e32 v53, v53, v170
	v_fma_f32 v171, v50, v50, v171
	v_fma_f32 v171, v51, v51, v171
	v_fma_f32 v171, v52, v52, v171
	v_fma_f32 v171, v53, v53, v171
	v_cvt_pk_bf16_f32 v50, v50, v51
	v_cvt_pk_bf16_f32 v51, v52, v53
	global_store_dwordx2 v164, v[50:51], s[50:51] offset:3072
	v_lshlrev_b32_e32 v167, 16, v250
	v_and_b32_e32 v168, 0xffff0000, v250
	v_lshlrev_b32_e32 v169, 16, v251
	v_and_b32_e32 v170, 0xffff0000, v251
	v_add_f32_e32 v54, v54, v167
	v_add_f32_e32 v55, v55, v168
	v_add_f32_e32 v56, v56, v169
	v_add_f32_e32 v57, v57, v170
	v_fma_f32 v171, v54, v54, v171
	v_fma_f32 v171, v55, v55, v171
	v_fma_f32 v171, v56, v56, v171
	v_fma_f32 v171, v57, v57, v171
	v_cvt_pk_bf16_f32 v54, v54, v55
	v_cvt_pk_bf16_f32 v55, v56, v57
	global_store_dwordx2 v164, v[54:55], s[50:51] offset:3104
	v_lshlrev_b32_e32 v167, 16, v156
	v_and_b32_e32 v168, 0xffff0000, v156
	v_lshlrev_b32_e32 v169, 16, v157
	v_and_b32_e32 v170, 0xffff0000, v157
	v_add_f32_e32 v58, v58, v167
	v_add_f32_e32 v59, v59, v168
	v_add_f32_e32 v60, v60, v169
	v_add_f32_e32 v61, v61, v170
	v_fma_f32 v171, v58, v58, v171
	v_fma_f32 v171, v59, v59, v171
	v_fma_f32 v171, v60, v60, v171
	v_fma_f32 v171, v61, v61, v171
	v_cvt_pk_bf16_f32 v58, v58, v59
	v_cvt_pk_bf16_f32 v59, v60, v61
	global_store_dwordx2 v122, v[58:59], s[50:51] offset:3072
	v_lshlrev_b32_e32 v167, 16, v158
	v_and_b32_e32 v168, 0xffff0000, v158
	v_lshlrev_b32_e32 v169, 16, v159
	v_and_b32_e32 v170, 0xffff0000, v159
	v_add_f32_e32 v62, v62, v167
	v_add_f32_e32 v63, v63, v168
	v_add_f32_e32 v64, v64, v169
	v_add_f32_e32 v65, v65, v170
	v_fma_f32 v171, v62, v62, v171
	v_fma_f32 v171, v63, v63, v171
	v_fma_f32 v171, v64, v64, v171
	v_fma_f32 v171, v65, v65, v171
	v_cvt_pk_bf16_f32 v62, v62, v63
	v_cvt_pk_bf16_f32 v63, v64, v65
	global_store_dwordx2 v122, v[62:63], s[50:51] offset:3104
	v_mov_b32_e32 v167, v171
	s_nop 1
	v_permlane32_swap_b32_e32 v171, v167
	v_add_f32_e32 v171, v171, v167
	ds_swizzle_b32 v167, v171 offset:0x401f
	s_waitcnt lgkmcnt(0)
	v_add_f32_e32 v171, v171, v167
	v_cmp_gt_u32_e32 vcc, 16, v160
	s_and_saveexec_b64 s[98:99], vcc
	global_store_dword v166, v171, s[14:15] offset:3072
	s_or_b64 exec, exec, s[98:99]
	v_add_u32_e32 v164, 0x400000, v164
	v_add_u32_e32 v122, 0x400000, v122
	global_load_dwordx2 v[224:225], v164, s[50:51] offset:0
	global_load_dwordx2 v[226:227], v164, s[50:51] offset:32
	global_load_dwordx2 v[228:229], v122, s[50:51] offset:0
	global_load_dwordx2 v[230:231], v122, s[50:51] offset:32
	global_load_dwordx2 v[232:233], v164, s[50:51] offset:1024
	global_load_dwordx2 v[234:235], v164, s[50:51] offset:1056
	global_load_dwordx2 v[236:237], v122, s[50:51] offset:1024
	global_load_dwordx2 v[238:239], v122, s[50:51] offset:1056
	global_load_dwordx2 v[240:241], v164, s[50:51] offset:2048
	global_load_dwordx2 v[242:243], v164, s[50:51] offset:2080
	global_load_dwordx2 v[244:245], v122, s[50:51] offset:2048
	global_load_dwordx2 v[246:247], v122, s[50:51] offset:2080
	global_load_dwordx2 v[248:249], v164, s[50:51] offset:3072
	global_load_dwordx2 v[250:251], v164, s[50:51] offset:3104
	global_load_dwordx2 v[156:157], v122, s[50:51] offset:3072
	global_load_dwordx2 v[158:159], v122, s[50:51] offset:3104
	s_waitcnt vmcnt(0)
; DI u32x4 pack8(const float (&v)[8]) { u32x4 r = {pk2(v[0], v[1]), pk2(v[2], v[3]), pk2(v[4], v[5]), pk2(v[6], v[7])}; return r; }
; DI void tile_ffn2(const Params& p, int l, const Chunk& ck, int tile, int next, PF& pf, char* smem) {
;     ...
;   const int row = tid >> 1, half = tid & 1; float ssq = 0.f;
;   float* xd = p.out + (size_t)(ck.tok0 + m0 + row) * 1024 + n0 + half * 64;
;   u16* xb = (u16*)(p.ws + OFF_XB) + (size_t)(m0 + row) * 1024 + n0 + half * 64;
; #pragma unroll
;   for (int c8 = 0; c8 < 8; ++c8) {
;     float v[8], x[8]; cs_ld8(Cs, row, half * 64 + c8 * 8, v); unpack8(*(const u32x4*)(xb + c8 * 8), x);
; #pragma unroll
;     for (int j = 0; j < 8; ++j) { v[j] += x[j]; ssq += v[j] * v[j]; }
;     if (l == 0) *(u32x4*)(xb + c8 * 8) = pack8(v);
;     else { *(f32x4*)(xd + c8 * 8) = f32x4{v[0], v[1], v[2], v[3]}; *(f32x4*)(xd + c8 * 8 + 4) = f32x4{v[4], v[5], v[6], v[7]}; }
;   }
;   if (l == 0) ((float*)(p.ws + OFF_PSIN))[(size_t)(m0 + row) * 16 + ni * 2 + half] = ssq;
	v_mov_b32_e32 v171, 0
	v_lshlrev_b32_e32 v167, 16, v224
	v_and_b32_e32 v168, 0xffff0000, v224
	v_lshlrev_b32_e32 v169, 16, v225
	v_and_b32_e32 v170, 0xffff0000, v225
	v_add_f32_e32 v74, v74, v167
	v_add_f32_e32 v75, v75, v168
	v_add_f32_e32 v76, v76, v169
	v_add_f32_e32 v77, v77, v170
	v_fma_f32 v171, v74, v74, v171
	v_fma_f32 v171, v75, v75, v171
	v_fma_f32 v171, v76, v76, v171
	v_fma_f32 v171, v77, v77, v171
	v_cvt_pk_bf16_f32 v74, v74, v75
	v_cvt_pk_bf16_f32 v75, v76, v77
	global_store_dwordx2 v164, v[74:75], s[50:51]
	v_lshlrev_b32_e32 v167, 16, v226
	v_and_b32_e32 v168, 0xffff0000, v226
	v_lshlrev_b32_e32 v169, 16, v227
	v_and_b32_e32 v170, 0xffff0000, v227
	v_add_f32_e32 v78, v78, v167
	v_add_f32_e32 v79, v79, v168
	v_add_f32_e32 v80, v80, v169
	v_add_f32_e32 v81, v81, v170
	v_fma_f32 v171, v78, v78, v171
	v_fma_f32 v171, v79, v79, v171
	v_fma_f32 v171, v80, v80, v171
	v_fma_f32 v171, v81, v81, v171
	v_cvt_pk_bf16_f32 v78, v78, v79
	v_cvt_pk_bf16_f32 v79, v80, v81
	global_store_dwordx2 v164, v[78:79], s[50:51] offset:32
	v_lshlrev_b32_e32 v167, 16, v228
	v_and_b32_e32 v168, 0xffff0000, v228
	v_lshlrev_b32_e32 v169, 16, v229
	v_and_b32_e32 v170, 0xffff0000, v229
	v_add_f32_e32 v82, v82, v167
	v_add_f32_e32 v83, v83, v168
	v_add_f32_e32 v84, v84, v169
	v_add_f32_e32 v85, v85, v170
	v_fma_f32 v171, v82, v82, v171
	v_fma_f32 v171, v83, v83, v171
	v_fma_f32 v171, v84, v84, v171
	v_fma_f32 v171, v85, v85, v171
	v_cvt_pk_bf16_f32 v82, v82, v83
	v_cvt_pk_bf16_f32 v83, v84, v85
	global_store_dwordx2 v122, v[82:83], s[50:51]
	v_lshlrev_b32_e32 v167, 16, v230
	v_and_b32_e32 v168, 0xffff0000, v230
	v_lshlrev_b32_e32 v169, 16, v231
	v_and_b32_e32 v170, 0xffff0000, v231
	v_add_f32_e32 v86, v86, v167
	v_add_f32_e32 v87, v87, v168
	v_add_f32_e32 v88, v88, v169
	v_add_f32_e32 v89, v89, v170
	v_fma_f32 v171, v86, v86, v171
	v_fma_f32 v171, v87, v87, v171
	v_fma_f32 v171, v88, v88, v171
	v_fma_f32 v171, v89, v89, v171
	v_cvt_pk_bf16_f32 v86, v86, v87
	v_cvt_pk_bf16_f32 v87, v88, v89
	global_store_dwordx2 v122, v[86:87], s[50:51] offset:32
	v_mov_b32_e32 v167, v171
	s_nop 1
	v_permlane32_swap_b32_e32 v171, v167
	v_add_f32_e32 v171, v171, v167
	ds_swizzle_b32 v167, v171 offset:0x401f
	s_waitcnt lgkmcnt(0)
	v_add_f32_e32 v171, v171, v167
	v_cmp_gt_u32_e32 vcc, 16, v160
	s_and_saveexec_b64 s[98:99], vcc
	global_store_dword v166, v171, s[14:15] offset:8
	s_or_b64 exec, exec, s[98:99]
	v_mov_b32_e32 v171, 0
	v_lshlrev_b32_e32 v167, 16, v232
	v_and_b32_e32 v168, 0xffff0000, v232
	v_lshlrev_b32_e32 v169, 16, v233
	v_and_b32_e32 v170, 0xffff0000, v233
	v_add_f32_e32 v90, v90, v167
	v_add_f32_e32 v91, v91, v168
	v_add_f32_e32 v92, v92, v169
	v_add_f32_e32 v93, v93, v170
	v_fma_f32 v171, v90, v90, v171
	v_fma_f32 v171, v91, v91, v171
	v_fma_f32 v171, v92, v92, v171
	v_fma_f32 v171, v93, v93, v171
	v_cvt_pk_bf16_f32 v90, v90, v91
	v_cvt_pk_bf16_f32 v91, v92, v93
	global_store_dwordx2 v164, v[90:91], s[50:51] offset:1024
	v_lshlrev_b32_e32 v167, 16, v234
	v_and_b32_e32 v168, 0xffff0000, v234
	v_lshlrev_b32_e32 v169, 16, v235
	v_and_b32_e32 v170, 0xffff0000, v235
	v_add_f32_e32 v94, v94, v167
	v_add_f32_e32 v95, v95, v168
	v_add_f32_e32 v96, v96, v169
	v_add_f32_e32 v97, v97, v170
	v_fma_f32 v171, v94, v94, v171
	v_fma_f32 v171, v95, v95, v171
	v_fma_f32 v171, v96, v96, v171
	v_fma_f32 v171, v97, v97, v171
	v_cvt_pk_bf16_f32 v94, v94, v95
	v_cvt_pk_bf16_f32 v95, v96, v97
	global_store_dwordx2 v164, v[94:95], s[50:51] offset:1056
	v_lshlrev_b32_e32 v167, 16, v236
	v_and_b32_e32 v168, 0xffff0000, v236
	v_lshlrev_b32_e32 v169, 16, v237
	v_and_b32_e32 v170, 0xffff0000, v237
	v_add_f32_e32 v98, v98, v167
	v_add_f32_e32 v99, v99, v168
	v_add_f32_e32 v100, v100, v169
	v_add_f32_e32 v101, v101, v170
	v_fma_f32 v171, v98, v98, v171
	v_fma_f32 v171, v99, v99, v171
	v_fma_f32 v171, v100, v100, v171
	v_fma_f32 v171, v101, v101, v171
	v_cvt_pk_bf16_f32 v98, v98, v99
	v_cvt_pk_bf16_f32 v99, v100, v101
	global_store_dwordx2 v122, v[98:99], s[50:51] offset:1024
	v_lshlrev_b32_e32 v167, 16, v238
	v_and_b32_e32 v168, 0xffff0000, v238
	v_lshlrev_b32_e32 v169, 16, v239
	v_and_b32_e32 v170, 0xffff0000, v239
	v_add_f32_e32 v102, v102, v167
	v_add_f32_e32 v103, v103, v168
	v_add_f32_e32 v104, v104, v169
	v_add_f32_e32 v105, v105, v170
	v_fma_f32 v171, v102, v102, v171
	v_fma_f32 v171, v103, v103, v171
	v_fma_f32 v171, v104, v104, v171
	v_fma_f32 v171, v105, v105, v171
	v_cvt_pk_bf16_f32 v102, v102, v103
	v_cvt_pk_bf16_f32 v103, v104, v105
	global_store_dwordx2 v122, v[102:103], s[50:51] offset:1056
	v_mov_b32_e32 v167, v171
	s_nop 1
	v_permlane32_swap_b32_e32 v171, v167
	v_add_f32_e32 v171, v171, v167
	ds_swizzle_b32 v167, v171 offset:0x401f
	s_waitcnt lgkmcnt(0)
; DI u32x4 pack8(const float (&v)[8]) { u32x4 r = {pk2(v[0], v[1]), pk2(v[2], v[3]), pk2(v[4], v[5]), pk2(v[6], v[7])}; return r; }
; DI void tile_ffn2(const Params& p, int l, const Chunk& ck, int tile, int next, PF& pf, char* smem) {
;     ...
;   const int row = tid >> 1, half = tid & 1; float ssq = 0.f;
;   float* xd = p.out + (size_t)(ck.tok0 + m0 + row) * 1024 + n0 + half * 64;
;   u16* xb = (u16*)(p.ws + OFF_XB) + (size_t)(m0 + row) * 1024 + n0 + half * 64;
; #pragma unroll
;   for (int c8 = 0; c8 < 8; ++c8) {
;     float v[8], x[8]; cs_ld8(Cs, row, half * 64 + c8 * 8, v); unpack8(*(const u32x4*)(xb + c8 * 8), x);
; #pragma unroll
;     for (int j = 0; j < 8; ++j) { v[j] += x[j]; ssq += v[j] * v[j]; }
;     if (l == 0) *(u32x4*)(xb + c8 * 8) = pack8(v);
;     else { *(f32x4*)(xd + c8 * 8) = f32x4{v[0], v[1], v[2], v[3]}; *(f32x4*)(xd + c8 * 8 + 4) = f32x4{v[4], v[5], v[6], v[7]}; }
;   }
;   if (l == 0) ((float*)(p.ws + OFF_PSIN))[(size_t)(m0 + row) * 16 + ni * 2 + half] = ssq;
	v_add_f32_e32 v171, v171, v167
	v_cmp_gt_u32_e32 vcc, 16, v160
	s_and_saveexec_b64 s[98:99], vcc
	global_store_dword v166, v171, s[14:15] offset:1032
	s_or_b64 exec, exec, s[98:99]
	v_mov_b32_e32 v171, 0
	v_lshlrev_b32_e32 v167, 16, v240
	v_and_b32_e32 v168, 0xffff0000, v240
	v_lshlrev_b32_e32 v169, 16, v241
	v_and_b32_e32 v170, 0xffff0000, v241
	v_add_f32_e32 v106, v106, v167
	v_add_f32_e32 v107, v107, v168
	v_add_f32_e32 v108, v108, v169
	v_add_f32_e32 v109, v109, v170
	v_fma_f32 v171, v106, v106, v171
	v_fma_f32 v171, v107, v107, v171
	v_fma_f32 v171, v108, v108, v171
	v_fma_f32 v171, v109, v109, v171
	v_cvt_pk_bf16_f32 v106, v106, v107
	v_cvt_pk_bf16_f32 v107, v108, v109
	global_store_dwordx2 v164, v[106:107], s[50:51] offset:2048
	v_lshlrev_b32_e32 v167, 16, v242
	v_and_b32_e32 v168, 0xffff0000, v242
	v_lshlrev_b32_e32 v169, 16, v243
	v_and_b32_e32 v170, 0xffff0000, v243
	v_add_f32_e32 v110, v110, v167
	v_add_f32_e32 v111, v111, v168
	v_add_f32_e32 v112, v112, v169
	v_add_f32_e32 v113, v113, v170
	v_fma_f32 v171, v110, v110, v171
	v_fma_f32 v171, v111, v111, v171
	v_fma_f32 v171, v112, v112, v171
	v_fma_f32 v171, v113, v113, v171
	v_cvt_pk_bf16_f32 v110, v110, v111
	v_cvt_pk_bf16_f32 v111, v112, v113
	global_store_dwordx2 v164, v[110:111], s[50:51] offset:2080
	v_lshlrev_b32_e32 v167, 16, v244
	v_and_b32_e32 v168, 0xffff0000, v244
	v_lshlrev_b32_e32 v169, 16, v245
	v_and_b32_e32 v170, 0xffff0000, v245
	v_add_f32_e32 v114, v114, v167
	v_add_f32_e32 v115, v115, v168
	v_add_f32_e32 v116, v116, v169
	v_add_f32_e32 v117, v117, v170
	v_fma_f32 v171, v114, v114, v171
	v_fma_f32 v171, v115, v115, v171
	v_fma_f32 v171, v116, v116, v171
	v_fma_f32 v171, v117, v117, v171
	v_cvt_pk_bf16_f32 v114, v114, v115
	v_cvt_pk_bf16_f32 v115, v116, v117
	global_store_dwordx2 v122, v[114:115], s[50:51] offset:2048
	v_lshlrev_b32_e32 v167, 16, v246
	v_and_b32_e32 v168, 0xffff0000, v246
	v_lshlrev_b32_e32 v169, 16, v247
	v_and_b32_e32 v170, 0xffff0000, v247
	v_add_f32_e32 v118, v118, v167
	v_add_f32_e32 v119, v119, v168
	v_add_f32_e32 v120, v120, v169
	v_add_f32_e32 v121, v121, v170
	v_fma_f32 v171, v118, v118, v171
	v_fma_f32 v171, v119, v119, v171
	v_fma_f32 v171, v120, v120, v171
	v_fma_f32 v171, v121, v121, v171
	v_cvt_pk_bf16_f32 v118, v118, v119
	v_cvt_pk_bf16_f32 v119, v120, v121
	global_store_dwordx2 v122, v[118:119], s[50:51] offset:2080
	v_mov_b32_e32 v167, v171
	s_nop 1
	v_permlane32_swap_b32_e32 v171, v167
	v_add_f32_e32 v171, v171, v167
	ds_swizzle_b32 v167, v171 offset:0x401f
	s_waitcnt lgkmcnt(0)
	v_add_f32_e32 v171, v171, v167
	v_cmp_gt_u32_e32 vcc, 16, v160
	s_and_saveexec_b64 s[98:99], vcc
	global_store_dword v166, v171, s[14:15] offset:2056
	s_or_b64 exec, exec, s[98:99]
	v_mov_b32_e32 v171, 0
	v_lshlrev_b32_e32 v167, 16, v248
	v_and_b32_e32 v168, 0xffff0000, v248
	v_lshlrev_b32_e32 v169, 16, v249
	v_and_b32_e32 v170, 0xffff0000, v249
	v_add_f32_e32 v208, v208, v167
	v_add_f32_e32 v209, v209, v168
	v_add_f32_e32 v210, v210, v169
	v_add_f32_e32 v211, v211, v170
	v_fma_f32 v171, v208, v208, v171
	v_fma_f32 v171, v209, v209, v171
	v_fma_f32 v171, v210, v210, v171
	v_fma_f32 v171, v211, v211, v171
	v_cvt_pk_bf16_f32 v208, v208, v209
	v_cvt_pk_bf16_f32 v209, v210, v211
	global_store_dwordx2 v164, v[208:209], s[50:51] offset:3072
	v_lshlrev_b32_e32 v167, 16, v250
	v_and_b32_e32 v168, 0xffff0000, v250
	v_lshlrev_b32_e32 v169, 16, v251
	v_and_b32_e32 v170, 0xffff0000, v251
	v_add_f32_e32 v212, v212, v167
	v_add_f32_e32 v213, v213, v168
	v_add_f32_e32 v214, v214, v169
	v_add_f32_e32 v215, v215, v170
	v_fma_f32 v171, v212, v212, v171
	v_fma_f32 v171, v213, v213, v171
	v_fma_f32 v171, v214, v214, v171
	v_fma_f32 v171, v215, v215, v171
	v_cvt_pk_bf16_f32 v212, v212, v213
	v_cvt_pk_bf16_f32 v213, v214, v215
	global_store_dwordx2 v164, v[212:213], s[50:51] offset:3104
	v_lshlrev_b32_e32 v167, 16, v156
	v_and_b32_e32 v168, 0xffff0000, v156
	v_lshlrev_b32_e32 v169, 16, v157
	v_and_b32_e32 v170, 0xffff0000, v157
	v_add_f32_e32 v216, v216, v167
	v_add_f32_e32 v217, v217, v168
	v_add_f32_e32 v218, v218, v169
	v_add_f32_e32 v219, v219, v170
	v_fma_f32 v171, v216, v216, v171
	v_fma_f32 v171, v217, v217, v171
	v_fma_f32 v171, v218, v218, v171
	v_fma_f32 v171, v219, v219, v171
	v_cvt_pk_bf16_f32 v216, v216, v217
	v_cvt_pk_bf16_f32 v217, v218, v219
	global_store_dwordx2 v122, v[216:217], s[50:51] offset:3072
	v_lshlrev_b32_e32 v167, 16, v158
	v_and_b32_e32 v168, 0xffff0000, v158
	v_lshlrev_b32_e32 v169, 16, v159
	v_and_b32_e32 v170, 0xffff0000, v159
	v_add_f32_e32 v220, v220, v167
	v_add_f32_e32 v221, v221, v168
	v_add_f32_e32 v222, v222, v169
	v_add_f32_e32 v223, v223, v170
	v_fma_f32 v171, v220, v220, v171
	v_fma_f32 v171, v221, v221, v171
	v_fma_f32 v171, v222, v222, v171
	v_fma_f32 v171, v223, v223, v171
	v_cvt_pk_bf16_f32 v220, v220, v221
	v_cvt_pk_bf16_f32 v221, v222, v223
	global_store_dwordx2 v122, v[220:221], s[50:51] offset:3104
	v_mov_b32_e32 v167, v171
	s_nop 1
	v_permlane32_swap_b32_e32 v171, v167
	v_add_f32_e32 v171, v171, v167
	ds_swizzle_b32 v167, v171 offset:0x401f
	s_waitcnt lgkmcnt(0)
	v_add_f32_e32 v171, v171, v167
	v_cmp_gt_u32_e32 vcc, 16, v160
	s_and_saveexec_b64 s[98:99], vcc
	global_store_dword v166, v171, s[14:15] offset:3080
	s_or_b64 exec, exec, s[98:99]
	s_branch .Lffn2_edone
; DI u32x4 pack8(const float (&v)[8]) { u32x4 r = {pk2(v[0], v[1]), pk2(v[2], v[3]), pk2(v[4], v[5]), pk2(v[6], v[7])}; return r; }
; DI void tile_ffn2(const Params& p, int l, const Chunk& ck, int tile, int next, PF& pf, char* smem) {
;     ...
;   float* xd = p.out + (size_t)(ck.tok0 + m0 + row) * 1024 + n0 + half * 64;
;   u16* xb = (u16*)(p.ws + OFF_XB) + (size_t)(m0 + row) * 1024 + n0 + half * 64;
; #pragma unroll
;   for (int c8 = 0; c8 < 8; ++c8) {
;     float v[8], x[8]; cs_ld8(Cs, row, half * 64 + c8 * 8, v); unpack8(*(const u32x4*)(xb + c8 * 8), x);
; #pragma unroll
;     for (int j = 0; j < 8; ++j) { v[j] += x[j]; ssq += v[j] * v[j]; }
;     if (l == 0) *(u32x4*)(xb + c8 * 8) = pack8(v);
;     else { *(f32x4*)(xd + c8 * 8) = f32x4{v[0], v[1], v[2], v[3]}; *(f32x4*)(xd + c8 * 8 + 4) = f32x4{v[4], v[5], v[6], v[7]}; }
.Lffn2_l1:
	global_load_dwordx2 v[224:225], v164, s[50:51] offset:0
	global_load_dwordx2 v[226:227], v164, s[50:51] offset:32
	global_load_dwordx2 v[228:229], v122, s[50:51] offset:0
	global_load_dwordx2 v[230:231], v122, s[50:51] offset:32
	global_load_dwordx2 v[232:233], v164, s[50:51] offset:1024
	global_load_dwordx2 v[234:235], v164, s[50:51] offset:1056
	global_load_dwordx2 v[236:237], v122, s[50:51] offset:1024
	global_load_dwordx2 v[238:239], v122, s[50:51] offset:1056
	global_load_dwordx2 v[240:241], v164, s[50:51] offset:2048
	global_load_dwordx2 v[242:243], v164, s[50:51] offset:2080
	global_load_dwordx2 v[244:245], v122, s[50:51] offset:2048
	global_load_dwordx2 v[246:247], v122, s[50:51] offset:2080
	global_load_dwordx2 v[248:249], v164, s[50:51] offset:3072
	global_load_dwordx2 v[250:251], v164, s[50:51] offset:3104
	global_load_dwordx2 v[156:157], v122, s[50:51] offset:3072
	global_load_dwordx2 v[158:159], v122, s[50:51] offset:3104
	s_waitcnt vmcnt(0)
	v_lshlrev_b32_e32 v167, 16, v224
	v_and_b32_e32 v168, 0xffff0000, v224
	v_lshlrev_b32_e32 v169, 16, v225
	v_and_b32_e32 v170, 0xffff0000, v225
	v_add_f32_e32 v2, v2, v167
	v_add_f32_e32 v3, v3, v168
	v_add_f32_e32 v4, v4, v169
	v_add_f32_e32 v5, v5, v170
	global_store_dwordx4 v165, v[2:5], s[12:13]
	v_lshlrev_b32_e32 v167, 16, v226
	v_and_b32_e32 v168, 0xffff0000, v226
	v_lshlrev_b32_e32 v169, 16, v227
	v_and_b32_e32 v170, 0xffff0000, v227
	v_add_f32_e32 v6, v6, v167
	v_add_f32_e32 v7, v7, v168
	v_add_f32_e32 v8, v8, v169
	v_add_f32_e32 v9, v9, v170
	global_store_dwordx4 v165, v[6:9], s[12:13] offset:64
	v_lshlrev_b32_e32 v167, 16, v228
	v_and_b32_e32 v168, 0xffff0000, v228
	v_lshlrev_b32_e32 v169, 16, v229
	v_and_b32_e32 v170, 0xffff0000, v229
	v_add_f32_e32 v10, v10, v167
	v_add_f32_e32 v11, v11, v168
	v_add_f32_e32 v12, v12, v169
	v_add_f32_e32 v13, v13, v170
	global_store_dwordx4 v165, v[10:13], s[12:13] offset:128
	v_lshlrev_b32_e32 v167, 16, v230
	v_and_b32_e32 v168, 0xffff0000, v230
	v_lshlrev_b32_e32 v169, 16, v231
	v_and_b32_e32 v170, 0xffff0000, v231
	v_add_f32_e32 v14, v14, v167
	v_add_f32_e32 v15, v15, v168
	v_add_f32_e32 v16, v16, v169
	v_add_f32_e32 v17, v17, v170
	global_store_dwordx4 v165, v[14:17], s[12:13] offset:192
	v_add_u32_e32 v165, 0x10000, v165
	v_lshlrev_b32_e32 v167, 16, v232
	v_and_b32_e32 v168, 0xffff0000, v232
	v_lshlrev_b32_e32 v169, 16, v233
	v_and_b32_e32 v170, 0xffff0000, v233
	v_add_f32_e32 v18, v18, v167
	v_add_f32_e32 v19, v19, v168
	v_add_f32_e32 v20, v20, v169
	v_add_f32_e32 v21, v21, v170
	global_store_dwordx4 v165, v[18:21], s[12:13]
	v_lshlrev_b32_e32 v167, 16, v234
	v_and_b32_e32 v168, 0xffff0000, v234
	v_lshlrev_b32_e32 v169, 16, v235
	v_and_b32_e32 v170, 0xffff0000, v235
	v_add_f32_e32 v22, v22, v167
	v_add_f32_e32 v23, v23, v168
	v_add_f32_e32 v24, v24, v169
	v_add_f32_e32 v25, v25, v170
	global_store_dwordx4 v165, v[22:25], s[12:13] offset:64
	v_lshlrev_b32_e32 v167, 16, v236
	v_and_b32_e32 v168, 0xffff0000, v236
	v_lshlrev_b32_e32 v169, 16, v237
	v_and_b32_e32 v170, 0xffff0000, v237
	v_add_f32_e32 v26, v26, v167
	v_add_f32_e32 v27, v27, v168
	v_add_f32_e32 v28, v28, v169
	v_add_f32_e32 v29, v29, v170
	global_store_dwordx4 v165, v[26:29], s[12:13] offset:128
	v_lshlrev_b32_e32 v167, 16, v238
	v_and_b32_e32 v168, 0xffff0000, v238
	v_lshlrev_b32_e32 v169, 16, v239
	v_and_b32_e32 v170, 0xffff0000, v239
	v_add_f32_e32 v30, v30, v167
	v_add_f32_e32 v31, v31, v168
	v_add_f32_e32 v32, v32, v169
	v_add_f32_e32 v33, v33, v170
	global_store_dwordx4 v165, v[30:33], s[12:13] offset:192
	v_add_u32_e32 v165, 0x10000, v165
	v_lshlrev_b32_e32 v167, 16, v240
	v_and_b32_e32 v168, 0xffff0000, v240
	v_lshlrev_b32_e32 v169, 16, v241
	v_and_b32_e32 v170, 0xffff0000, v241
	v_add_f32_e32 v34, v34, v167
	v_add_f32_e32 v35, v35, v168
	v_add_f32_e32 v36, v36, v169
	v_add_f32_e32 v37, v37, v170
	global_store_dwordx4 v165, v[34:37], s[12:13]
	v_lshlrev_b32_e32 v167, 16, v242
	v_and_b32_e32 v168, 0xffff0000, v242
	v_lshlrev_b32_e32 v169, 16, v243
	v_and_b32_e32 v170, 0xffff0000, v243
	v_add_f32_e32 v38, v38, v167
	v_add_f32_e32 v39, v39, v168
	v_add_f32_e32 v40, v40, v169
	v_add_f32_e32 v41, v41, v170
	global_store_dwordx4 v165, v[38:41], s[12:13] offset:64
	v_lshlrev_b32_e32 v167, 16, v244
	v_and_b32_e32 v168, 0xffff0000, v244
	v_lshlrev_b32_e32 v169, 16, v245
	v_and_b32_e32 v170, 0xffff0000, v245
	v_add_f32_e32 v42, v42, v167
	v_add_f32_e32 v43, v43, v168
	v_add_f32_e32 v44, v44, v169
	v_add_f32_e32 v45, v45, v170
	global_store_dwordx4 v165, v[42:45], s[12:13] offset:128
	v_lshlrev_b32_e32 v167, 16, v246
	v_and_b32_e32 v168, 0xffff0000, v246
	v_lshlrev_b32_e32 v169, 16, v247
	v_and_b32_e32 v170, 0xffff0000, v247
	v_add_f32_e32 v46, v46, v167
	v_add_f32_e32 v47, v47, v168
	v_add_f32_e32 v48, v48, v169
	v_add_f32_e32 v49, v49, v170
	global_store_dwordx4 v165, v[46:49], s[12:13] offset:192
	v_add_u32_e32 v165, 0x10000, v165
	v_lshlrev_b32_e32 v167, 16, v248
	v_and_b32_e32 v168, 0xffff0000, v248
	v_lshlrev_b32_e32 v169, 16, v249
	v_and_b32_e32 v170, 0xffff0000, v249
	v_add_f32_e32 v50, v50, v167
	v_add_f32_e32 v51, v51, v168
	v_add_f32_e32 v52, v52, v169
	v_add_f32_e32 v53, v53, v170
	global_store_dwordx4 v165, v[50:53], s[12:13]
	v_lshlrev_b32_e32 v167, 16, v250
	v_and_b32_e32 v168, 0xffff0000, v250
	v_lshlrev_b32_e32 v169, 16, v251
	v_and_b32_e32 v170, 0xffff0000, v251
	v_add_f32_e32 v54, v54, v167
	v_add_f32_e32 v55, v55, v168
	v_add_f32_e32 v56, v56, v169
	v_add_f32_e32 v57, v57, v170
	global_store_dwordx4 v165, v[54:57], s[12:13] offset:64
	v_lshlrev_b32_e32 v167, 16, v156
	v_and_b32_e32 v168, 0xffff0000, v156
	v_lshlrev_b32_e32 v169, 16, v157
; DI u32x4 pack8(const float (&v)[8]) { u32x4 r = {pk2(v[0], v[1]), pk2(v[2], v[3]), pk2(v[4], v[5]), pk2(v[6], v[7])}; return r; }
; DI void tile_ffn2(const Params& p, int l, const Chunk& ck, int tile, int next, PF& pf, char* smem) {
;     ...
;   float* xd = p.out + (size_t)(ck.tok0 + m0 + row) * 1024 + n0 + half * 64;
;   u16* xb = (u16*)(p.ws + OFF_XB) + (size_t)(m0 + row) * 1024 + n0 + half * 64;
; #pragma unroll
;   for (int c8 = 0; c8 < 8; ++c8) {
;     float v[8], x[8]; cs_ld8(Cs, row, half * 64 + c8 * 8, v); unpack8(*(const u32x4*)(xb + c8 * 8), x);
; #pragma unroll
;     for (int j = 0; j < 8; ++j) { v[j] += x[j]; ssq += v[j] * v[j]; }
;     if (l == 0) *(u32x4*)(xb + c8 * 8) = pack8(v);
;     else { *(f32x4*)(xd + c8 * 8) = f32x4{v[0], v[1], v[2], v[3]}; *(f32x4*)(xd + c8 * 8 + 4) = f32x4{v[4], v[5], v[6], v[7]}; }
	v_and_b32_e32 v170, 0xffff0000, v157
	v_add_f32_e32 v58, v58, v167
	v_add_f32_e32 v59, v59, v168
	v_add_f32_e32 v60, v60, v169
	v_add_f32_e32 v61, v61, v170
	global_store_dwordx4 v165, v[58:61], s[12:13] offset:128
	v_lshlrev_b32_e32 v167, 16, v158
	v_and_b32_e32 v168, 0xffff0000, v158
	v_lshlrev_b32_e32 v169, 16, v159
	v_and_b32_e32 v170, 0xffff0000, v159
	v_add_f32_e32 v62, v62, v167
	v_add_f32_e32 v63, v63, v168
	v_add_f32_e32 v64, v64, v169
	v_add_f32_e32 v65, v65, v170
	global_store_dwordx4 v165, v[62:65], s[12:13] offset:192
	v_subrev_u32_e32 v165, 0x30000, v165
	v_add_u32_e32 v164, 0x400000, v164
	v_add_u32_e32 v122, 0x400000, v122
	global_load_dwordx2 v[224:225], v164, s[50:51] offset:0
	global_load_dwordx2 v[226:227], v164, s[50:51] offset:32
	global_load_dwordx2 v[228:229], v122, s[50:51] offset:0
	global_load_dwordx2 v[230:231], v122, s[50:51] offset:32
	global_load_dwordx2 v[232:233], v164, s[50:51] offset:1024
	global_load_dwordx2 v[234:235], v164, s[50:51] offset:1056
	global_load_dwordx2 v[236:237], v122, s[50:51] offset:1024
	global_load_dwordx2 v[238:239], v122, s[50:51] offset:1056
	global_load_dwordx2 v[240:241], v164, s[50:51] offset:2048
	global_load_dwordx2 v[242:243], v164, s[50:51] offset:2080
	global_load_dwordx2 v[244:245], v122, s[50:51] offset:2048
	global_load_dwordx2 v[246:247], v122, s[50:51] offset:2080
	global_load_dwordx2 v[248:249], v164, s[50:51] offset:3072
	global_load_dwordx2 v[250:251], v164, s[50:51] offset:3104
	global_load_dwordx2 v[156:157], v122, s[50:51] offset:3072
	global_load_dwordx2 v[158:159], v122, s[50:51] offset:3104
	s_waitcnt vmcnt(0)
	v_lshlrev_b32_e32 v167, 16, v224
	v_and_b32_e32 v168, 0xffff0000, v224
	v_lshlrev_b32_e32 v169, 16, v225
	v_and_b32_e32 v170, 0xffff0000, v225
	v_add_f32_e32 v74, v74, v167
	v_add_f32_e32 v75, v75, v168
	v_add_f32_e32 v76, v76, v169
	v_add_f32_e32 v77, v77, v170
	global_store_dwordx4 v165, v[74:77], s[12:13] offset:512
	v_lshlrev_b32_e32 v167, 16, v226
	v_and_b32_e32 v168, 0xffff0000, v226
	v_lshlrev_b32_e32 v169, 16, v227
	v_and_b32_e32 v170, 0xffff0000, v227
	v_add_f32_e32 v78, v78, v167
	v_add_f32_e32 v79, v79, v168
	v_add_f32_e32 v80, v80, v169
	v_add_f32_e32 v81, v81, v170
	global_store_dwordx4 v165, v[78:81], s[12:13] offset:576
	v_lshlrev_b32_e32 v167, 16, v228
	v_and_b32_e32 v168, 0xffff0000, v228
	v_lshlrev_b32_e32 v169, 16, v229
	v_and_b32_e32 v170, 0xffff0000, v229
	v_add_f32_e32 v82, v82, v167
	v_add_f32_e32 v83, v83, v168
	v_add_f32_e32 v84, v84, v169
	v_add_f32_e32 v85, v85, v170
	global_store_dwordx4 v165, v[82:85], s[12:13] offset:640
	v_lshlrev_b32_e32 v167, 16, v230
	v_and_b32_e32 v168, 0xffff0000, v230
	v_lshlrev_b32_e32 v169, 16, v231
	v_and_b32_e32 v170, 0xffff0000, v231
	v_add_f32_e32 v86, v86, v167
	v_add_f32_e32 v87, v87, v168
	v_add_f32_e32 v88, v88, v169
	v_add_f32_e32 v89, v89, v170
	global_store_dwordx4 v165, v[86:89], s[12:13] offset:704
	v_add_u32_e32 v165, 0x10000, v165
	v_lshlrev_b32_e32 v167, 16, v232
	v_and_b32_e32 v168, 0xffff0000, v232
	v_lshlrev_b32_e32 v169, 16, v233
	v_and_b32_e32 v170, 0xffff0000, v233
	v_add_f32_e32 v90, v90, v167
	v_add_f32_e32 v91, v91, v168
	v_add_f32_e32 v92, v92, v169
	v_add_f32_e32 v93, v93, v170
	global_store_dwordx4 v165, v[90:93], s[12:13] offset:512
	v_lshlrev_b32_e32 v167, 16, v234
	v_and_b32_e32 v168, 0xffff0000, v234
	v_lshlrev_b32_e32 v169, 16, v235
	v_and_b32_e32 v170, 0xffff0000, v235
	v_add_f32_e32 v94, v94, v167
	v_add_f32_e32 v95, v95, v168
	v_add_f32_e32 v96, v96, v169
	v_add_f32_e32 v97, v97, v170
	global_store_dwordx4 v165, v[94:97], s[12:13] offset:576
	v_lshlrev_b32_e32 v167, 16, v236
	v_and_b32_e32 v168, 0xffff0000, v236
	v_lshlrev_b32_e32 v169, 16, v237
	v_and_b32_e32 v170, 0xffff0000, v237
	v_add_f32_e32 v98, v98, v167
	v_add_f32_e32 v99, v99, v168
	v_add_f32_e32 v100, v100, v169
	v_add_f32_e32 v101, v101, v170
	global_store_dwordx4 v165, v[98:101], s[12:13] offset:640
	v_lshlrev_b32_e32 v167, 16, v238
	v_and_b32_e32 v168, 0xffff0000, v238
	v_lshlrev_b32_e32 v169, 16, v239
	v_and_b32_e32 v170, 0xffff0000, v239
	v_add_f32_e32 v102, v102, v167
	v_add_f32_e32 v103, v103, v168
	v_add_f32_e32 v104, v104, v169
	v_add_f32_e32 v105, v105, v170
	global_store_dwordx4 v165, v[102:105], s[12:13] offset:704
	v_add_u32_e32 v165, 0x10000, v165
	v_lshlrev_b32_e32 v167, 16, v240
	v_and_b32_e32 v168, 0xffff0000, v240
	v_lshlrev_b32_e32 v169, 16, v241
	v_and_b32_e32 v170, 0xffff0000, v241
	v_add_f32_e32 v106, v106, v167
	v_add_f32_e32 v107, v107, v168
	v_add_f32_e32 v108, v108, v169
	v_add_f32_e32 v109, v109, v170
	global_store_dwordx4 v165, v[106:109], s[12:13] offset:512
	v_lshlrev_b32_e32 v167, 16, v242
	v_and_b32_e32 v168, 0xffff0000, v242
	v_lshlrev_b32_e32 v169, 16, v243
	v_and_b32_e32 v170, 0xffff0000, v243
	v_add_f32_e32 v110, v110, v167
	v_add_f32_e32 v111, v111, v168
	v_add_f32_e32 v112, v112, v169
	v_add_f32_e32 v113, v113, v170
	global_store_dwordx4 v165, v[110:113], s[12:13] offset:576
	v_lshlrev_b32_e32 v167, 16, v244
	v_and_b32_e32 v168, 0xffff0000, v244
	v_lshlrev_b32_e32 v169, 16, v245
	v_and_b32_e32 v170, 0xffff0000, v245
	v_add_f32_e32 v114, v114, v167
	v_add_f32_e32 v115, v115, v168
	v_add_f32_e32 v116, v116, v169
	v_add_f32_e32 v117, v117, v170
	global_store_dwordx4 v165, v[114:117], s[12:13] offset:640
	v_lshlrev_b32_e32 v167, 16, v246
	v_and_b32_e32 v168, 0xffff0000, v246
	v_lshlrev_b32_e32 v169, 16, v247
	v_and_b32_e32 v170, 0xffff0000, v247
	v_add_f32_e32 v118, v118, v167
	v_add_f32_e32 v119, v119, v168
	v_add_f32_e32 v120, v120, v169
	v_add_f32_e32 v121, v121, v170
	global_store_dwordx4 v165, v[118:121], s[12:13] offset:704
	v_add_u32_e32 v165, 0x10000, v165
	v_lshlrev_b32_e32 v167, 16, v248
	v_and_b32_e32 v168, 0xffff0000, v248
	v_lshlrev_b32_e32 v169, 16, v249
	v_and_b32_e32 v170, 0xffff0000, v249
	v_add_f32_e32 v208, v208, v167
	v_add_f32_e32 v209, v209, v168
	v_add_f32_e32 v210, v210, v169
	v_add_f32_e32 v211, v211, v170
	global_store_dwordx4 v165, v[208:211], s[12:13] offset:512
	v_lshlrev_b32_e32 v167, 16, v250
	v_and_b32_e32 v168, 0xffff0000, v250
	v_lshlrev_b32_e32 v169, 16, v251
	v_and_b32_e32 v170, 0xffff0000, v251
	v_add_f32_e32 v212, v212, v167
	v_add_f32_e32 v213, v213, v168
	v_add_f32_e32 v214, v214, v169
	v_add_f32_e32 v215, v215, v170
	global_store_dwordx4 v165, v[212:215], s[12:13] offset:576
	v_lshlrev_b32_e32 v167, 16, v156
	v_and_b32_e32 v168, 0xffff0000, v156
	v_lshlrev_b32_e32 v169, 16, v157
	v_and_b32_e32 v170, 0xffff0000, v157
	v_add_f32_e32 v216, v216, v167
	v_add_f32_e32 v217, v217, v168
	v_add_f32_e32 v218, v218, v169
	v_add_f32_e32 v219, v219, v170
	global_store_dwordx4 v165, v[216:219], s[12:13] offset:640
	v_lshlrev_b32_e32 v167, 16, v158
	v_and_b32_e32 v168, 0xffff0000, v158
	v_lshlrev_b32_e32 v169, 16, v159
	v_and_b32_e32 v170, 0xffff0000, v159
	v_add_f32_e32 v220, v220, v167
	v_add_f32_e32 v221, v221, v168
	v_add_f32_e32 v222, v222, v169
	v_add_f32_e32 v223, v223, v170
	global_store_dwordx4 v165, v[220:223], s[12:13] offset:704
	v_subrev_u32_e32 v165, 0x30000, v165

; DI int TID() { int t = (int)__builtin_amdgcn_workitem_id_x(); asm volatile("" : "+v"(t)); return t; }
; #define BLOAD(A_, B_, kt) do { _Pragma("unroll") for (int i = 0; i < 4; ++i) { \
;     A_[i] = *(const u32x4*)((const char*)Ap + (aoff + (unsigned)(32 * i * lda + (kt) * 64) * 2u)); B_[i] = *(const u32x4*)((const char*)Wt + (woff + (unsigned)(32 * i * K + (kt) * 64) * 2u)); } } while (0)
; DI RowSS rowss_load(const float* ps, int m0) { const int tid = TID(); const float* q = ps + (size_t)(m0 + (tid >> 1)) * 16 + (tid & 1) * 8; RowSS r; r.a = *(const f32x4*)q; r.b = *(const f32x4*)(q + 4); return r; }
; #define BLOAD(A_, B_, kt) do { _Pragma("unroll") for (int i = 0; i < 4; ++i) { \
;     A_[i] = *(const u32x4*)((const char*)Ap + (aoff + (unsigned)(32 * i * lda + (kt) * 64) * 2u)); B_[i] = *(const u32x4*)((const char*)Wt + (woff + (unsigned)(32 * i * K + (kt) * 64) * 2u)); } } while (0)
; template <int NK>
; DI void gemm_run(PF& pf, const u16* __restrict__ Ap, int lda, const u16* __restrict__ Wt, f32x16 (&acc)[2][2], char* smem) {
;   constexpr int K = NK * 64;
;   const int tid = TID(), lane = tid & 63, w = tid >> 6, wm = w >> 1, wn = w & 1, r32 = lane & 31, hi = lane >> 5;
;   u16* As = (u16*)smem; u16* Bs = As + 128 * LDT;
;   const int srow = tid >> 3, sc8 = (tid & 7) * 8;
;   constexpr int nk = NK;
;   const unsigned aoff = (unsigned)(srow * lda + sc8) * 2u, woff = (unsigned)(srow * K + sc8) * 2u;
;     ...
;   __builtin_amdgcn_s_setprio(0);
;   __syncthreads();
;   BSTORE(pf.a0, pf.b0, 0);
;   BLOAD(pf.a0, pf.b0, 2);
;   __syncthreads();
; DI void tile_ffn1(const Params& p, int l, const Chunk& ck, int tile, int next, PF& pf, char* smem) {
;   float* Cs = (float*)smem; float* rinv_s = (float*)(smem + SMEM_CS);
;   const int tid = TID(); const int mi = tile & (MTN - 1), ni = tile >> MTS; const int m0 = mi * 128, n0 = ni * 128;
;   f32x16 acc[2][2]; zero_acc(acc);
;   const RowSS rss = rowss_load((const float*)(p.ws + OFF_PSMID), m0);
;   { const u16* Ap; const u16* Wt; ffn1_ptrs(p, l, tile, Ap, Wt); gemm_run<16>(pf, Ap, 1024, Wt, acc, smem); }
;   if (next >= 0) { const u16* An; const u16* Wn; ffn1_ptrs(p, l, next, An, Wn); gemm_issue(pf, An, 1024, Wn, 1024); }
;   rowss_finish(rss, rinv_s);
;   acc_to_cs(acc, Cs);
.LBB1_246:
	s_mov_b32 s26, s16
	s_add_i32 s16, s16, s78
	s_cmpk_gt_i32 s16, 0x7ff
	s_cselect_b64 s[24:25], -1, 0
	s_cmpk_lt_i32 s16, 0x800
	v_mov_b32_e32 v148, v172
	v_mov_b32_e32 v0, v172
	s_cselect_b32 s0, s16, -1
	s_and_b32 s41, s40, 0x3f80
	s_and_b32 s27, s35, 0xfe0000
	v_ashrrev_i32_e32 v2, 1, v0
	v_add_u32_e32 v2, s41, v2
	v_ashrrev_i32_e32 v3, 31, v2
	v_lshlrev_b64 v[2:3], 6, v[2:3]
	v_lshlrev_b32_e32 v0, 5, v0
	v_lshl_add_u64 v[2:3], s[20:21], 0, v[2:3]
	v_and_b32_e32 v0, 32, v0
	v_lshl_add_u64 v[2:3], v[2:3], 0, v[0:1]
	global_load_dwordx4 v[66:69], v[2:3], off offset:16
	global_load_dwordx4 v[70:73], v[2:3], off
	s_and_b32 s26, s26, 0xffffff80
	s_lshl_b32 s26, s26, 1
	s_lshr_b32 s27, s27, 4
	s_add_u32 s28, s17, s27
	s_addc_u32 s29, s34, 0
	s_ashr_i32 s27, s26, 31
	s_lshl_b64 s[30:31], s[26:27], 6
	s_add_u32 s30, s36, s30
	s_addc_u32 s31, s37, s31
	s_setprio 0
	s_waitcnt lgkmcnt(0)
	s_mov_b32 s0, 0
	v_and_b32_e32 v149, 63, v172
	v_lshrrev_b32_e32 v151, 6, v172
	v_bfe_u32 v152, v149, 4, 2
	v_lshrrev_b32_e32 v153, 1, v152
	v_xor_b32_e32 v152, v152, v153
	v_and_b32_e32 v152, 1, v152
	v_lshl_or_b32 v152, v152, 1, v153
	v_xor_b32_e32 v152, v152, v149
	v_and_b32_e32 v152, 3, v152
	v_lshlrev_b32_e32 v152, 4, v152
	v_lshrrev_b32_e32 v153, 2, v149
	v_lshl_add_u32 v142, v151, 5, v153
	v_lshl_add_u32 v142, v142, 6, v152
	v_mov_b32_e32 v143, v142
	v_lshl_add_u32 v144, v151, 6, v153
	v_lshl_add_u32 v144, v144, 6, v152
	v_mov_b32_e32 v145, v144
	v_mov_b32_e32 v146, v144
	v_mov_b32_e32 v147, v144
	v_readfirstlane_b32 s42, v151
	s_lshl_b32 s43, s42, 12
	s_lshl_b32 s42, s42, 11
	s_add_u32 s43, s43, 0x2000
	v_bfe_u32 v152, v149, 2, 2
	v_lshrrev_b32_e32 v153, 1, v152
	v_xor_b32_e32 v152, v152, v153
	v_and_b32_e32 v152, 1, v152
	v_lshl_or_b32 v152, v152, 1, v153
	v_lshrrev_b32_e32 v153, 4, v149
	v_xor_b32_e32 v152, v152, v153
	v_lshlrev_b32_e32 v152, 4, v152
	v_and_b32_e32 v149, 15, v149
	v_lshl_add_u32 v149, v149, 6, v152
	v_lshrrev_b32_e32 v152, 1, v151
	v_and_b32_e32 v153, 1, v151
	v_lshl_add_u32 v138, v152, 12, v149
	v_lshl_add_u32 v140, v153, 12, v149
	v_add_u32_e32 v140, 0x2000, v140
	s_barrier
	v_mov_b32_e32 v2, 0
	v_mov_b32_e32 v3, 0
	v_mov_b32_e32 v4, 0
	v_mov_b32_e32 v5, 0
	v_mov_b32_e32 v6, 0
	v_mov_b32_e32 v7, 0
	v_mov_b32_e32 v8, 0
	v_mov_b32_e32 v9, 0
	v_mov_b32_e32 v10, 0
	v_mov_b32_e32 v11, 0
	v_mov_b32_e32 v12, 0
	v_mov_b32_e32 v13, 0
	v_mov_b32_e32 v14, 0
	v_mov_b32_e32 v15, 0
	v_mov_b32_e32 v16, 0
	v_mov_b32_e32 v17, 0
	v_mov_b32_e32 v18, 0
	v_mov_b32_e32 v19, 0
	v_mov_b32_e32 v20, 0
	v_mov_b32_e32 v21, 0
	v_mov_b32_e32 v22, 0
	v_mov_b32_e32 v23, 0
	v_mov_b32_e32 v24, 0
	v_mov_b32_e32 v25, 0
	v_mov_b32_e32 v26, 0
	v_mov_b32_e32 v27, 0
	v_mov_b32_e32 v28, 0
	v_mov_b32_e32 v29, 0
	v_mov_b32_e32 v30, 0
	v_mov_b32_e32 v31, 0
	v_mov_b32_e32 v32, 0
	v_mov_b32_e32 v33, 0
	v_mov_b32_e32 v34, 0
	v_mov_b32_e32 v35, 0
	v_mov_b32_e32 v36, 0
	v_mov_b32_e32 v37, 0
	v_mov_b32_e32 v38, 0
	v_mov_b32_e32 v39, 0
	v_mov_b32_e32 v40, 0
	v_mov_b32_e32 v41, 0
	v_mov_b32_e32 v42, 0
	v_mov_b32_e32 v43, 0
	v_mov_b32_e32 v44, 0
	v_mov_b32_e32 v45, 0
	v_mov_b32_e32 v46, 0
	v_mov_b32_e32 v47, 0
	v_mov_b32_e32 v48, 0
	v_mov_b32_e32 v49, 0
	v_mov_b32_e32 v50, 0
	v_mov_b32_e32 v51, 0
	v_mov_b32_e32 v52, 0
	v_mov_b32_e32 v53, 0
	v_mov_b32_e32 v54, 0
	v_mov_b32_e32 v55, 0
	v_mov_b32_e32 v56, 0
	v_mov_b32_e32 v57, 0
	v_mov_b32_e32 v58, 0
	v_mov_b32_e32 v59, 0
	v_mov_b32_e32 v60, 0
	v_mov_b32_e32 v61, 0
	v_mov_b32_e32 v62, 0
	v_mov_b32_e32 v63, 0
	v_mov_b32_e32 v64, 0
	v_mov_b32_e32 v65, 0
	v_mov_b32_e32 v74, 0
	v_mov_b32_e32 v75, 0
	v_mov_b32_e32 v76, 0
	v_mov_b32_e32 v77, 0
	v_mov_b32_e32 v78, 0
	v_mov_b32_e32 v79, 0
	v_mov_b32_e32 v80, 0
	v_mov_b32_e32 v81, 0
	v_mov_b32_e32 v82, 0
	v_mov_b32_e32 v83, 0
	v_mov_b32_e32 v84, 0
	v_mov_b32_e32 v85, 0
	v_mov_b32_e32 v86, 0
	v_mov_b32_e32 v87, 0
	v_mov_b32_e32 v88, 0
	v_mov_b32_e32 v89, 0
	v_mov_b32_e32 v90, 0
	v_mov_b32_e32 v91, 0
	v_mov_b32_e32 v92, 0
	v_mov_b32_e32 v93, 0
	v_mov_b32_e32 v94, 0
	v_mov_b32_e32 v95, 0
	v_mov_b32_e32 v96, 0
	v_mov_b32_e32 v97, 0
	v_mov_b32_e32 v98, 0
	v_mov_b32_e32 v99, 0
	v_mov_b32_e32 v100, 0
	v_mov_b32_e32 v101, 0
	v_mov_b32_e32 v102, 0
	v_mov_b32_e32 v103, 0
	v_mov_b32_e32 v104, 0
	v_mov_b32_e32 v105, 0
	v_mov_b32_e32 v106, 0
	v_mov_b32_e32 v107, 0
	v_mov_b32_e32 v108, 0
	v_mov_b32_e32 v109, 0
	v_mov_b32_e32 v110, 0
	v_mov_b32_e32 v111, 0
	v_mov_b32_e32 v112, 0
	v_mov_b32_e32 v113, 0
	v_mov_b32_e32 v114, 0
	v_mov_b32_e32 v115, 0
	v_mov_b32_e32 v116, 0
	v_mov_b32_e32 v117, 0
	v_mov_b32_e32 v118, 0
	v_mov_b32_e32 v119, 0
	v_mov_b32_e32 v120, 0
	v_mov_b32_e32 v121, 0
	v_mov_b32_e32 v122, 0
	v_mov_b32_e32 v123, 0
	v_mov_b32_e32 v124, 0
	v_mov_b32_e32 v125, 0
	v_mov_b32_e32 v126, 0
	v_mov_b32_e32 v127, 0
	v_mov_b32_e32 v128, 0
	v_mov_b32_e32 v129, 0
	v_mov_b32_e32 v130, 0
	v_mov_b32_e32 v131, 0
	v_mov_b32_e32 v132, 0
	v_mov_b32_e32 v133, 0
	v_mov_b32_e32 v134, 0
	v_mov_b32_e32 v135, 0
	v_mov_b32_e32 v136, 0
	v_mov_b32_e32 v137, 0
	s_add_u32 m0, s42, 0x0
	s_nop 0
	global_load_lds_dwordx4 v142, s[28:29]
	global_load_lds_dwordx4 v143, s[28:29] offset:1024
	s_add_u32 m0, s43, 0x0
	s_nop 0
	global_load_lds_dwordx4 v144, s[30:31]
	global_load_lds_dwordx4 v145, s[30:31] offset:1024
	global_load_lds_dwordx4 v146, s[30:31] offset:2048
	global_load_lds_dwordx4 v147, s[30:31] offset:3072
	s_add_u32 m0, s42, 0x6000
	s_add_u32 s28, s28, 0x100000
	s_addc_u32 s29, s29, 0
	global_load_lds_dwordx4 v142, s[28:29]
	global_load_lds_dwordx4 v143, s[28:29] offset:1024
	s_add_u32 m0, s43, 0x6000
	s_add_u32 s30, s30, 0x40000
	s_addc_u32 s31, s31, 0
	global_load_lds_dwordx4 v144, s[30:31]
	global_load_lds_dwordx4 v145, s[30:31] offset:1024
	global_load_lds_dwordx4 v146, s[30:31] offset:2048
	global_load_lds_dwordx4 v147, s[30:31] offset:3072
	s_mov_b32 s46, 10
; #define BLOAD(A_, B_, kt) do { _Pragma("unroll") for (int i = 0; i < 4; ++i) { \
;     A_[i] = *(const u32x4*)((const char*)Ap + (aoff + (unsigned)(32 * i * lda + (kt) * 64) * 2u)); B_[i] = *(const u32x4*)((const char*)Wt + (woff + (unsigned)(32 * i * K + (kt) * 64) * 2u)); } } while (0)
; #define BLOAD(A_, B_, kt) do { _Pragma("unroll") for (int i = 0; i < 4; ++i) { \
;     A_[i] = *(const u32x4*)((const char*)Ap + (aoff + (unsigned)(32 * i * lda + (kt) * 64) * 2u)); B_[i] = *(const u32x4*)((const char*)Wt + (woff + (unsigned)(32 * i * K + (kt) * 64) * 2u)); } } while (0)
; #define BSTORE(A_, B_, buf) do { _Pragma("unroll") for (int i = 0; i < 4; ++i) { \
;     *(u32x4*)&As[(buf) * GBUF + (srow + 32 * i) * LDT + sc8] = A_[i]; \
;     *(u32x4*)&Bs[(buf) * GBUF + (srow + 32 * i) * LDT + sc8] = B_[i]; } } while (0)
; template <int NK>
; DI void gemm_run(PF& pf, const u16* __restrict__ Ap, int lda, const u16* __restrict__ Wt, f32x16 (&acc)[2][2], char* smem) {
;     ...
; #pragma unroll
;   for (int kt = 0; kt < nk; kt += 2) {
;     BCOMP(0);
;     BSTORE(pf.a1, pf.b1, 1);
;     if (kt + 3 < nk) BLOAD(pf.a1, pf.b1, kt + 3);
;     __syncthreads();
;     BCOMP(1);
;     if (kt + 2 < nk) { BSTORE(pf.a0, pf.b0, 0); if (kt + 4 < nk) BLOAD(pf.a0, pf.b0, kt + 4); }
;     __syncthreads();
;   }
.Lffn1_kloop:
	s_waitcnt vmcnt(6)
	s_barrier
	ds_read_b128 v[208:211], v138 offset:0
	ds_read_b128 v[224:227], v140 offset:0
	ds_read_b128 v[228:231], v140 offset:1024
	ds_read_b128 v[232:235], v140 offset:2048
	ds_read_b128 v[236:239], v140 offset:3072
	s_add_u32 m0, s42, 0xc000
	s_add_u32 s28, s28, 0x100000
	s_addc_u32 s29, s29, 0
	global_load_lds_dwordx4 v142, s[28:29]
	global_load_lds_dwordx4 v143, s[28:29] offset:1024
	s_add_u32 m0, s43, 0xc000
	s_add_u32 s30, s30, 0x40000
	s_addc_u32 s31, s31, 0
	global_load_lds_dwordx4 v144, s[30:31]
	global_load_lds_dwordx4 v145, s[30:31] offset:1024
	global_load_lds_dwordx4 v146, s[30:31] offset:2048
	global_load_lds_dwordx4 v147, s[30:31] offset:3072
	ds_read_b128 v[212:215], v138 offset:1024
	ds_read_b128 v[216:219], v138 offset:2048
	ds_read_b128 v[220:223], v138 offset:3072
	ds_read_b128 v[240:243], v140 offset:8192
	ds_read_b128 v[244:247], v140 offset:9216
	ds_read_b128 v[248:251], v140 offset:10240
	ds_read_b128 v[156:159], v140 offset:11264
	s_waitcnt lgkmcnt(10)
	v_mfma_f32_16x16x32_bf16 v[2:5], v[224:227], v[208:211], v[2:5]
	s_waitcnt lgkmcnt(9)
	v_mfma_f32_16x16x32_bf16 v[6:9], v[228:231], v[208:211], v[6:9]
	s_waitcnt lgkmcnt(8)
	v_mfma_f32_16x16x32_bf16 v[10:13], v[232:235], v[208:211], v[10:13]
	s_waitcnt lgkmcnt(7)
	v_mfma_f32_16x16x32_bf16 v[14:17], v[236:239], v[208:211], v[14:17]
	s_waitcnt lgkmcnt(6)
	v_mfma_f32_16x16x32_bf16 v[18:21], v[224:227], v[212:215], v[18:21]
	v_mfma_f32_16x16x32_bf16 v[22:25], v[228:231], v[212:215], v[22:25]
	v_mfma_f32_16x16x32_bf16 v[26:29], v[232:235], v[212:215], v[26:29]
	v_mfma_f32_16x16x32_bf16 v[30:33], v[236:239], v[212:215], v[30:33]
	s_waitcnt lgkmcnt(5)
	v_mfma_f32_16x16x32_bf16 v[34:37], v[224:227], v[216:219], v[34:37]
	v_mfma_f32_16x16x32_bf16 v[38:41], v[228:231], v[216:219], v[38:41]
	v_mfma_f32_16x16x32_bf16 v[42:45], v[232:235], v[216:219], v[42:45]
	v_mfma_f32_16x16x32_bf16 v[46:49], v[236:239], v[216:219], v[46:49]
	s_waitcnt lgkmcnt(4)
	v_mfma_f32_16x16x32_bf16 v[50:53], v[224:227], v[220:223], v[50:53]
	v_mfma_f32_16x16x32_bf16 v[54:57], v[228:231], v[220:223], v[54:57]
	v_mfma_f32_16x16x32_bf16 v[58:61], v[232:235], v[220:223], v[58:61]
	v_mfma_f32_16x16x32_bf16 v[62:65], v[236:239], v[220:223], v[62:65]
	s_waitcnt lgkmcnt(3)
	v_mfma_f32_16x16x32_bf16 v[74:77], v[240:243], v[208:211], v[74:77]
	s_waitcnt lgkmcnt(2)
	v_mfma_f32_16x16x32_bf16 v[78:81], v[244:247], v[208:211], v[78:81]
	s_waitcnt lgkmcnt(1)
	v_mfma_f32_16x16x32_bf16 v[82:85], v[248:251], v[208:211], v[82:85]
	s_waitcnt lgkmcnt(0)
	v_mfma_f32_16x16x32_bf16 v[86:89], v[156:159], v[208:211], v[86:89]
	v_mfma_f32_16x16x32_bf16 v[90:93], v[240:243], v[212:215], v[90:93]
	v_mfma_f32_16x16x32_bf16 v[94:97], v[244:247], v[212:215], v[94:97]
	v_mfma_f32_16x16x32_bf16 v[98:101], v[248:251], v[212:215], v[98:101]
	v_mfma_f32_16x16x32_bf16 v[102:105], v[156:159], v[212:215], v[102:105]
	v_mfma_f32_16x16x32_bf16 v[106:109], v[240:243], v[216:219], v[106:109]
	v_mfma_f32_16x16x32_bf16 v[110:113], v[244:247], v[216:219], v[110:113]
	v_mfma_f32_16x16x32_bf16 v[114:117], v[248:251], v[216:219], v[114:117]
	v_mfma_f32_16x16x32_bf16 v[118:121], v[156:159], v[216:219], v[118:121]
	v_mfma_f32_16x16x32_bf16 v[122:125], v[240:243], v[220:223], v[122:125]
	v_mfma_f32_16x16x32_bf16 v[126:129], v[244:247], v[220:223], v[126:129]
	v_mfma_f32_16x16x32_bf16 v[130:133], v[248:251], v[220:223], v[130:133]
	v_mfma_f32_16x16x32_bf16 v[134:137], v[156:159], v[220:223], v[134:137]
	s_waitcnt vmcnt(6)
	s_barrier
	ds_read_b128 v[208:211], v138 offset:24576
	ds_read_b128 v[224:227], v140 offset:24576
	ds_read_b128 v[228:231], v140 offset:25600
	ds_read_b128 v[232:235], v140 offset:26624
	ds_read_b128 v[236:239], v140 offset:27648
	s_add_u32 m0, s42, 0x0
	s_add_u32 s28, s28, 0x100000
	s_addc_u32 s29, s29, 0
	global_load_lds_dwordx4 v142, s[28:29]
	global_load_lds_dwordx4 v143, s[28:29] offset:1024
	s_add_u32 m0, s43, 0x0
	s_add_u32 s30, s30, 0x40000
	s_addc_u32 s31, s31, 0
	global_load_lds_dwordx4 v144, s[30:31]
	global_load_lds_dwordx4 v145, s[30:31] offset:1024
	global_load_lds_dwordx4 v146, s[30:31] offset:2048
	global_load_lds_dwordx4 v147, s[30:31] offset:3072
	ds_read_b128 v[212:215], v138 offset:25600
	ds_read_b128 v[216:219], v138 offset:26624
	ds_read_b128 v[220:223], v138 offset:27648
	ds_read_b128 v[240:243], v140 offset:32768
	ds_read_b128 v[244:247], v140 offset:33792
	ds_read_b128 v[248:251], v140 offset:34816
	ds_read_b128 v[156:159], v140 offset:35840
	s_waitcnt lgkmcnt(10)
	v_mfma_f32_16x16x32_bf16 v[2:5], v[224:227], v[208:211], v[2:5]
	s_waitcnt lgkmcnt(9)
	v_mfma_f32_16x16x32_bf16 v[6:9], v[228:231], v[208:211], v[6:9]
	s_waitcnt lgkmcnt(8)
	v_mfma_f32_16x16x32_bf16 v[10:13], v[232:235], v[208:211], v[10:13]
	s_waitcnt lgkmcnt(7)
	v_mfma_f32_16x16x32_bf16 v[14:17], v[236:239], v[208:211], v[14:17]
	s_waitcnt lgkmcnt(6)
	v_mfma_f32_16x16x32_bf16 v[18:21], v[224:227], v[212:215], v[18:21]
	v_mfma_f32_16x16x32_bf16 v[22:25], v[228:231], v[212:215], v[22:25]
	v_mfma_f32_16x16x32_bf16 v[26:29], v[232:235], v[212:215], v[26:29]
	v_mfma_f32_16x16x32_bf16 v[30:33], v[236:239], v[212:215], v[30:33]
	s_waitcnt lgkmcnt(5)
	v_mfma_f32_16x16x32_bf16 v[34:37], v[224:227], v[216:219], v[34:37]
	v_mfma_f32_16x16x32_bf16 v[38:41], v[228:231], v[216:219], v[38:41]
	v_mfma_f32_16x16x32_bf16 v[42:45], v[232:235], v[216:219], v[42:45]
	v_mfma_f32_16x16x32_bf16 v[46:49], v[236:239], v[216:219], v[46:49]
	s_waitcnt lgkmcnt(4)
	v_mfma_f32_16x16x32_bf16 v[50:53], v[224:227], v[220:223], v[50:53]
	v_mfma_f32_16x16x32_bf16 v[54:57], v[228:231], v[220:223], v[54:57]
	v_mfma_f32_16x16x32_bf16 v[58:61], v[232:235], v[220:223], v[58:61]
	v_mfma_f32_16x16x32_bf16 v[62:65], v[236:239], v[220:223], v[62:65]
	s_waitcnt lgkmcnt(3)
	v_mfma_f32_16x16x32_bf16 v[74:77], v[240:243], v[208:211], v[74:77]
	s_waitcnt lgkmcnt(2)
	v_mfma_f32_16x16x32_bf16 v[78:81], v[244:247], v[208:211], v[78:81]
	s_waitcnt lgkmcnt(1)
	v_mfma_f32_16x16x32_bf16 v[82:85], v[248:251], v[208:211], v[82:85]
	s_waitcnt lgkmcnt(0)
	v_mfma_f32_16x16x32_bf16 v[86:89], v[156:159], v[208:211], v[86:89]
	v_mfma_f32_16x16x32_bf16 v[90:93], v[240:243], v[212:215], v[90:93]
	v_mfma_f32_16x16x32_bf16 v[94:97], v[244:247], v[212:215], v[94:97]
	v_mfma_f32_16x16x32_bf16 v[98:101], v[248:251], v[212:215], v[98:101]
	v_mfma_f32_16x16x32_bf16 v[102:105], v[156:159], v[212:215], v[102:105]
	v_mfma_f32_16x16x32_bf16 v[106:109], v[240:243], v[216:219], v[106:109]
	v_mfma_f32_16x16x32_bf16 v[110:113], v[244:247], v[216:219], v[110:113]
	v_mfma_f32_16x16x32_bf16 v[114:117], v[248:251], v[216:219], v[114:117]
	v_mfma_f32_16x16x32_bf16 v[118:121], v[156:159], v[216:219], v[118:121]
	v_mfma_f32_16x16x32_bf16 v[122:125], v[240:243], v[220:223], v[122:125]
	v_mfma_f32_16x16x32_bf16 v[126:129], v[244:247], v[220:223], v[126:129]
	v_mfma_f32_16x16x32_bf16 v[130:133], v[248:251], v[220:223], v[130:133]
	v_mfma_f32_16x16x32_bf16 v[134:137], v[156:159], v[220:223], v[134:137]
	s_waitcnt vmcnt(6)
	s_barrier
; #define BLOAD(A_, B_, kt) do { _Pragma("unroll") for (int i = 0; i < 4; ++i) { \
;     A_[i] = *(const u32x4*)((const char*)Ap + (aoff + (unsigned)(32 * i * lda + (kt) * 64) * 2u)); B_[i] = *(const u32x4*)((const char*)Wt + (woff + (unsigned)(32 * i * K + (kt) * 64) * 2u)); } } while (0)
; #define BLOAD(A_, B_, kt) do { _Pragma("unroll") for (int i = 0; i < 4; ++i) { \
;     A_[i] = *(const u32x4*)((const char*)Ap + (aoff + (unsigned)(32 * i * lda + (kt) * 64) * 2u)); B_[i] = *(const u32x4*)((const char*)Wt + (woff + (unsigned)(32 * i * K + (kt) * 64) * 2u)); } } while (0)
; #define BSTORE(A_, B_, buf) do { _Pragma("unroll") for (int i = 0; i < 4; ++i) { \
;     *(u32x4*)&As[(buf) * GBUF + (srow + 32 * i) * LDT + sc8] = A_[i]; \
;     *(u32x4*)&Bs[(buf) * GBUF + (srow + 32 * i) * LDT + sc8] = B_[i]; } } while (0)
; template <int NK>
; DI void gemm_run(PF& pf, const u16* __restrict__ Ap, int lda, const u16* __restrict__ Wt, f32x16 (&acc)[2][2], char* smem) {
;     ...
; #pragma unroll
;   for (int kt = 0; kt < nk; kt += 2) {
;     BCOMP(0);
;     BSTORE(pf.a1, pf.b1, 1);
;     if (kt + 3 < nk) BLOAD(pf.a1, pf.b1, kt + 3);
;     __syncthreads();
;     BCOMP(1);
;     if (kt + 2 < nk) { BSTORE(pf.a0, pf.b0, 0); if (kt + 4 < nk) BLOAD(pf.a0, pf.b0, kt + 4); }
;     __syncthreads();
;   }
	ds_read_b128 v[208:211], v138 offset:49152
	ds_read_b128 v[224:227], v140 offset:49152
	ds_read_b128 v[228:231], v140 offset:50176
	ds_read_b128 v[232:235], v140 offset:51200
	ds_read_b128 v[236:239], v140 offset:52224
	s_add_u32 m0, s42, 0x6000
	s_add_u32 s28, s28, 0x100000
	s_addc_u32 s29, s29, 0
	global_load_lds_dwordx4 v142, s[28:29]
	global_load_lds_dwordx4 v143, s[28:29] offset:1024
	s_add_u32 m0, s43, 0x6000
	s_add_u32 s30, s30, 0x40000
	s_addc_u32 s31, s31, 0
	global_load_lds_dwordx4 v144, s[30:31]
	global_load_lds_dwordx4 v145, s[30:31] offset:1024
	global_load_lds_dwordx4 v146, s[30:31] offset:2048
	global_load_lds_dwordx4 v147, s[30:31] offset:3072
	ds_read_b128 v[212:215], v138 offset:50176
	ds_read_b128 v[216:219], v138 offset:51200
	ds_read_b128 v[220:223], v138 offset:52224
	ds_read_b128 v[240:243], v140 offset:57344
	ds_read_b128 v[244:247], v140 offset:58368
	ds_read_b128 v[248:251], v140 offset:59392
	ds_read_b128 v[156:159], v140 offset:60416
	s_waitcnt lgkmcnt(10)
	v_mfma_f32_16x16x32_bf16 v[2:5], v[224:227], v[208:211], v[2:5]
	s_waitcnt lgkmcnt(9)
	v_mfma_f32_16x16x32_bf16 v[6:9], v[228:231], v[208:211], v[6:9]
	s_waitcnt lgkmcnt(8)
	v_mfma_f32_16x16x32_bf16 v[10:13], v[232:235], v[208:211], v[10:13]
	s_waitcnt lgkmcnt(7)
	v_mfma_f32_16x16x32_bf16 v[14:17], v[236:239], v[208:211], v[14:17]
	s_waitcnt lgkmcnt(6)
	v_mfma_f32_16x16x32_bf16 v[18:21], v[224:227], v[212:215], v[18:21]
	v_mfma_f32_16x16x32_bf16 v[22:25], v[228:231], v[212:215], v[22:25]
	v_mfma_f32_16x16x32_bf16 v[26:29], v[232:235], v[212:215], v[26:29]
	v_mfma_f32_16x16x32_bf16 v[30:33], v[236:239], v[212:215], v[30:33]
	s_waitcnt lgkmcnt(5)
	v_mfma_f32_16x16x32_bf16 v[34:37], v[224:227], v[216:219], v[34:37]
	v_mfma_f32_16x16x32_bf16 v[38:41], v[228:231], v[216:219], v[38:41]
	v_mfma_f32_16x16x32_bf16 v[42:45], v[232:235], v[216:219], v[42:45]
	v_mfma_f32_16x16x32_bf16 v[46:49], v[236:239], v[216:219], v[46:49]
	s_waitcnt lgkmcnt(4)
	v_mfma_f32_16x16x32_bf16 v[50:53], v[224:227], v[220:223], v[50:53]
	v_mfma_f32_16x16x32_bf16 v[54:57], v[228:231], v[220:223], v[54:57]
	v_mfma_f32_16x16x32_bf16 v[58:61], v[232:235], v[220:223], v[58:61]
	v_mfma_f32_16x16x32_bf16 v[62:65], v[236:239], v[220:223], v[62:65]
	s_waitcnt lgkmcnt(3)
	v_mfma_f32_16x16x32_bf16 v[74:77], v[240:243], v[208:211], v[74:77]
	s_waitcnt lgkmcnt(2)
	v_mfma_f32_16x16x32_bf16 v[78:81], v[244:247], v[208:211], v[78:81]
	s_waitcnt lgkmcnt(1)
	v_mfma_f32_16x16x32_bf16 v[82:85], v[248:251], v[208:211], v[82:85]
	s_waitcnt lgkmcnt(0)
	v_mfma_f32_16x16x32_bf16 v[86:89], v[156:159], v[208:211], v[86:89]
	v_mfma_f32_16x16x32_bf16 v[90:93], v[240:243], v[212:215], v[90:93]
	v_mfma_f32_16x16x32_bf16 v[94:97], v[244:247], v[212:215], v[94:97]
	v_mfma_f32_16x16x32_bf16 v[98:101], v[248:251], v[212:215], v[98:101]
	v_mfma_f32_16x16x32_bf16 v[102:105], v[156:159], v[212:215], v[102:105]
	v_mfma_f32_16x16x32_bf16 v[106:109], v[240:243], v[216:219], v[106:109]
	v_mfma_f32_16x16x32_bf16 v[110:113], v[244:247], v[216:219], v[110:113]
	v_mfma_f32_16x16x32_bf16 v[114:117], v[248:251], v[216:219], v[114:117]
	v_mfma_f32_16x16x32_bf16 v[118:121], v[156:159], v[216:219], v[118:121]
	v_mfma_f32_16x16x32_bf16 v[122:125], v[240:243], v[220:223], v[122:125]
	v_mfma_f32_16x16x32_bf16 v[126:129], v[244:247], v[220:223], v[126:129]
	v_mfma_f32_16x16x32_bf16 v[130:133], v[248:251], v[220:223], v[130:133]
	v_mfma_f32_16x16x32_bf16 v[134:137], v[156:159], v[220:223], v[134:137]
	s_sub_u32 s46, s46, 1
	s_cmp_lg_u32 s46, 0
	s_cbranch_scc1 .Lffn1_kloop
	s_waitcnt vmcnt(6)
	s_barrier
; #define BLOAD(A_, B_, kt) do { _Pragma("unroll") for (int i = 0; i < 4; ++i) { \
;     A_[i] = *(const u32x4*)((const char*)Ap + (aoff + (unsigned)(32 * i * lda + (kt) * 64) * 2u)); B_[i] = *(const u32x4*)((const char*)Wt + (woff + (unsigned)(32 * i * K + (kt) * 64) * 2u)); } } while (0)
; #define BLOAD(A_, B_, kt) do { _Pragma("unroll") for (int i = 0; i < 4; ++i) { \
;     A_[i] = *(const u32x4*)((const char*)Ap + (aoff + (unsigned)(32 * i * lda + (kt) * 64) * 2u)); B_[i] = *(const u32x4*)((const char*)Wt + (woff + (unsigned)(32 * i * K + (kt) * 64) * 2u)); } } while (0)
; #define BSTORE(A_, B_, buf) do { _Pragma("unroll") for (int i = 0; i < 4; ++i) { \
;     *(u32x4*)&As[(buf) * GBUF + (srow + 32 * i) * LDT + sc8] = A_[i]; \
;     *(u32x4*)&Bs[(buf) * GBUF + (srow + 32 * i) * LDT + sc8] = B_[i]; } } while (0)
; template <int NK>
; DI void gemm_run(PF& pf, const u16* __restrict__ Ap, int lda, const u16* __restrict__ Wt, f32x16 (&acc)[2][2], char* smem) {
;     ...
; #pragma unroll
;   for (int kt = 0; kt < nk; kt += 2) {
;     BCOMP(0);
;     BSTORE(pf.a1, pf.b1, 1);
;     if (kt + 3 < nk) BLOAD(pf.a1, pf.b1, kt + 3);
;     __syncthreads();
;     BCOMP(1);
;     if (kt + 2 < nk) { BSTORE(pf.a0, pf.b0, 0); if (kt + 4 < nk) BLOAD(pf.a0, pf.b0, kt + 4); }
;     __syncthreads();
;   }
	ds_read_b128 v[208:211], v138 offset:0
	ds_read_b128 v[224:227], v140 offset:0
	ds_read_b128 v[228:231], v140 offset:1024
	ds_read_b128 v[232:235], v140 offset:2048
	ds_read_b128 v[236:239], v140 offset:3072
	ds_read_b128 v[212:215], v138 offset:1024
	ds_read_b128 v[216:219], v138 offset:2048
	ds_read_b128 v[220:223], v138 offset:3072
	ds_read_b128 v[240:243], v140 offset:8192
	ds_read_b128 v[244:247], v140 offset:9216
	ds_read_b128 v[248:251], v140 offset:10240
	ds_read_b128 v[156:159], v140 offset:11264
	s_waitcnt lgkmcnt(10)
	v_mfma_f32_16x16x32_bf16 v[2:5], v[224:227], v[208:211], v[2:5]
	s_waitcnt lgkmcnt(9)
	v_mfma_f32_16x16x32_bf16 v[6:9], v[228:231], v[208:211], v[6:9]
	s_waitcnt lgkmcnt(8)
	v_mfma_f32_16x16x32_bf16 v[10:13], v[232:235], v[208:211], v[10:13]
	s_waitcnt lgkmcnt(7)
	v_mfma_f32_16x16x32_bf16 v[14:17], v[236:239], v[208:211], v[14:17]
	s_waitcnt lgkmcnt(6)
	v_mfma_f32_16x16x32_bf16 v[18:21], v[224:227], v[212:215], v[18:21]
	v_mfma_f32_16x16x32_bf16 v[22:25], v[228:231], v[212:215], v[22:25]
	v_mfma_f32_16x16x32_bf16 v[26:29], v[232:235], v[212:215], v[26:29]
	v_mfma_f32_16x16x32_bf16 v[30:33], v[236:239], v[212:215], v[30:33]
	s_waitcnt lgkmcnt(5)
	v_mfma_f32_16x16x32_bf16 v[34:37], v[224:227], v[216:219], v[34:37]
	v_mfma_f32_16x16x32_bf16 v[38:41], v[228:231], v[216:219], v[38:41]
	v_mfma_f32_16x16x32_bf16 v[42:45], v[232:235], v[216:219], v[42:45]
	v_mfma_f32_16x16x32_bf16 v[46:49], v[236:239], v[216:219], v[46:49]
	s_waitcnt lgkmcnt(4)
	v_mfma_f32_16x16x32_bf16 v[50:53], v[224:227], v[220:223], v[50:53]
	v_mfma_f32_16x16x32_bf16 v[54:57], v[228:231], v[220:223], v[54:57]
	v_mfma_f32_16x16x32_bf16 v[58:61], v[232:235], v[220:223], v[58:61]
	v_mfma_f32_16x16x32_bf16 v[62:65], v[236:239], v[220:223], v[62:65]
	s_waitcnt lgkmcnt(3)
	v_mfma_f32_16x16x32_bf16 v[74:77], v[240:243], v[208:211], v[74:77]
	s_waitcnt lgkmcnt(2)
	v_mfma_f32_16x16x32_bf16 v[78:81], v[244:247], v[208:211], v[78:81]
	s_waitcnt lgkmcnt(1)
	v_mfma_f32_16x16x32_bf16 v[82:85], v[248:251], v[208:211], v[82:85]
	s_waitcnt lgkmcnt(0)
	v_mfma_f32_16x16x32_bf16 v[86:89], v[156:159], v[208:211], v[86:89]
	v_mfma_f32_16x16x32_bf16 v[90:93], v[240:243], v[212:215], v[90:93]
	v_mfma_f32_16x16x32_bf16 v[94:97], v[244:247], v[212:215], v[94:97]
	v_mfma_f32_16x16x32_bf16 v[98:101], v[248:251], v[212:215], v[98:101]
	v_mfma_f32_16x16x32_bf16 v[102:105], v[156:159], v[212:215], v[102:105]
	v_mfma_f32_16x16x32_bf16 v[106:109], v[240:243], v[216:219], v[106:109]
	v_mfma_f32_16x16x32_bf16 v[110:113], v[244:247], v[216:219], v[110:113]
	v_mfma_f32_16x16x32_bf16 v[114:117], v[248:251], v[216:219], v[114:117]
	v_mfma_f32_16x16x32_bf16 v[118:121], v[156:159], v[216:219], v[118:121]
	v_mfma_f32_16x16x32_bf16 v[122:125], v[240:243], v[220:223], v[122:125]
	v_mfma_f32_16x16x32_bf16 v[126:129], v[244:247], v[220:223], v[126:129]
	v_mfma_f32_16x16x32_bf16 v[130:133], v[248:251], v[220:223], v[130:133]
	v_mfma_f32_16x16x32_bf16 v[134:137], v[156:159], v[220:223], v[134:137]
	s_waitcnt vmcnt(0)
	s_barrier
	ds_read_b128 v[208:211], v138 offset:24576
	ds_read_b128 v[224:227], v140 offset:24576
	ds_read_b128 v[228:231], v140 offset:25600
	ds_read_b128 v[232:235], v140 offset:26624
	ds_read_b128 v[236:239], v140 offset:27648
	ds_read_b128 v[212:215], v138 offset:25600
	ds_read_b128 v[216:219], v138 offset:26624
	ds_read_b128 v[220:223], v138 offset:27648
	ds_read_b128 v[240:243], v140 offset:32768
	ds_read_b128 v[244:247], v140 offset:33792
	ds_read_b128 v[248:251], v140 offset:34816
	ds_read_b128 v[156:159], v140 offset:35840
	s_waitcnt lgkmcnt(10)
	v_mfma_f32_16x16x32_bf16 v[2:5], v[224:227], v[208:211], v[2:5]
	s_waitcnt lgkmcnt(9)
	v_mfma_f32_16x16x32_bf16 v[6:9], v[228:231], v[208:211], v[6:9]
	s_waitcnt lgkmcnt(8)
	v_mfma_f32_16x16x32_bf16 v[10:13], v[232:235], v[208:211], v[10:13]
	s_waitcnt lgkmcnt(7)
	v_mfma_f32_16x16x32_bf16 v[14:17], v[236:239], v[208:211], v[14:17]
	s_waitcnt lgkmcnt(6)
	v_mfma_f32_16x16x32_bf16 v[18:21], v[224:227], v[212:215], v[18:21]
	v_mfma_f32_16x16x32_bf16 v[22:25], v[228:231], v[212:215], v[22:25]
	v_mfma_f32_16x16x32_bf16 v[26:29], v[232:235], v[212:215], v[26:29]
	v_mfma_f32_16x16x32_bf16 v[30:33], v[236:239], v[212:215], v[30:33]
	s_waitcnt lgkmcnt(5)
	v_mfma_f32_16x16x32_bf16 v[34:37], v[224:227], v[216:219], v[34:37]
	v_mfma_f32_16x16x32_bf16 v[38:41], v[228:231], v[216:219], v[38:41]
	v_mfma_f32_16x16x32_bf16 v[42:45], v[232:235], v[216:219], v[42:45]
	v_mfma_f32_16x16x32_bf16 v[46:49], v[236:239], v[216:219], v[46:49]
	s_waitcnt lgkmcnt(4)
	v_mfma_f32_16x16x32_bf16 v[50:53], v[224:227], v[220:223], v[50:53]
	v_mfma_f32_16x16x32_bf16 v[54:57], v[228:231], v[220:223], v[54:57]
	v_mfma_f32_16x16x32_bf16 v[58:61], v[232:235], v[220:223], v[58:61]
	v_mfma_f32_16x16x32_bf16 v[62:65], v[236:239], v[220:223], v[62:65]
	s_waitcnt lgkmcnt(3)
	v_mfma_f32_16x16x32_bf16 v[74:77], v[240:243], v[208:211], v[74:77]
	s_waitcnt lgkmcnt(2)
	v_mfma_f32_16x16x32_bf16 v[78:81], v[244:247], v[208:211], v[78:81]
	s_waitcnt lgkmcnt(1)
	v_mfma_f32_16x16x32_bf16 v[82:85], v[248:251], v[208:211], v[82:85]
	s_waitcnt lgkmcnt(0)
	v_mfma_f32_16x16x32_bf16 v[86:89], v[156:159], v[208:211], v[86:89]
	v_mfma_f32_16x16x32_bf16 v[90:93], v[240:243], v[212:215], v[90:93]
	v_mfma_f32_16x16x32_bf16 v[94:97], v[244:247], v[212:215], v[94:97]
	v_mfma_f32_16x16x32_bf16 v[98:101], v[248:251], v[212:215], v[98:101]
	v_mfma_f32_16x16x32_bf16 v[102:105], v[156:159], v[212:215], v[102:105]
	v_mfma_f32_16x16x32_bf16 v[106:109], v[240:243], v[216:219], v[106:109]
	v_mfma_f32_16x16x32_bf16 v[110:113], v[244:247], v[216:219], v[110:113]
	v_mfma_f32_16x16x32_bf16 v[114:117], v[248:251], v[216:219], v[114:117]
	v_mfma_f32_16x16x32_bf16 v[118:121], v[156:159], v[216:219], v[118:121]
	v_mfma_f32_16x16x32_bf16 v[122:125], v[240:243], v[220:223], v[122:125]
	v_mfma_f32_16x16x32_bf16 v[126:129], v[244:247], v[220:223], v[126:129]
	v_mfma_f32_16x16x32_bf16 v[130:133], v[248:251], v[220:223], v[130:133]
	v_mfma_f32_16x16x32_bf16 v[134:137], v[156:159], v[220:223], v[134:137]
	s_barrier

; #define BLOAD(A_, B_, kt) do { _Pragma("unroll") for (int i = 0; i < 4; ++i) { \
;     A_[i] = *(const u32x4*)((const char*)Ap + (aoff + (unsigned)(32 * i * lda + (kt) * 64) * 2u)); B_[i] = *(const u32x4*)((const char*)Wt + (woff + (unsigned)(32 * i * K + (kt) * 64) * 2u)); } } while (0)
; #define BLOAD(A_, B_, kt) do { _Pragma("unroll") for (int i = 0; i < 4; ++i) { \
;     A_[i] = *(const u32x4*)((const char*)Ap + (aoff + (unsigned)(32 * i * lda + (kt) * 64) * 2u)); B_[i] = *(const u32x4*)((const char*)Wt + (woff + (unsigned)(32 * i * K + (kt) * 64) * 2u)); } } while (0)
; #define BSTORE(A_, B_, buf) do { _Pragma("unroll") for (int i = 0; i < 4; ++i) { \
;     *(u32x4*)&As[(buf) * GBUF + (srow + 32 * i) * LDT + sc8] = A_[i]; \
;     *(u32x4*)&Bs[(buf) * GBUF + (srow + 32 * i) * LDT + sc8] = B_[i]; } } while (0)
; template <int NK>
; DI void gemm_run(PF& pf, const u16* __restrict__ Ap, int lda, const u16* __restrict__ Wt, f32x16 (&acc)[2][2], char* smem) {
;     ...
; #pragma unroll
;   for (int kt = 0; kt < nk; kt += 2) {
;     BCOMP(0);
;     BSTORE(pf.a1, pf.b1, 1);
;     if (kt + 3 < nk) BLOAD(pf.a1, pf.b1, kt + 3);
;     __syncthreads();
;     BCOMP(1);
;     if (kt + 2 < nk) { BSTORE(pf.a0, pf.b0, 0); if (kt + 4 < nk) BLOAD(pf.a0, pf.b0, kt + 4); }
;     __syncthreads();
;   }
.Lout_kloop:
	s_waitcnt vmcnt(6)
	s_barrier
	ds_read_b128 v[224:227], v126 offset:0
	ds_read_b128 v[240:243], v128 offset:0
	ds_read_b128 v[244:247], v128 offset:1024
	ds_read_b128 v[248:251], v128 offset:2048
	ds_read_b128 v[156:159], v128 offset:3072
	s_add_u32 m0, s42, 0xc000
	s_add_u32 s28, s28, 0x100000
	s_addc_u32 s29, s29, 0
	global_load_lds_dwordx4 v143, s[28:29]
	global_load_lds_dwordx4 v144, s[28:29] offset:1024
	s_add_u32 m0, s43, 0xc000
	s_add_u32 s30, s30, 0x10000
	s_addc_u32 s31, s31, 0
	global_load_lds_dwordx4 v145, s[30:31]
	global_load_lds_dwordx4 v146, s[30:31] offset:1024
	global_load_lds_dwordx4 v147, s[30:31] offset:2048
	global_load_lds_dwordx4 v148, s[30:31] offset:3072
	ds_read_b128 v[228:231], v126 offset:1024
	ds_read_b128 v[232:235], v126 offset:2048
	ds_read_b128 v[236:239], v126 offset:3072
	ds_read_b128 v[160:163], v128 offset:8192
	ds_read_b128 v[164:167], v128 offset:9216
	ds_read_b128 v[168:171], v128 offset:10240
	ds_read_b128 v[122:125], v128 offset:11264
	s_waitcnt lgkmcnt(10)
	v_mfma_f32_16x16x32_bf16 v[2:5], v[240:243], v[224:227], v[2:5]
	s_waitcnt lgkmcnt(9)
	v_mfma_f32_16x16x32_bf16 v[6:9], v[244:247], v[224:227], v[6:9]
	s_waitcnt lgkmcnt(8)
	v_mfma_f32_16x16x32_bf16 v[10:13], v[248:251], v[224:227], v[10:13]
	s_waitcnt lgkmcnt(7)
	v_mfma_f32_16x16x32_bf16 v[14:17], v[156:159], v[224:227], v[14:17]
	s_waitcnt lgkmcnt(6)
	v_mfma_f32_16x16x32_bf16 v[18:21], v[240:243], v[228:231], v[18:21]
	v_mfma_f32_16x16x32_bf16 v[22:25], v[244:247], v[228:231], v[22:25]
	v_mfma_f32_16x16x32_bf16 v[26:29], v[248:251], v[228:231], v[26:29]
	v_mfma_f32_16x16x32_bf16 v[30:33], v[156:159], v[228:231], v[30:33]
	s_waitcnt lgkmcnt(5)
	v_mfma_f32_16x16x32_bf16 v[34:37], v[240:243], v[232:235], v[34:37]
	v_mfma_f32_16x16x32_bf16 v[38:41], v[244:247], v[232:235], v[38:41]
	v_mfma_f32_16x16x32_bf16 v[42:45], v[248:251], v[232:235], v[42:45]
	v_mfma_f32_16x16x32_bf16 v[46:49], v[156:159], v[232:235], v[46:49]
	s_waitcnt lgkmcnt(4)
	v_mfma_f32_16x16x32_bf16 v[50:53], v[240:243], v[236:239], v[50:53]
	v_mfma_f32_16x16x32_bf16 v[54:57], v[244:247], v[236:239], v[54:57]
	v_mfma_f32_16x16x32_bf16 v[58:61], v[248:251], v[236:239], v[58:61]
	v_mfma_f32_16x16x32_bf16 v[62:65], v[156:159], v[236:239], v[62:65]
	s_waitcnt lgkmcnt(3)
	v_mfma_f32_16x16x32_bf16 v[74:77], v[160:163], v[224:227], v[74:77]
	s_waitcnt lgkmcnt(2)
	v_mfma_f32_16x16x32_bf16 v[78:81], v[164:167], v[224:227], v[78:81]
	s_waitcnt lgkmcnt(1)
	v_mfma_f32_16x16x32_bf16 v[82:85], v[168:171], v[224:227], v[82:85]
	s_waitcnt lgkmcnt(0)
	v_mfma_f32_16x16x32_bf16 v[86:89], v[122:125], v[224:227], v[86:89]
	v_mfma_f32_16x16x32_bf16 v[90:93], v[160:163], v[228:231], v[90:93]
	v_mfma_f32_16x16x32_bf16 v[94:97], v[164:167], v[228:231], v[94:97]
	v_mfma_f32_16x16x32_bf16 v[98:101], v[168:171], v[228:231], v[98:101]
	v_mfma_f32_16x16x32_bf16 v[102:105], v[122:125], v[228:231], v[102:105]
	v_mfma_f32_16x16x32_bf16 v[106:109], v[160:163], v[232:235], v[106:109]
	v_mfma_f32_16x16x32_bf16 v[110:113], v[164:167], v[232:235], v[110:113]
	v_mfma_f32_16x16x32_bf16 v[114:117], v[168:171], v[232:235], v[114:117]
	v_mfma_f32_16x16x32_bf16 v[118:121], v[122:125], v[232:235], v[118:121]
	v_mfma_f32_16x16x32_bf16 v[208:211], v[160:163], v[236:239], v[208:211]
	v_mfma_f32_16x16x32_bf16 v[212:215], v[164:167], v[236:239], v[212:215]
	v_mfma_f32_16x16x32_bf16 v[216:219], v[168:171], v[236:239], v[216:219]
	v_mfma_f32_16x16x32_bf16 v[220:223], v[122:125], v[236:239], v[220:223]
	s_waitcnt vmcnt(6)
	s_barrier
	ds_read_b128 v[224:227], v126 offset:24576
	ds_read_b128 v[240:243], v128 offset:24576
	ds_read_b128 v[244:247], v128 offset:25600
	ds_read_b128 v[248:251], v128 offset:26624
	ds_read_b128 v[156:159], v128 offset:27648
	s_add_u32 m0, s42, 0x0
	s_add_u32 s28, s28, 0x100000
	s_addc_u32 s29, s29, 0
	global_load_lds_dwordx4 v143, s[28:29]
	global_load_lds_dwordx4 v144, s[28:29] offset:1024
	s_add_u32 m0, s43, 0x0
	s_add_u32 s30, s30, 0x10000
	s_addc_u32 s31, s31, 0
	global_load_lds_dwordx4 v145, s[30:31]
	global_load_lds_dwordx4 v146, s[30:31] offset:1024
	global_load_lds_dwordx4 v147, s[30:31] offset:2048
	global_load_lds_dwordx4 v148, s[30:31] offset:3072
	ds_read_b128 v[228:231], v126 offset:25600
	ds_read_b128 v[232:235], v126 offset:26624
	ds_read_b128 v[236:239], v126 offset:27648
	ds_read_b128 v[160:163], v128 offset:32768
	ds_read_b128 v[164:167], v128 offset:33792
	ds_read_b128 v[168:171], v128 offset:34816
	ds_read_b128 v[122:125], v128 offset:35840
	s_waitcnt lgkmcnt(10)
	v_mfma_f32_16x16x32_bf16 v[2:5], v[240:243], v[224:227], v[2:5]
	s_waitcnt lgkmcnt(9)
	v_mfma_f32_16x16x32_bf16 v[6:9], v[244:247], v[224:227], v[6:9]
	s_waitcnt lgkmcnt(8)
	v_mfma_f32_16x16x32_bf16 v[10:13], v[248:251], v[224:227], v[10:13]
	s_waitcnt lgkmcnt(7)
	v_mfma_f32_16x16x32_bf16 v[14:17], v[156:159], v[224:227], v[14:17]
	s_waitcnt lgkmcnt(6)
	v_mfma_f32_16x16x32_bf16 v[18:21], v[240:243], v[228:231], v[18:21]
	v_mfma_f32_16x16x32_bf16 v[22:25], v[244:247], v[228:231], v[22:25]
	v_mfma_f32_16x16x32_bf16 v[26:29], v[248:251], v[228:231], v[26:29]
	v_mfma_f32_16x16x32_bf16 v[30:33], v[156:159], v[228:231], v[30:33]
	s_waitcnt lgkmcnt(5)
	v_mfma_f32_16x16x32_bf16 v[34:37], v[240:243], v[232:235], v[34:37]
	v_mfma_f32_16x16x32_bf16 v[38:41], v[244:247], v[232:235], v[38:41]
	v_mfma_f32_16x16x32_bf16 v[42:45], v[248:251], v[232:235], v[42:45]
	v_mfma_f32_16x16x32_bf16 v[46:49], v[156:159], v[232:235], v[46:49]
	s_waitcnt lgkmcnt(4)
	v_mfma_f32_16x16x32_bf16 v[50:53], v[240:243], v[236:239], v[50:53]
	v_mfma_f32_16x16x32_bf16 v[54:57], v[244:247], v[236:239], v[54:57]
	v_mfma_f32_16x16x32_bf16 v[58:61], v[248:251], v[236:239], v[58:61]
	v_mfma_f32_16x16x32_bf16 v[62:65], v[156:159], v[236:239], v[62:65]
	s_waitcnt lgkmcnt(3)
	v_mfma_f32_16x16x32_bf16 v[74:77], v[160:163], v[224:227], v[74:77]
	s_waitcnt lgkmcnt(2)
	v_mfma_f32_16x16x32_bf16 v[78:81], v[164:167], v[224:227], v[78:81]
	s_waitcnt lgkmcnt(1)
	v_mfma_f32_16x16x32_bf16 v[82:85], v[168:171], v[224:227], v[82:85]
	s_waitcnt lgkmcnt(0)
	v_mfma_f32_16x16x32_bf16 v[86:89], v[122:125], v[224:227], v[86:89]
	v_mfma_f32_16x16x32_bf16 v[90:93], v[160:163], v[228:231], v[90:93]
	v_mfma_f32_16x16x32_bf16 v[94:97], v[164:167], v[228:231], v[94:97]
	v_mfma_f32_16x16x32_bf16 v[98:101], v[168:171], v[228:231], v[98:101]
	v_mfma_f32_16x16x32_bf16 v[102:105], v[122:125], v[228:231], v[102:105]
	v_mfma_f32_16x16x32_bf16 v[106:109], v[160:163], v[232:235], v[106:109]
	v_mfma_f32_16x16x32_bf16 v[110:113], v[164:167], v[232:235], v[110:113]
	v_mfma_f32_16x16x32_bf16 v[114:117], v[168:171], v[232:235], v[114:117]
	v_mfma_f32_16x16x32_bf16 v[118:121], v[122:125], v[232:235], v[118:121]
	v_mfma_f32_16x16x32_bf16 v[208:211], v[160:163], v[236:239], v[208:211]
	v_mfma_f32_16x16x32_bf16 v[212:215], v[164:167], v[236:239], v[212:215]
	v_mfma_f32_16x16x32_bf16 v[216:219], v[168:171], v[236:239], v[216:219]
	v_mfma_f32_16x16x32_bf16 v[220:223], v[122:125], v[236:239], v[220:223]
	s_waitcnt vmcnt(6)
	s_barrier
; #define BLOAD(A_, B_, kt) do { _Pragma("unroll") for (int i = 0; i < 4; ++i) { \
;     A_[i] = *(const u32x4*)((const char*)Ap + (aoff + (unsigned)(32 * i * lda + (kt) * 64) * 2u)); B_[i] = *(const u32x4*)((const char*)Wt + (woff + (unsigned)(32 * i * K + (kt) * 64) * 2u)); } } while (0)
; #define BLOAD(A_, B_, kt) do { _Pragma("unroll") for (int i = 0; i < 4; ++i) { \
;     A_[i] = *(const u32x4*)((const char*)Ap + (aoff + (unsigned)(32 * i * lda + (kt) * 64) * 2u)); B_[i] = *(const u32x4*)((const char*)Wt + (woff + (unsigned)(32 * i * K + (kt) * 64) * 2u)); } } while (0)
; #define BSTORE(A_, B_, buf) do { _Pragma("unroll") for (int i = 0; i < 4; ++i) { \
;     *(u32x4*)&As[(buf) * GBUF + (srow + 32 * i) * LDT + sc8] = A_[i]; \
;     *(u32x4*)&Bs[(buf) * GBUF + (srow + 32 * i) * LDT + sc8] = B_[i]; } } while (0)
; template <int NK>
; DI void gemm_run(PF& pf, const u16* __restrict__ Ap, int lda, const u16* __restrict__ Wt, f32x16 (&acc)[2][2], char* smem) {
;     ...
; #pragma unroll
;   for (int kt = 0; kt < nk; kt += 2) {
;     BCOMP(0);
;     BSTORE(pf.a1, pf.b1, 1);
;     if (kt + 3 < nk) BLOAD(pf.a1, pf.b1, kt + 3);
;     __syncthreads();
;     BCOMP(1);
;     if (kt + 2 < nk) { BSTORE(pf.a0, pf.b0, 0); if (kt + 4 < nk) BLOAD(pf.a0, pf.b0, kt + 4); }
;     __syncthreads();
;   }
	ds_read_b128 v[224:227], v126 offset:49152
	ds_read_b128 v[240:243], v128 offset:49152
	ds_read_b128 v[244:247], v128 offset:50176
	ds_read_b128 v[248:251], v128 offset:51200
	ds_read_b128 v[156:159], v128 offset:52224
	s_add_u32 m0, s42, 0x6000
	s_add_u32 s28, s28, 0x100000
	s_addc_u32 s29, s29, 0
	global_load_lds_dwordx4 v143, s[28:29]
	global_load_lds_dwordx4 v144, s[28:29] offset:1024
	s_add_u32 m0, s43, 0x6000
	s_add_u32 s30, s30, 0x10000
	s_addc_u32 s31, s31, 0
	global_load_lds_dwordx4 v145, s[30:31]
	global_load_lds_dwordx4 v146, s[30:31] offset:1024
	global_load_lds_dwordx4 v147, s[30:31] offset:2048
	global_load_lds_dwordx4 v148, s[30:31] offset:3072
	ds_read_b128 v[228:231], v126 offset:50176
	ds_read_b128 v[232:235], v126 offset:51200
	ds_read_b128 v[236:239], v126 offset:52224
	ds_read_b128 v[160:163], v128 offset:57344
	ds_read_b128 v[164:167], v128 offset:58368
	ds_read_b128 v[168:171], v128 offset:59392
	ds_read_b128 v[122:125], v128 offset:60416
	s_waitcnt lgkmcnt(10)
	v_mfma_f32_16x16x32_bf16 v[2:5], v[240:243], v[224:227], v[2:5]
	s_waitcnt lgkmcnt(9)
	v_mfma_f32_16x16x32_bf16 v[6:9], v[244:247], v[224:227], v[6:9]
	s_waitcnt lgkmcnt(8)
	v_mfma_f32_16x16x32_bf16 v[10:13], v[248:251], v[224:227], v[10:13]
	s_waitcnt lgkmcnt(7)
	v_mfma_f32_16x16x32_bf16 v[14:17], v[156:159], v[224:227], v[14:17]
	s_waitcnt lgkmcnt(6)
	v_mfma_f32_16x16x32_bf16 v[18:21], v[240:243], v[228:231], v[18:21]
	v_mfma_f32_16x16x32_bf16 v[22:25], v[244:247], v[228:231], v[22:25]
	v_mfma_f32_16x16x32_bf16 v[26:29], v[248:251], v[228:231], v[26:29]
	v_mfma_f32_16x16x32_bf16 v[30:33], v[156:159], v[228:231], v[30:33]
	s_waitcnt lgkmcnt(5)
	v_mfma_f32_16x16x32_bf16 v[34:37], v[240:243], v[232:235], v[34:37]
	v_mfma_f32_16x16x32_bf16 v[38:41], v[244:247], v[232:235], v[38:41]
	v_mfma_f32_16x16x32_bf16 v[42:45], v[248:251], v[232:235], v[42:45]
	v_mfma_f32_16x16x32_bf16 v[46:49], v[156:159], v[232:235], v[46:49]
	s_waitcnt lgkmcnt(4)
	v_mfma_f32_16x16x32_bf16 v[50:53], v[240:243], v[236:239], v[50:53]
	v_mfma_f32_16x16x32_bf16 v[54:57], v[244:247], v[236:239], v[54:57]
	v_mfma_f32_16x16x32_bf16 v[58:61], v[248:251], v[236:239], v[58:61]
	v_mfma_f32_16x16x32_bf16 v[62:65], v[156:159], v[236:239], v[62:65]
	s_waitcnt lgkmcnt(3)
	v_mfma_f32_16x16x32_bf16 v[74:77], v[160:163], v[224:227], v[74:77]
	s_waitcnt lgkmcnt(2)
	v_mfma_f32_16x16x32_bf16 v[78:81], v[164:167], v[224:227], v[78:81]
	s_waitcnt lgkmcnt(1)
	v_mfma_f32_16x16x32_bf16 v[82:85], v[168:171], v[224:227], v[82:85]
	s_waitcnt lgkmcnt(0)
	v_mfma_f32_16x16x32_bf16 v[86:89], v[122:125], v[224:227], v[86:89]
	v_mfma_f32_16x16x32_bf16 v[90:93], v[160:163], v[228:231], v[90:93]
	v_mfma_f32_16x16x32_bf16 v[94:97], v[164:167], v[228:231], v[94:97]
	v_mfma_f32_16x16x32_bf16 v[98:101], v[168:171], v[228:231], v[98:101]
	v_mfma_f32_16x16x32_bf16 v[102:105], v[122:125], v[228:231], v[102:105]
	v_mfma_f32_16x16x32_bf16 v[106:109], v[160:163], v[232:235], v[106:109]
	v_mfma_f32_16x16x32_bf16 v[110:113], v[164:167], v[232:235], v[110:113]
	v_mfma_f32_16x16x32_bf16 v[114:117], v[168:171], v[232:235], v[114:117]
	v_mfma_f32_16x16x32_bf16 v[118:121], v[122:125], v[232:235], v[118:121]
	v_mfma_f32_16x16x32_bf16 v[208:211], v[160:163], v[236:239], v[208:211]
	v_mfma_f32_16x16x32_bf16 v[212:215], v[164:167], v[236:239], v[212:215]
	v_mfma_f32_16x16x32_bf16 v[216:219], v[168:171], v[236:239], v[216:219]
	v_mfma_f32_16x16x32_bf16 v[220:223], v[122:125], v[236:239], v[220:223]
	s_sub_u32 s46, s46, 1
	s_cmp_lg_u32 s46, 0
	s_cbranch_scc1 .Lout_kloop
	s_waitcnt vmcnt(6)
	s_barrier
	ds_read_b128 v[224:227], v126 offset:0
	ds_read_b128 v[240:243], v128 offset:0
	ds_read_b128 v[244:247], v128 offset:1024
	ds_read_b128 v[248:251], v128 offset:2048
	ds_read_b128 v[156:159], v128 offset:3072
	ds_read_b128 v[228:231], v126 offset:1024
	ds_read_b128 v[232:235], v126 offset:2048
	ds_read_b128 v[236:239], v126 offset:3072
	ds_read_b128 v[160:163], v128 offset:8192
	ds_read_b128 v[164:167], v128 offset:9216
	ds_read_b128 v[168:171], v128 offset:10240
	ds_read_b128 v[122:125], v128 offset:11264
	s_waitcnt lgkmcnt(10)
	v_mfma_f32_16x16x32_bf16 v[2:5], v[240:243], v[224:227], v[2:5]
	s_waitcnt lgkmcnt(9)
	v_mfma_f32_16x16x32_bf16 v[6:9], v[244:247], v[224:227], v[6:9]
	s_waitcnt lgkmcnt(8)
	v_mfma_f32_16x16x32_bf16 v[10:13], v[248:251], v[224:227], v[10:13]
	s_waitcnt lgkmcnt(7)
	v_mfma_f32_16x16x32_bf16 v[14:17], v[156:159], v[224:227], v[14:17]
	s_waitcnt lgkmcnt(6)
	v_mfma_f32_16x16x32_bf16 v[18:21], v[240:243], v[228:231], v[18:21]
	v_mfma_f32_16x16x32_bf16 v[22:25], v[244:247], v[228:231], v[22:25]
	v_mfma_f32_16x16x32_bf16 v[26:29], v[248:251], v[228:231], v[26:29]
	v_mfma_f32_16x16x32_bf16 v[30:33], v[156:159], v[228:231], v[30:33]
	s_waitcnt lgkmcnt(5)
	v_mfma_f32_16x16x32_bf16 v[34:37], v[240:243], v[232:235], v[34:37]
	v_mfma_f32_16x16x32_bf16 v[38:41], v[244:247], v[232:235], v[38:41]
	v_mfma_f32_16x16x32_bf16 v[42:45], v[248:251], v[232:235], v[42:45]
	v_mfma_f32_16x16x32_bf16 v[46:49], v[156:159], v[232:235], v[46:49]
	s_waitcnt lgkmcnt(4)
	v_mfma_f32_16x16x32_bf16 v[50:53], v[240:243], v[236:239], v[50:53]
	v_mfma_f32_16x16x32_bf16 v[54:57], v[244:247], v[236:239], v[54:57]
	v_mfma_f32_16x16x32_bf16 v[58:61], v[248:251], v[236:239], v[58:61]
	v_mfma_f32_16x16x32_bf16 v[62:65], v[156:159], v[236:239], v[62:65]
	s_waitcnt lgkmcnt(3)
	v_mfma_f32_16x16x32_bf16 v[74:77], v[160:163], v[224:227], v[74:77]
	s_waitcnt lgkmcnt(2)
	v_mfma_f32_16x16x32_bf16 v[78:81], v[164:167], v[224:227], v[78:81]
	s_waitcnt lgkmcnt(1)
	v_mfma_f32_16x16x32_bf16 v[82:85], v[168:171], v[224:227], v[82:85]
	s_waitcnt lgkmcnt(0)
	v_mfma_f32_16x16x32_bf16 v[86:89], v[122:125], v[224:227], v[86:89]
	v_mfma_f32_16x16x32_bf16 v[90:93], v[160:163], v[228:231], v[90:93]
	v_mfma_f32_16x16x32_bf16 v[94:97], v[164:167], v[228:231], v[94:97]
	v_mfma_f32_16x16x32_bf16 v[98:101], v[168:171], v[228:231], v[98:101]
	v_mfma_f32_16x16x32_bf16 v[102:105], v[122:125], v[228:231], v[102:105]
	v_mfma_f32_16x16x32_bf16 v[106:109], v[160:163], v[232:235], v[106:109]
	v_mfma_f32_16x16x32_bf16 v[110:113], v[164:167], v[232:235], v[110:113]
	v_mfma_f32_16x16x32_bf16 v[114:117], v[168:171], v[232:235], v[114:117]
	v_mfma_f32_16x16x32_bf16 v[118:121], v[122:125], v[232:235], v[118:121]
	v_mfma_f32_16x16x32_bf16 v[208:211], v[160:163], v[236:239], v[208:211]
	v_mfma_f32_16x16x32_bf16 v[212:215], v[164:167], v[236:239], v[212:215]
	v_mfma_f32_16x16x32_bf16 v[216:219], v[168:171], v[236:239], v[216:219]
	v_mfma_f32_16x16x32_bf16 v[220:223], v[122:125], v[236:239], v[220:223]
	s_waitcnt vmcnt(0)
	s_barrier
; DI int TID() { int t = (int)__builtin_amdgcn_workitem_id_x(); asm volatile("" : "+v"(t)); return t; }
; DI u32x4 pack8(const float (&v)[8]) { u32x4 r = {pk2(v[0], v[1]), pk2(v[2], v[3]), pk2(v[4], v[5]), pk2(v[6], v[7])}; return r; }
; DI void tile_outproj(const Params& p, int l, const Chunk& ck, int tile, int next, PF& pf, char* smem) {
;   float* Cs = (float*)smem;
;   const int tid = TID(); const int mi = tile & (MTN - 1), ni = tile >> MTS; const int m0 = mi * 128, n0 = ni * 128;
;   f32x16 acc[2][2]; zero_acc(acc);
;   { const u16* Ap; const u16* Wt; outproj_ptrs(p, l, tile, Ap, Wt); gemm_run<16>(pf, Ap, 1024, Wt, acc, smem); }
;   if (next >= 0) { const u16* An; const u16* Wn; outproj_ptrs(p, l, next, An, Wn); gemm_issue(pf, An, 1024, Wn, 1024); }
;   acc_to_cs(acc, Cs);
;   const int row = tid >> 1, half = tid & 1; float ssq = 0.f;
;   u16* xb = (u16*)(p.ws + OFF_XB) + (size_t)(m0 + row) * 1024 + n0 + half * 64;
; #pragma unroll
;   for (int c8 = 0; c8 < 8; ++c8) {
;     float v[8], x[8]; cs_ld8(Cs, row, half * 64 + c8 * 8, v); unpack8(*(const u32x4*)(xb + c8 * 8), x);
; #pragma unroll
;     for (int j = 0; j < 8; ++j) { v[j] += x[j]; ssq += v[j] * v[j]; }
;     *(u32x4*)(xb + c8 * 8) = pack8(v);
	ds_read_b128 v[224:227], v126 offset:24576
	ds_read_b128 v[240:243], v128 offset:24576
	ds_read_b128 v[244:247], v128 offset:25600
	ds_read_b128 v[248:251], v128 offset:26624
	ds_read_b128 v[156:159], v128 offset:27648
	ds_read_b128 v[228:231], v126 offset:25600
	ds_read_b128 v[232:235], v126 offset:26624
	ds_read_b128 v[236:239], v126 offset:27648
	ds_read_b128 v[160:163], v128 offset:32768
	ds_read_b128 v[164:167], v128 offset:33792
	ds_read_b128 v[168:171], v128 offset:34816
	ds_read_b128 v[122:125], v128 offset:35840
	s_waitcnt lgkmcnt(10)
	v_mfma_f32_16x16x32_bf16 v[2:5], v[240:243], v[224:227], v[2:5]
	s_waitcnt lgkmcnt(9)
	v_mfma_f32_16x16x32_bf16 v[6:9], v[244:247], v[224:227], v[6:9]
	s_waitcnt lgkmcnt(8)
	v_mfma_f32_16x16x32_bf16 v[10:13], v[248:251], v[224:227], v[10:13]
	s_waitcnt lgkmcnt(7)
	v_mfma_f32_16x16x32_bf16 v[14:17], v[156:159], v[224:227], v[14:17]
	s_waitcnt lgkmcnt(6)
	v_mfma_f32_16x16x32_bf16 v[18:21], v[240:243], v[228:231], v[18:21]
	v_mfma_f32_16x16x32_bf16 v[22:25], v[244:247], v[228:231], v[22:25]
	v_mfma_f32_16x16x32_bf16 v[26:29], v[248:251], v[228:231], v[26:29]
	v_mfma_f32_16x16x32_bf16 v[30:33], v[156:159], v[228:231], v[30:33]
	s_waitcnt lgkmcnt(5)
	v_mfma_f32_16x16x32_bf16 v[34:37], v[240:243], v[232:235], v[34:37]
	v_mfma_f32_16x16x32_bf16 v[38:41], v[244:247], v[232:235], v[38:41]
	v_mfma_f32_16x16x32_bf16 v[42:45], v[248:251], v[232:235], v[42:45]
	v_mfma_f32_16x16x32_bf16 v[46:49], v[156:159], v[232:235], v[46:49]
	s_waitcnt lgkmcnt(4)
	v_mfma_f32_16x16x32_bf16 v[50:53], v[240:243], v[236:239], v[50:53]
	v_mfma_f32_16x16x32_bf16 v[54:57], v[244:247], v[236:239], v[54:57]
	v_mfma_f32_16x16x32_bf16 v[58:61], v[248:251], v[236:239], v[58:61]
	v_mfma_f32_16x16x32_bf16 v[62:65], v[156:159], v[236:239], v[62:65]
	s_waitcnt lgkmcnt(3)
	v_mfma_f32_16x16x32_bf16 v[74:77], v[160:163], v[224:227], v[74:77]
	s_waitcnt lgkmcnt(2)
	v_mfma_f32_16x16x32_bf16 v[78:81], v[164:167], v[224:227], v[78:81]
	s_waitcnt lgkmcnt(1)
	v_mfma_f32_16x16x32_bf16 v[82:85], v[168:171], v[224:227], v[82:85]
	s_waitcnt lgkmcnt(0)
	v_mfma_f32_16x16x32_bf16 v[86:89], v[122:125], v[224:227], v[86:89]
	v_mfma_f32_16x16x32_bf16 v[90:93], v[160:163], v[228:231], v[90:93]
	v_mfma_f32_16x16x32_bf16 v[94:97], v[164:167], v[228:231], v[94:97]
	v_mfma_f32_16x16x32_bf16 v[98:101], v[168:171], v[228:231], v[98:101]
	v_mfma_f32_16x16x32_bf16 v[102:105], v[122:125], v[228:231], v[102:105]
	v_mfma_f32_16x16x32_bf16 v[106:109], v[160:163], v[232:235], v[106:109]
	v_mfma_f32_16x16x32_bf16 v[110:113], v[164:167], v[232:235], v[110:113]
	v_mfma_f32_16x16x32_bf16 v[114:117], v[168:171], v[232:235], v[114:117]
	v_mfma_f32_16x16x32_bf16 v[118:121], v[122:125], v[232:235], v[118:121]
	v_mfma_f32_16x16x32_bf16 v[208:211], v[160:163], v[236:239], v[208:211]
	v_mfma_f32_16x16x32_bf16 v[212:215], v[164:167], v[236:239], v[212:215]
	v_mfma_f32_16x16x32_bf16 v[216:219], v[168:171], v[236:239], v[216:219]
	v_mfma_f32_16x16x32_bf16 v[220:223], v[122:125], v[236:239], v[220:223]
	s_barrier
	s_and_b32 s0, s40, 0x3f80
	v_and_b32_e32 v160, 63, v172
	v_lshrrev_b32_e32 v161, 6, v172
	v_and_b32_e32 v162, 15, v160
	v_lshrrev_b32_e32 v163, 4, v160
	v_lshrrev_b32_e32 v167, 1, v161
	v_lshl_add_u32 v167, v167, 6, v162
	v_and_b32_e32 v168, 1, v161
	v_lshlrev_b32_e32 v169, 6, v168
	v_lshl_add_u32 v169, v163, 2, v169
	v_add_u32_e32 v169, s26, v169
	v_add_u32_e32 v170, s0, v167
	v_lshlrev_b32_e32 v164, 6, v170
	v_lshl_add_u32 v164, v163, 3, v164
	v_lshrrev_b32_e32 v122, 5, v169
	v_lshl_add_u32 v164, v122, 20, v164
	v_add_u32_e32 v122, 0x100000, v164
	v_lshlrev_b32_e32 v165, 12, v167
	v_lshl_add_u32 v165, v169, 2, v165
	v_lshlrev_b32_e32 v166, 6, v170
	v_lshl_add_u32 v166, v168, 2, v166
	s_lshr_b32 s0, s26, 4
	s_add_u32 s14, s22, s0
	s_addc_u32 s15, s23, 0
	global_load_dwordx2 v[224:225], v164, s[20:21] offset:0
	global_load_dwordx2 v[226:227], v164, s[20:21] offset:32
	global_load_dwordx2 v[228:229], v122, s[20:21] offset:0
	global_load_dwordx2 v[230:231], v122, s[20:21] offset:32
	global_load_dwordx2 v[232:233], v164, s[20:21] offset:1024
	global_load_dwordx2 v[234:235], v164, s[20:21] offset:1056
	global_load_dwordx2 v[236:237], v122, s[20:21] offset:1024
	global_load_dwordx2 v[238:239], v122, s[20:21] offset:1056
	global_load_dwordx2 v[240:241], v164, s[20:21] offset:2048
	global_load_dwordx2 v[242:243], v164, s[20:21] offset:2080
	global_load_dwordx2 v[244:245], v122, s[20:21] offset:2048
	global_load_dwordx2 v[246:247], v122, s[20:21] offset:2080
	global_load_dwordx2 v[248:249], v164, s[20:21] offset:3072
	global_load_dwordx2 v[250:251], v164, s[20:21] offset:3104
	global_load_dwordx2 v[156:157], v122, s[20:21] offset:3072
	global_load_dwordx2 v[158:159], v122, s[20:21] offset:3104
	s_waitcnt vmcnt(0)
; DI u32x4 pack8(const float (&v)[8]) { u32x4 r = {pk2(v[0], v[1]), pk2(v[2], v[3]), pk2(v[4], v[5]), pk2(v[6], v[7])}; return r; }
; DI void tile_outproj(const Params& p, int l, const Chunk& ck, int tile, int next, PF& pf, char* smem) {
;     ...
;   const int row = tid >> 1, half = tid & 1; float ssq = 0.f;
;   u16* xb = (u16*)(p.ws + OFF_XB) + (size_t)(m0 + row) * 1024 + n0 + half * 64;
; #pragma unroll
;   for (int c8 = 0; c8 < 8; ++c8) {
;     float v[8], x[8]; cs_ld8(Cs, row, half * 64 + c8 * 8, v); unpack8(*(const u32x4*)(xb + c8 * 8), x);
; #pragma unroll
;     for (int j = 0; j < 8; ++j) { v[j] += x[j]; ssq += v[j] * v[j]; }
;     *(u32x4*)(xb + c8 * 8) = pack8(v);
;   }
;   ((float*)(p.ws + OFF_PSMID))[(size_t)(m0 + row) * 16 + ni * 2 + half] = ssq;
	v_mov_b32_e32 v171, 0
	v_lshlrev_b32_e32 v167, 16, v224
	v_and_b32_e32 v168, 0xffff0000, v224
	v_lshlrev_b32_e32 v169, 16, v225
	v_and_b32_e32 v170, 0xffff0000, v225
	v_add_f32_e32 v2, v2, v167
	v_add_f32_e32 v3, v3, v168
	v_add_f32_e32 v4, v4, v169
	v_add_f32_e32 v5, v5, v170
	v_fma_f32 v171, v2, v2, v171
	v_fma_f32 v171, v3, v3, v171
	v_fma_f32 v171, v4, v4, v171
	v_fma_f32 v171, v5, v5, v171
	v_cvt_pk_bf16_f32 v2, v2, v3
	v_cvt_pk_bf16_f32 v3, v4, v5
	global_store_dwordx2 v164, v[2:3], s[20:21]
	v_lshlrev_b32_e32 v167, 16, v226
	v_and_b32_e32 v168, 0xffff0000, v226
	v_lshlrev_b32_e32 v169, 16, v227
	v_and_b32_e32 v170, 0xffff0000, v227
	v_add_f32_e32 v6, v6, v167
	v_add_f32_e32 v7, v7, v168
	v_add_f32_e32 v8, v8, v169
	v_add_f32_e32 v9, v9, v170
	v_fma_f32 v171, v6, v6, v171
	v_fma_f32 v171, v7, v7, v171
	v_fma_f32 v171, v8, v8, v171
	v_fma_f32 v171, v9, v9, v171
	v_cvt_pk_bf16_f32 v6, v6, v7
	v_cvt_pk_bf16_f32 v7, v8, v9
	global_store_dwordx2 v164, v[6:7], s[20:21] offset:32
	v_lshlrev_b32_e32 v167, 16, v228
	v_and_b32_e32 v168, 0xffff0000, v228
	v_lshlrev_b32_e32 v169, 16, v229
	v_and_b32_e32 v170, 0xffff0000, v229
	v_add_f32_e32 v10, v10, v167
	v_add_f32_e32 v11, v11, v168
	v_add_f32_e32 v12, v12, v169
	v_add_f32_e32 v13, v13, v170
	v_fma_f32 v171, v10, v10, v171
	v_fma_f32 v171, v11, v11, v171
	v_fma_f32 v171, v12, v12, v171
	v_fma_f32 v171, v13, v13, v171
	v_cvt_pk_bf16_f32 v10, v10, v11
	v_cvt_pk_bf16_f32 v11, v12, v13
	global_store_dwordx2 v122, v[10:11], s[20:21]
	v_lshlrev_b32_e32 v167, 16, v230
	v_and_b32_e32 v168, 0xffff0000, v230
	v_lshlrev_b32_e32 v169, 16, v231
	v_and_b32_e32 v170, 0xffff0000, v231
	v_add_f32_e32 v14, v14, v167
	v_add_f32_e32 v15, v15, v168
	v_add_f32_e32 v16, v16, v169
	v_add_f32_e32 v17, v17, v170
	v_fma_f32 v171, v14, v14, v171
	v_fma_f32 v171, v15, v15, v171
	v_fma_f32 v171, v16, v16, v171
	v_fma_f32 v171, v17, v17, v171
	v_cvt_pk_bf16_f32 v14, v14, v15
	v_cvt_pk_bf16_f32 v15, v16, v17
	global_store_dwordx2 v122, v[14:15], s[20:21] offset:32
	v_mov_b32_e32 v167, v171
	s_nop 1
	v_permlane32_swap_b32_e32 v171, v167
	v_add_f32_e32 v171, v171, v167
	ds_swizzle_b32 v167, v171 offset:0x401f
	s_waitcnt lgkmcnt(0)
	v_add_f32_e32 v171, v171, v167
	v_cmp_gt_u32_e32 vcc, 16, v160
	s_and_saveexec_b64 s[98:99], vcc
	global_store_dword v166, v171, s[14:15] offset:0
	s_or_b64 exec, exec, s[98:99]
	v_mov_b32_e32 v171, 0
	v_lshlrev_b32_e32 v167, 16, v232
	v_and_b32_e32 v168, 0xffff0000, v232
	v_lshlrev_b32_e32 v169, 16, v233
	v_and_b32_e32 v170, 0xffff0000, v233
	v_add_f32_e32 v18, v18, v167
	v_add_f32_e32 v19, v19, v168
	v_add_f32_e32 v20, v20, v169
	v_add_f32_e32 v21, v21, v170
	v_fma_f32 v171, v18, v18, v171
	v_fma_f32 v171, v19, v19, v171
	v_fma_f32 v171, v20, v20, v171
	v_fma_f32 v171, v21, v21, v171
	v_cvt_pk_bf16_f32 v18, v18, v19
	v_cvt_pk_bf16_f32 v19, v20, v21
	global_store_dwordx2 v164, v[18:19], s[20:21] offset:1024
	v_lshlrev_b32_e32 v167, 16, v234
	v_and_b32_e32 v168, 0xffff0000, v234
	v_lshlrev_b32_e32 v169, 16, v235
	v_and_b32_e32 v170, 0xffff0000, v235
	v_add_f32_e32 v22, v22, v167
	v_add_f32_e32 v23, v23, v168
	v_add_f32_e32 v24, v24, v169
	v_add_f32_e32 v25, v25, v170
	v_fma_f32 v171, v22, v22, v171
	v_fma_f32 v171, v23, v23, v171
	v_fma_f32 v171, v24, v24, v171
	v_fma_f32 v171, v25, v25, v171
	v_cvt_pk_bf16_f32 v22, v22, v23
	v_cvt_pk_bf16_f32 v23, v24, v25
	global_store_dwordx2 v164, v[22:23], s[20:21] offset:1056
	v_lshlrev_b32_e32 v167, 16, v236
	v_and_b32_e32 v168, 0xffff0000, v236
	v_lshlrev_b32_e32 v169, 16, v237
	v_and_b32_e32 v170, 0xffff0000, v237
	v_add_f32_e32 v26, v26, v167
	v_add_f32_e32 v27, v27, v168
	v_add_f32_e32 v28, v28, v169
	v_add_f32_e32 v29, v29, v170
	v_fma_f32 v171, v26, v26, v171
	v_fma_f32 v171, v27, v27, v171
	v_fma_f32 v171, v28, v28, v171
	v_fma_f32 v171, v29, v29, v171
	v_cvt_pk_bf16_f32 v26, v26, v27
	v_cvt_pk_bf16_f32 v27, v28, v29
	global_store_dwordx2 v122, v[26:27], s[20:21] offset:1024
	v_lshlrev_b32_e32 v167, 16, v238
	v_and_b32_e32 v168, 0xffff0000, v238
	v_lshlrev_b32_e32 v169, 16, v239
	v_and_b32_e32 v170, 0xffff0000, v239
	v_add_f32_e32 v30, v30, v167
	v_add_f32_e32 v31, v31, v168
	v_add_f32_e32 v32, v32, v169
	v_add_f32_e32 v33, v33, v170
	v_fma_f32 v171, v30, v30, v171
	v_fma_f32 v171, v31, v31, v171
	v_fma_f32 v171, v32, v32, v171
	v_fma_f32 v171, v33, v33, v171
	v_cvt_pk_bf16_f32 v30, v30, v31
	v_cvt_pk_bf16_f32 v31, v32, v33
	global_store_dwordx2 v122, v[30:31], s[20:21] offset:1056
	v_mov_b32_e32 v167, v171
	s_nop 1
	v_permlane32_swap_b32_e32 v171, v167
	v_add_f32_e32 v171, v171, v167
	ds_swizzle_b32 v167, v171 offset:0x401f
	s_waitcnt lgkmcnt(0)
; DI u32x4 pack8(const float (&v)[8]) { u32x4 r = {pk2(v[0], v[1]), pk2(v[2], v[3]), pk2(v[4], v[5]), pk2(v[6], v[7])}; return r; }
; DI void tile_outproj(const Params& p, int l, const Chunk& ck, int tile, int next, PF& pf, char* smem) {
;     ...
;   const int row = tid >> 1, half = tid & 1; float ssq = 0.f;
;   u16* xb = (u16*)(p.ws + OFF_XB) + (size_t)(m0 + row) * 1024 + n0 + half * 64;
; #pragma unroll
;   for (int c8 = 0; c8 < 8; ++c8) {
;     float v[8], x[8]; cs_ld8(Cs, row, half * 64 + c8 * 8, v); unpack8(*(const u32x4*)(xb + c8 * 8), x);
; #pragma unroll
;     for (int j = 0; j < 8; ++j) { v[j] += x[j]; ssq += v[j] * v[j]; }
;     *(u32x4*)(xb + c8 * 8) = pack8(v);
;   }
;   ((float*)(p.ws + OFF_PSMID))[(size_t)(m0 + row) * 16 + ni * 2 + half] = ssq;
	v_add_f32_e32 v171, v171, v167
	v_cmp_gt_u32_e32 vcc, 16, v160
	s_and_saveexec_b64 s[98:99], vcc
	global_store_dword v166, v171, s[14:15] offset:1024
	s_or_b64 exec, exec, s[98:99]
	v_mov_b32_e32 v171, 0
	v_lshlrev_b32_e32 v167, 16, v240
	v_and_b32_e32 v168, 0xffff0000, v240
	v_lshlrev_b32_e32 v169, 16, v241
	v_and_b32_e32 v170, 0xffff0000, v241
	v_add_f32_e32 v34, v34, v167
	v_add_f32_e32 v35, v35, v168
	v_add_f32_e32 v36, v36, v169
	v_add_f32_e32 v37, v37, v170
	v_fma_f32 v171, v34, v34, v171
	v_fma_f32 v171, v35, v35, v171
	v_fma_f32 v171, v36, v36, v171
	v_fma_f32 v171, v37, v37, v171
	v_cvt_pk_bf16_f32 v34, v34, v35
	v_cvt_pk_bf16_f32 v35, v36, v37
	global_store_dwordx2 v164, v[34:35], s[20:21] offset:2048
	v_lshlrev_b32_e32 v167, 16, v242
	v_and_b32_e32 v168, 0xffff0000, v242
	v_lshlrev_b32_e32 v169, 16, v243
	v_and_b32_e32 v170, 0xffff0000, v243
	v_add_f32_e32 v38, v38, v167
	v_add_f32_e32 v39, v39, v168
	v_add_f32_e32 v40, v40, v169
	v_add_f32_e32 v41, v41, v170
	v_fma_f32 v171, v38, v38, v171
	v_fma_f32 v171, v39, v39, v171
	v_fma_f32 v171, v40, v40, v171
	v_fma_f32 v171, v41, v41, v171
	v_cvt_pk_bf16_f32 v38, v38, v39
	v_cvt_pk_bf16_f32 v39, v40, v41
	global_store_dwordx2 v164, v[38:39], s[20:21] offset:2080
	v_lshlrev_b32_e32 v167, 16, v244
	v_and_b32_e32 v168, 0xffff0000, v244
	v_lshlrev_b32_e32 v169, 16, v245
	v_and_b32_e32 v170, 0xffff0000, v245
	v_add_f32_e32 v42, v42, v167
	v_add_f32_e32 v43, v43, v168
	v_add_f32_e32 v44, v44, v169
	v_add_f32_e32 v45, v45, v170
	v_fma_f32 v171, v42, v42, v171
	v_fma_f32 v171, v43, v43, v171
	v_fma_f32 v171, v44, v44, v171
	v_fma_f32 v171, v45, v45, v171
	v_cvt_pk_bf16_f32 v42, v42, v43
	v_cvt_pk_bf16_f32 v43, v44, v45
	global_store_dwordx2 v122, v[42:43], s[20:21] offset:2048
	v_lshlrev_b32_e32 v167, 16, v246
	v_and_b32_e32 v168, 0xffff0000, v246
	v_lshlrev_b32_e32 v169, 16, v247
	v_and_b32_e32 v170, 0xffff0000, v247
	v_add_f32_e32 v46, v46, v167
	v_add_f32_e32 v47, v47, v168
	v_add_f32_e32 v48, v48, v169
	v_add_f32_e32 v49, v49, v170
	v_fma_f32 v171, v46, v46, v171
	v_fma_f32 v171, v47, v47, v171
	v_fma_f32 v171, v48, v48, v171
	v_fma_f32 v171, v49, v49, v171
	v_cvt_pk_bf16_f32 v46, v46, v47
	v_cvt_pk_bf16_f32 v47, v48, v49
	global_store_dwordx2 v122, v[46:47], s[20:21] offset:2080
	v_mov_b32_e32 v167, v171
	s_nop 1
	v_permlane32_swap_b32_e32 v171, v167
	v_add_f32_e32 v171, v171, v167
	ds_swizzle_b32 v167, v171 offset:0x401f
	s_waitcnt lgkmcnt(0)
	v_add_f32_e32 v171, v171, v167
	v_cmp_gt_u32_e32 vcc, 16, v160
	s_and_saveexec_b64 s[98:99], vcc
	global_store_dword v166, v171, s[14:15] offset:2048
	s_or_b64 exec, exec, s[98:99]
	v_mov_b32_e32 v171, 0
	v_lshlrev_b32_e32 v167, 16, v248
	v_and_b32_e32 v168, 0xffff0000, v248
	v_lshlrev_b32_e32 v169, 16, v249
	v_and_b32_e32 v170, 0xffff0000, v249
	v_add_f32_e32 v50, v50, v167
	v_add_f32_e32 v51, v51, v168
	v_add_f32_e32 v52, v52, v169
	v_add_f32_e32 v53, v53, v170
	v_fma_f32 v171, v50, v50, v171
	v_fma_f32 v171, v51, v51, v171
	v_fma_f32 v171, v52, v52, v171
	v_fma_f32 v171, v53, v53, v171
	v_cvt_pk_bf16_f32 v50, v50, v51
	v_cvt_pk_bf16_f32 v51, v52, v53
	global_store_dwordx2 v164, v[50:51], s[20:21] offset:3072
	v_lshlrev_b32_e32 v167, 16, v250
	v_and_b32_e32 v168, 0xffff0000, v250
	v_lshlrev_b32_e32 v169, 16, v251
	v_and_b32_e32 v170, 0xffff0000, v251
	v_add_f32_e32 v54, v54, v167
	v_add_f32_e32 v55, v55, v168
	v_add_f32_e32 v56, v56, v169
	v_add_f32_e32 v57, v57, v170
	v_fma_f32 v171, v54, v54, v171
	v_fma_f32 v171, v55, v55, v171
	v_fma_f32 v171, v56, v56, v171
	v_fma_f32 v171, v57, v57, v171
	v_cvt_pk_bf16_f32 v54, v54, v55
	v_cvt_pk_bf16_f32 v55, v56, v57
	global_store_dwordx2 v164, v[54:55], s[20:21] offset:3104
	v_lshlrev_b32_e32 v167, 16, v156
	v_and_b32_e32 v168, 0xffff0000, v156
	v_lshlrev_b32_e32 v169, 16, v157
	v_and_b32_e32 v170, 0xffff0000, v157
	v_add_f32_e32 v58, v58, v167
	v_add_f32_e32 v59, v59, v168
	v_add_f32_e32 v60, v60, v169
	v_add_f32_e32 v61, v61, v170
	v_fma_f32 v171, v58, v58, v171
	v_fma_f32 v171, v59, v59, v171
	v_fma_f32 v171, v60, v60, v171
	v_fma_f32 v171, v61, v61, v171
	v_cvt_pk_bf16_f32 v58, v58, v59
	v_cvt_pk_bf16_f32 v59, v60, v61
	global_store_dwordx2 v122, v[58:59], s[20:21] offset:3072
	v_lshlrev_b32_e32 v167, 16, v158
	v_and_b32_e32 v168, 0xffff0000, v158
	v_lshlrev_b32_e32 v169, 16, v159
	v_and_b32_e32 v170, 0xffff0000, v159
	v_add_f32_e32 v62, v62, v167
	v_add_f32_e32 v63, v63, v168
	v_add_f32_e32 v64, v64, v169
	v_add_f32_e32 v65, v65, v170
	v_fma_f32 v171, v62, v62, v171
	v_fma_f32 v171, v63, v63, v171
	v_fma_f32 v171, v64, v64, v171
	v_fma_f32 v171, v65, v65, v171
	v_cvt_pk_bf16_f32 v62, v62, v63
	v_cvt_pk_bf16_f32 v63, v64, v65
	global_store_dwordx2 v122, v[62:63], s[20:21] offset:3104
	v_mov_b32_e32 v167, v171
	s_nop 1
	v_permlane32_swap_b32_e32 v171, v167
	v_add_f32_e32 v171, v171, v167
	ds_swizzle_b32 v167, v171 offset:0x401f
	s_waitcnt lgkmcnt(0)
	v_add_f32_e32 v171, v171, v167
	v_cmp_gt_u32_e32 vcc, 16, v160
	s_and_saveexec_b64 s[98:99], vcc
	global_store_dword v166, v171, s[14:15] offset:3072
	s_or_b64 exec, exec, s[98:99]
	v_add_u32_e32 v164, 0x400000, v164
	v_add_u32_e32 v122, 0x400000, v122
	global_load_dwordx2 v[224:225], v164, s[20:21] offset:0
	global_load_dwordx2 v[226:227], v164, s[20:21] offset:32
	global_load_dwordx2 v[228:229], v122, s[20:21] offset:0
	global_load_dwordx2 v[230:231], v122, s[20:21] offset:32
	global_load_dwordx2 v[232:233], v164, s[20:21] offset:1024
	global_load_dwordx2 v[234:235], v164, s[20:21] offset:1056
	global_load_dwordx2 v[236:237], v122, s[20:21] offset:1024
	global_load_dwordx2 v[238:239], v122, s[20:21] offset:1056
	global_load_dwordx2 v[240:241], v164, s[20:21] offset:2048
	global_load_dwordx2 v[242:243], v164, s[20:21] offset:2080
	global_load_dwordx2 v[244:245], v122, s[20:21] offset:2048
	global_load_dwordx2 v[246:247], v122, s[20:21] offset:2080
	global_load_dwordx2 v[248:249], v164, s[20:21] offset:3072
	global_load_dwordx2 v[250:251], v164, s[20:21] offset:3104
	global_load_dwordx2 v[156:157], v122, s[20:21] offset:3072
	global_load_dwordx2 v[158:159], v122, s[20:21] offset:3104
	s_waitcnt vmcnt(0)
; DI u32x4 pack8(const float (&v)[8]) { u32x4 r = {pk2(v[0], v[1]), pk2(v[2], v[3]), pk2(v[4], v[5]), pk2(v[6], v[7])}; return r; }
; DI void tile_outproj(const Params& p, int l, const Chunk& ck, int tile, int next, PF& pf, char* smem) {
;     ...
;   const int row = tid >> 1, half = tid & 1; float ssq = 0.f;
;   u16* xb = (u16*)(p.ws + OFF_XB) + (size_t)(m0 + row) * 1024 + n0 + half * 64;
; #pragma unroll
;   for (int c8 = 0; c8 < 8; ++c8) {
;     float v[8], x[8]; cs_ld8(Cs, row, half * 64 + c8 * 8, v); unpack8(*(const u32x4*)(xb + c8 * 8), x);
; #pragma unroll
;     for (int j = 0; j < 8; ++j) { v[j] += x[j]; ssq += v[j] * v[j]; }
;     *(u32x4*)(xb + c8 * 8) = pack8(v);
;   }
;   ((float*)(p.ws + OFF_PSMID))[(size_t)(m0 + row) * 16 + ni * 2 + half] = ssq;
	v_mov_b32_e32 v171, 0
	v_lshlrev_b32_e32 v167, 16, v224
	v_and_b32_e32 v168, 0xffff0000, v224
	v_lshlrev_b32_e32 v169, 16, v225
	v_and_b32_e32 v170, 0xffff0000, v225
	v_add_f32_e32 v74, v74, v167
	v_add_f32_e32 v75, v75, v168
	v_add_f32_e32 v76, v76, v169
	v_add_f32_e32 v77, v77, v170
	v_fma_f32 v171, v74, v74, v171
	v_fma_f32 v171, v75, v75, v171
	v_fma_f32 v171, v76, v76, v171
	v_fma_f32 v171, v77, v77, v171
	v_cvt_pk_bf16_f32 v74, v74, v75
	v_cvt_pk_bf16_f32 v75, v76, v77
	global_store_dwordx2 v164, v[74:75], s[20:21]
	v_lshlrev_b32_e32 v167, 16, v226
	v_and_b32_e32 v168, 0xffff0000, v226
	v_lshlrev_b32_e32 v169, 16, v227
	v_and_b32_e32 v170, 0xffff0000, v227
	v_add_f32_e32 v78, v78, v167
	v_add_f32_e32 v79, v79, v168
	v_add_f32_e32 v80, v80, v169
	v_add_f32_e32 v81, v81, v170
	v_fma_f32 v171, v78, v78, v171
	v_fma_f32 v171, v79, v79, v171
	v_fma_f32 v171, v80, v80, v171
	v_fma_f32 v171, v81, v81, v171
	v_cvt_pk_bf16_f32 v78, v78, v79
	v_cvt_pk_bf16_f32 v79, v80, v81
	global_store_dwordx2 v164, v[78:79], s[20:21] offset:32
	v_lshlrev_b32_e32 v167, 16, v228
	v_and_b32_e32 v168, 0xffff0000, v228
	v_lshlrev_b32_e32 v169, 16, v229
	v_and_b32_e32 v170, 0xffff0000, v229
	v_add_f32_e32 v82, v82, v167
	v_add_f32_e32 v83, v83, v168
	v_add_f32_e32 v84, v84, v169
	v_add_f32_e32 v85, v85, v170
	v_fma_f32 v171, v82, v82, v171
	v_fma_f32 v171, v83, v83, v171
	v_fma_f32 v171, v84, v84, v171
	v_fma_f32 v171, v85, v85, v171
	v_cvt_pk_bf16_f32 v82, v82, v83
	v_cvt_pk_bf16_f32 v83, v84, v85
	global_store_dwordx2 v122, v[82:83], s[20:21]
	v_lshlrev_b32_e32 v167, 16, v230
	v_and_b32_e32 v168, 0xffff0000, v230
	v_lshlrev_b32_e32 v169, 16, v231
	v_and_b32_e32 v170, 0xffff0000, v231
	v_add_f32_e32 v86, v86, v167
	v_add_f32_e32 v87, v87, v168
	v_add_f32_e32 v88, v88, v169
	v_add_f32_e32 v89, v89, v170
	v_fma_f32 v171, v86, v86, v171
	v_fma_f32 v171, v87, v87, v171
	v_fma_f32 v171, v88, v88, v171
	v_fma_f32 v171, v89, v89, v171
	v_cvt_pk_bf16_f32 v86, v86, v87
	v_cvt_pk_bf16_f32 v87, v88, v89
	global_store_dwordx2 v122, v[86:87], s[20:21] offset:32
	v_mov_b32_e32 v167, v171
	s_nop 1
	v_permlane32_swap_b32_e32 v171, v167
	v_add_f32_e32 v171, v171, v167
	ds_swizzle_b32 v167, v171 offset:0x401f
	s_waitcnt lgkmcnt(0)
	v_add_f32_e32 v171, v171, v167
	v_cmp_gt_u32_e32 vcc, 16, v160
	s_and_saveexec_b64 s[98:99], vcc
	global_store_dword v166, v171, s[14:15] offset:8
	s_or_b64 exec, exec, s[98:99]
	v_mov_b32_e32 v171, 0
	v_lshlrev_b32_e32 v167, 16, v232
	v_and_b32_e32 v168, 0xffff0000, v232
	v_lshlrev_b32_e32 v169, 16, v233
	v_and_b32_e32 v170, 0xffff0000, v233
	v_add_f32_e32 v90, v90, v167
	v_add_f32_e32 v91, v91, v168
	v_add_f32_e32 v92, v92, v169
	v_add_f32_e32 v93, v93, v170
	v_fma_f32 v171, v90, v90, v171
	v_fma_f32 v171, v91, v91, v171
	v_fma_f32 v171, v92, v92, v171
	v_fma_f32 v171, v93, v93, v171
	v_cvt_pk_bf16_f32 v90, v90, v91
	v_cvt_pk_bf16_f32 v91, v92, v93
	global_store_dwordx2 v164, v[90:91], s[20:21] offset:1024
	v_lshlrev_b32_e32 v167, 16, v234
	v_and_b32_e32 v168, 0xffff0000, v234
	v_lshlrev_b32_e32 v169, 16, v235
	v_and_b32_e32 v170, 0xffff0000, v235
	v_add_f32_e32 v94, v94, v167
	v_add_f32_e32 v95, v95, v168
	v_add_f32_e32 v96, v96, v169
	v_add_f32_e32 v97, v97, v170
	v_fma_f32 v171, v94, v94, v171
	v_fma_f32 v171, v95, v95, v171
	v_fma_f32 v171, v96, v96, v171
	v_fma_f32 v171, v97, v97, v171
	v_cvt_pk_bf16_f32 v94, v94, v95
	v_cvt_pk_bf16_f32 v95, v96, v97
	global_store_dwordx2 v164, v[94:95], s[20:21] offset:1056
	v_lshlrev_b32_e32 v167, 16, v236
	v_and_b32_e32 v168, 0xffff0000, v236
	v_lshlrev_b32_e32 v169, 16, v237
	v_and_b32_e32 v170, 0xffff0000, v237
	v_add_f32_e32 v98, v98, v167
	v_add_f32_e32 v99, v99, v168
	v_add_f32_e32 v100, v100, v169
	v_add_f32_e32 v101, v101, v170
	v_fma_f32 v171, v98, v98, v171
	v_fma_f32 v171, v99, v99, v171
	v_fma_f32 v171, v100, v100, v171
	v_fma_f32 v171, v101, v101, v171
	v_cvt_pk_bf16_f32 v98, v98, v99
	v_cvt_pk_bf16_f32 v99, v100, v101
	global_store_dwordx2 v122, v[98:99], s[20:21] offset:1024
	v_lshlrev_b32_e32 v167, 16, v238
	v_and_b32_e32 v168, 0xffff0000, v238
	v_lshlrev_b32_e32 v169, 16, v239
	v_and_b32_e32 v170, 0xffff0000, v239
	v_add_f32_e32 v102, v102, v167
	v_add_f32_e32 v103, v103, v168
	v_add_f32_e32 v104, v104, v169
	v_add_f32_e32 v105, v105, v170
	v_fma_f32 v171, v102, v102, v171
	v_fma_f32 v171, v103, v103, v171
	v_fma_f32 v171, v104, v104, v171
	v_fma_f32 v171, v105, v105, v171
	v_cvt_pk_bf16_f32 v102, v102, v103
	v_cvt_pk_bf16_f32 v103, v104, v105
	global_store_dwordx2 v122, v[102:103], s[20:21] offset:1056
	v_mov_b32_e32 v167, v171
	s_nop 1
	v_permlane32_swap_b32_e32 v171, v167
	v_add_f32_e32 v171, v171, v167
	ds_swizzle_b32 v167, v171 offset:0x401f
	s_waitcnt lgkmcnt(0)
; DI u32x4 pack8(const float (&v)[8]) { u32x4 r = {pk2(v[0], v[1]), pk2(v[2], v[3]), pk2(v[4], v[5]), pk2(v[6], v[7])}; return r; }
; DI void tile_outproj(const Params& p, int l, const Chunk& ck, int tile, int next, PF& pf, char* smem) {
;     ...
;   const int row = tid >> 1, half = tid & 1; float ssq = 0.f;
;   u16* xb = (u16*)(p.ws + OFF_XB) + (size_t)(m0 + row) * 1024 + n0 + half * 64;
; #pragma unroll
;   for (int c8 = 0; c8 < 8; ++c8) {
;     float v[8], x[8]; cs_ld8(Cs, row, half * 64 + c8 * 8, v); unpack8(*(const u32x4*)(xb + c8 * 8), x);
; #pragma unroll
;     for (int j = 0; j < 8; ++j) { v[j] += x[j]; ssq += v[j] * v[j]; }
;     *(u32x4*)(xb + c8 * 8) = pack8(v);
;   }
;   ((float*)(p.ws + OFF_PSMID))[(size_t)(m0 + row) * 16 + ni * 2 + half] = ssq;
	v_add_f32_e32 v171, v171, v167
	v_cmp_gt_u32_e32 vcc, 16, v160
	s_and_saveexec_b64 s[98:99], vcc
	global_store_dword v166, v171, s[14:15] offset:1032
	s_or_b64 exec, exec, s[98:99]
	v_mov_b32_e32 v171, 0
	v_lshlrev_b32_e32 v167, 16, v240
	v_and_b32_e32 v168, 0xffff0000, v240
	v_lshlrev_b32_e32 v169, 16, v241
	v_and_b32_e32 v170, 0xffff0000, v241
	v_add_f32_e32 v106, v106, v167
	v_add_f32_e32 v107, v107, v168
	v_add_f32_e32 v108, v108, v169
	v_add_f32_e32 v109, v109, v170
	v_fma_f32 v171, v106, v106, v171
	v_fma_f32 v171, v107, v107, v171
	v_fma_f32 v171, v108, v108, v171
	v_fma_f32 v171, v109, v109, v171
	v_cvt_pk_bf16_f32 v106, v106, v107
	v_cvt_pk_bf16_f32 v107, v108, v109
	global_store_dwordx2 v164, v[106:107], s[20:21] offset:2048
	v_lshlrev_b32_e32 v167, 16, v242
	v_and_b32_e32 v168, 0xffff0000, v242
	v_lshlrev_b32_e32 v169, 16, v243
	v_and_b32_e32 v170, 0xffff0000, v243
	v_add_f32_e32 v110, v110, v167
	v_add_f32_e32 v111, v111, v168
	v_add_f32_e32 v112, v112, v169
	v_add_f32_e32 v113, v113, v170
	v_fma_f32 v171, v110, v110, v171
	v_fma_f32 v171, v111, v111, v171
	v_fma_f32 v171, v112, v112, v171
	v_fma_f32 v171, v113, v113, v171
	v_cvt_pk_bf16_f32 v110, v110, v111
	v_cvt_pk_bf16_f32 v111, v112, v113
	global_store_dwordx2 v164, v[110:111], s[20:21] offset:2080
	v_lshlrev_b32_e32 v167, 16, v244
	v_and_b32_e32 v168, 0xffff0000, v244
	v_lshlrev_b32_e32 v169, 16, v245
	v_and_b32_e32 v170, 0xffff0000, v245
	v_add_f32_e32 v114, v114, v167
	v_add_f32_e32 v115, v115, v168
	v_add_f32_e32 v116, v116, v169
	v_add_f32_e32 v117, v117, v170
	v_fma_f32 v171, v114, v114, v171
	v_fma_f32 v171, v115, v115, v171
	v_fma_f32 v171, v116, v116, v171
	v_fma_f32 v171, v117, v117, v171
	v_cvt_pk_bf16_f32 v114, v114, v115
	v_cvt_pk_bf16_f32 v115, v116, v117
	global_store_dwordx2 v122, v[114:115], s[20:21] offset:2048
	v_lshlrev_b32_e32 v167, 16, v246
	v_and_b32_e32 v168, 0xffff0000, v246
	v_lshlrev_b32_e32 v169, 16, v247
	v_and_b32_e32 v170, 0xffff0000, v247
	v_add_f32_e32 v118, v118, v167
	v_add_f32_e32 v119, v119, v168
	v_add_f32_e32 v120, v120, v169
	v_add_f32_e32 v121, v121, v170
	v_fma_f32 v171, v118, v118, v171
	v_fma_f32 v171, v119, v119, v171
	v_fma_f32 v171, v120, v120, v171
	v_fma_f32 v171, v121, v121, v171
	v_cvt_pk_bf16_f32 v118, v118, v119
	v_cvt_pk_bf16_f32 v119, v120, v121
	global_store_dwordx2 v122, v[118:119], s[20:21] offset:2080
	v_mov_b32_e32 v167, v171
	s_nop 1
	v_permlane32_swap_b32_e32 v171, v167
	v_add_f32_e32 v171, v171, v167
	ds_swizzle_b32 v167, v171 offset:0x401f
	s_waitcnt lgkmcnt(0)
	v_add_f32_e32 v171, v171, v167
	v_cmp_gt_u32_e32 vcc, 16, v160
	s_and_saveexec_b64 s[98:99], vcc
	global_store_dword v166, v171, s[14:15] offset:2056
	s_or_b64 exec, exec, s[98:99]
	v_mov_b32_e32 v171, 0
	v_lshlrev_b32_e32 v167, 16, v248
	v_and_b32_e32 v168, 0xffff0000, v248
	v_lshlrev_b32_e32 v169, 16, v249
	v_and_b32_e32 v170, 0xffff0000, v249
	v_add_f32_e32 v208, v208, v167
	v_add_f32_e32 v209, v209, v168
	v_add_f32_e32 v210, v210, v169
	v_add_f32_e32 v211, v211, v170
	v_fma_f32 v171, v208, v208, v171
	v_fma_f32 v171, v209, v209, v171
	v_fma_f32 v171, v210, v210, v171
	v_fma_f32 v171, v211, v211, v171
	v_cvt_pk_bf16_f32 v208, v208, v209
	v_cvt_pk_bf16_f32 v209, v210, v211
	global_store_dwordx2 v164, v[208:209], s[20:21] offset:3072
	v_lshlrev_b32_e32 v167, 16, v250
	v_and_b32_e32 v168, 0xffff0000, v250
	v_lshlrev_b32_e32 v169, 16, v251
	v_and_b32_e32 v170, 0xffff0000, v251
	v_add_f32_e32 v212, v212, v167
	v_add_f32_e32 v213, v213, v168
	v_add_f32_e32 v214, v214, v169
	v_add_f32_e32 v215, v215, v170
	v_fma_f32 v171, v212, v212, v171
	v_fma_f32 v171, v213, v213, v171
	v_fma_f32 v171, v214, v214, v171
	v_fma_f32 v171, v215, v215, v171
	v_cvt_pk_bf16_f32 v212, v212, v213
	v_cvt_pk_bf16_f32 v213, v214, v215
	global_store_dwordx2 v164, v[212:213], s[20:21] offset:3104
	v_lshlrev_b32_e32 v167, 16, v156
	v_and_b32_e32 v168, 0xffff0000, v156
	v_lshlrev_b32_e32 v169, 16, v157
	v_and_b32_e32 v170, 0xffff0000, v157
	v_add_f32_e32 v216, v216, v167
	v_add_f32_e32 v217, v217, v168
	v_add_f32_e32 v218, v218, v169
	v_add_f32_e32 v219, v219, v170
	v_fma_f32 v171, v216, v216, v171
	v_fma_f32 v171, v217, v217, v171
	v_fma_f32 v171, v218, v218, v171
	v_fma_f32 v171, v219, v219, v171
	v_cvt_pk_bf16_f32 v216, v216, v217
	v_cvt_pk_bf16_f32 v217, v218, v219
	global_store_dwordx2 v122, v[216:217], s[20:21] offset:3072
	v_lshlrev_b32_e32 v167, 16, v158
	v_and_b32_e32 v168, 0xffff0000, v158
	v_lshlrev_b32_e32 v169, 16, v159
	v_and_b32_e32 v170, 0xffff0000, v159
	v_add_f32_e32 v220, v220, v167
	v_add_f32_e32 v221, v221, v168
	v_add_f32_e32 v222, v222, v169
	v_add_f32_e32 v223, v223, v170
	v_fma_f32 v171, v220, v220, v171
	v_fma_f32 v171, v221, v221, v171
	v_fma_f32 v171, v222, v222, v171
	v_fma_f32 v171, v223, v223, v171
	v_cvt_pk_bf16_f32 v220, v220, v221
	v_cvt_pk_bf16_f32 v221, v222, v223
	global_store_dwordx2 v122, v[220:221], s[20:21] offset:3104
	v_mov_b32_e32 v167, v171
	s_nop 1
	v_permlane32_swap_b32_e32 v171, v167
	v_add_f32_e32 v171, v171, v167
	ds_swizzle_b32 v167, v171 offset:0x401f
	s_waitcnt lgkmcnt(0)
	v_add_f32_e32 v171, v171, v167
	v_cmp_gt_u32_e32 vcc, 16, v160
	s_and_saveexec_b64 s[98:99], vcc
	global_store_dword v166, v171, s[14:15] offset:3080
	s_or_b64 exec, exec, s[98:99]
	s_branch .LBB1_254

; DI int TID() { int t = (int)__builtin_amdgcn_workitem_id_x(); asm volatile("" : "+v"(t)); return t; }
; DI RowSS rowss_load(const float* ps, int m0) { const int tid = TID(); const float* q = ps + (size_t)(m0 + (tid >> 1)) * 16 + (tid & 1) * 8; RowSS r; r.a = *(const f32x4*)q; r.b = *(const f32x4*)(q + 4); return r; }
; DI void tile_branch(const Params& p, int l, int tile, char* smem) {
;   float* Cs = (float*)smem;
;   const int tid = TID(), lane = tid & 63, w = tid >> 6, wm = w >> 1, wn = w & 1, r32 = lane & 31, hi = lane >> 5;
;   const int mi = tile & (MTN - 1), ni = tile >> MTS; const int m0 = mi * 128, n0 = ni * 128;
;   unsigned upk[2][2][8];
; #pragma unroll
;   for (int a = 0; a < 2; ++a)
; #pragma unroll
;     for (int b = 0; b < 2; ++b)
; #pragma unroll
;       for (int i = 0; i < 8; ++i) upk[a][b][i] = 0u;
;   float* rinv_s = (float*)(smem + SMEM_CS);
;   { const RowSS rss = rowss_load((const float*)(p.ws + OFF_PSIN), m0); rowss_finish(rss, rinv_s); }
; #pragma unroll 1
;   for (int br = 0; br < 3; ++br) {
;     unsigned gpk[2][2][8];
;     {
;       f32x16 accg[2][2]; zero_acc(accg);
;       gemm_main_bf<false, 16>((const u16*)(p.ws + OFF_XB) + (size_t)m0 * 1024, 1024,
;                               (const u16*)(p.ws + OFF_WIN + l * SZ_WIN) + (size_t)(5760 + br * 1024 + n0) * 1024, accg, smem, nullptr);
.LBB1_264:
	s_or_b64 exec, exec, s[26:27]
	v_and_b32_e32 v246, 63, v172
	v_lshrrev_b32_e32 v247, 6, v172
	v_bfe_u32 v166, v246, 4, 2
	v_lshrrev_b32_e32 v167, 1, v166
	v_xor_b32_e32 v166, v166, v167
	v_and_b32_e32 v166, 1, v166
	v_lshl_or_b32 v166, v166, 1, v167
	v_xor_b32_e32 v166, v166, v246
	v_and_b32_e32 v166, 3, v166
	v_lshlrev_b32_e32 v166, 4, v166
	v_lshrrev_b32_e32 v167, 2, v246
	v_lshl_add_u32 v168, v247, 5, v167
	v_lshl_add_u32 v242, v168, 11, v166
	v_add_u32_e32 v243, 0x7c00, v242
	v_lshl_add_u32 v244, v168, 10, v166
	v_add_u32_e32 v245, 0x3c00, v244
	v_lshl_add_u32 v251, v168, 6, v166
	v_readfirstlane_b32 s52, v247
	s_lshl_b32 s52, s52, 11
	s_add_u32 s53, s52, 0x2000
	v_bfe_u32 v166, v246, 2, 2
	v_lshrrev_b32_e32 v167, 1, v166
	v_xor_b32_e32 v166, v166, v167
	v_and_b32_e32 v166, 1, v166
	v_lshl_or_b32 v166, v166, 1, v167
	v_lshrrev_b32_e32 v171, 4, v246
	v_xor_b32_e32 v166, v166, v171
	v_lshlrev_b32_e32 v166, 4, v166
	v_and_b32_e32 v169, 15, v246
	v_lshl_add_u32 v170, v169, 6, v166
	v_lshrrev_b32_e32 v166, 1, v247
	v_and_b32_e32 v167, 1, v247
	v_lshl_add_u32 v240, v166, 12, v170
	v_lshl_add_u32 v241, v167, 12, v170
	v_add_u32_e32 v241, 0x2000, v241
	v_lshl_add_u32 v248, v166, 6, v169
	v_lshlrev_b32_e32 v250, 2, v248
	v_add_u32_e32 v250, 0x12000, v250
	v_lshlrev_b32_e32 v167, 6, v167
	v_lshl_add_u32 v167, v171, 2, v167
	s_and_b32 s12, s17, 0xffffff80
	v_add_u32_e32 v167, s12, v167
	v_add_u32_e32 v168, s16, v248
	v_lshlrev_b32_e32 v249, 6, v168
	v_lshl_add_u32 v249, v171, 3, v249
	v_lshrrev_b32_e32 v167, 5, v167
	v_lshl_add_u32 v249, v167, 20, v249
	s_lshl_b32 s0, s16, 6
	s_add_u32 s44, s34, s0
	s_addc_u32 s45, s35, 0
	s_lshl_b32 s0, s12, 6
	s_add_u32 s0, s0, 0xb40000
	s_add_u32 s46, s93, s0
	s_addc_u32 s47, s42, 0
	s_lshl_b32 s0, s16, 10
	s_add_u32 s48, s18, s96
	s_addc_u32 s49, s19, 0
	s_add_u32 s48, s48, s0
	s_addc_u32 s49, s49, 0
	s_add_u32 s50, s18, s97
	s_addc_u32 s51, s19, 0
	s_add_u32 s50, s50, s24
	s_addc_u32 s51, s51, s25
	s_lshl_b32 s0, s12, 6
	s_add_u32 s50, s50, s0
	s_addc_u32 s51, s51, 0
	s_mov_b64 s[28:29], s[44:45]
	s_mov_b64 s[30:31], s[46:47]
	s_add_u32 m0, s52, 0x0
	s_nop 0
	global_load_lds_dwordx4 v251, s[28:29]
	global_load_lds_dwordx4 v251, s[28:29] offset:1024
	s_add_u32 m0, s53, 0x0
	s_nop 0
	global_load_lds_dwordx4 v251, s[30:31]
	global_load_lds_dwordx4 v251, s[30:31] offset:1024
	s_add_u32 m0, s52, 0x4000
	s_add_u32 s28, s28, 0x100000
	s_addc_u32 s29, s29, 0
	global_load_lds_dwordx4 v251, s[28:29]
	global_load_lds_dwordx4 v251, s[28:29] offset:1024
	s_add_u32 m0, s53, 0x4000
	s_add_u32 s30, s30, 0x30000
	s_addc_u32 s31, s31, 0
	global_load_lds_dwordx4 v251, s[30:31]
	global_load_lds_dwordx4 v251, s[30:31] offset:1024
	s_add_u32 m0, s52, 0x8000
	s_add_u32 s28, s28, 0x100000
	s_addc_u32 s29, s29, 0
	global_load_lds_dwordx4 v251, s[28:29]
	global_load_lds_dwordx4 v251, s[28:29] offset:1024
	s_add_u32 m0, s53, 0x8000
	s_add_u32 s30, s30, 0x30000
	s_addc_u32 s31, s31, 0
	global_load_lds_dwordx4 v251, s[30:31]
	global_load_lds_dwordx4 v251, s[30:31] offset:1024
	v_mov_b32_e32 v66, 0
	v_mov_b32_e32 v67, 0
	v_mov_b32_e32 v68, 0
	v_mov_b32_e32 v69, 0
	v_mov_b32_e32 v70, 0
	v_mov_b32_e32 v71, 0
	v_mov_b32_e32 v72, 0
	v_mov_b32_e32 v73, 0
	v_mov_b32_e32 v74, 0
	v_mov_b32_e32 v75, 0
	v_mov_b32_e32 v76, 0
	v_mov_b32_e32 v77, 0
	v_mov_b32_e32 v78, 0
	v_mov_b32_e32 v79, 0
	v_mov_b32_e32 v80, 0
	v_mov_b32_e32 v81, 0
	v_mov_b32_e32 v82, 0
	v_mov_b32_e32 v83, 0
	v_mov_b32_e32 v84, 0
	v_mov_b32_e32 v85, 0
	v_mov_b32_e32 v86, 0
	v_mov_b32_e32 v87, 0
	v_mov_b32_e32 v88, 0
	v_mov_b32_e32 v89, 0
	v_mov_b32_e32 v90, 0
	v_mov_b32_e32 v91, 0
	v_mov_b32_e32 v92, 0
	v_mov_b32_e32 v93, 0
	v_mov_b32_e32 v94, 0
	v_mov_b32_e32 v95, 0
	v_mov_b32_e32 v96, 0
	v_mov_b32_e32 v97, 0
	v_mov_b32_e32 v98, 0
	v_mov_b32_e32 v99, 0
	v_mov_b32_e32 v100, 0
	v_mov_b32_e32 v101, 0
	v_mov_b32_e32 v102, 0
	v_mov_b32_e32 v103, 0
	v_mov_b32_e32 v104, 0
	v_mov_b32_e32 v105, 0
	v_mov_b32_e32 v106, 0
	v_mov_b32_e32 v107, 0
	v_mov_b32_e32 v108, 0
	v_mov_b32_e32 v109, 0
	v_mov_b32_e32 v110, 0
	v_mov_b32_e32 v111, 0
	v_mov_b32_e32 v112, 0
	v_mov_b32_e32 v113, 0
	v_mov_b32_e32 v114, 0
	v_mov_b32_e32 v115, 0
	v_mov_b32_e32 v116, 0
	v_mov_b32_e32 v117, 0
	v_mov_b32_e32 v118, 0
	v_mov_b32_e32 v119, 0
	v_mov_b32_e32 v120, 0
	v_mov_b32_e32 v121, 0
	v_mov_b32_e32 v122, 0
	v_mov_b32_e32 v123, 0
	v_mov_b32_e32 v124, 0
	v_mov_b32_e32 v125, 0
	v_mov_b32_e32 v126, 0
	v_mov_b32_e32 v127, 0
	v_mov_b32_e32 v128, 0
	v_mov_b32_e32 v129, 0
	s_mov_b32 s75, 0

; #define BLOAD(A_, B_, kt) do { _Pragma("unroll") for (int i = 0; i < 4; ++i) { \
;     A_[i] = *(const u32x4*)((const char*)Ap + (aoff + (unsigned)(32 * i * lda + (kt) * 64) * 2u)); B_[i] = *(const u32x4*)((const char*)Wt + (woff + (unsigned)(32 * i * K + (kt) * 64) * 2u)); } } while (0)
; #define BLOAD(A_, B_, kt) do { _Pragma("unroll") for (int i = 0; i < 4; ++i) { \
;     A_[i] = *(const u32x4*)((const char*)Ap + (aoff + (unsigned)(32 * i * lda + (kt) * 64) * 2u)); B_[i] = *(const u32x4*)((const char*)Wt + (woff + (unsigned)(32 * i * K + (kt) * 64) * 2u)); } } while (0)
; #define BSTORE(A_, B_, buf) do { _Pragma("unroll") for (int i = 0; i < 4; ++i) { \
;     *(u32x4*)&As[(buf) * GBUF + (srow + 32 * i) * LDT + sc8] = A_[i]; \
;     *(u32x4*)&Bs[(buf) * GBUF + (srow + 32 * i) * LDT + sc8] = B_[i]; } } while (0)
; template <bool ROWNORM, int NK>
; DI void gemm_main_bf(const u16* __restrict__ Ap, int lda, const u16* __restrict__ Wt, f32x16 (&acc)[2][2], char* smem, float* rinv_s) {
;     ...
;   __builtin_amdgcn_s_setprio(0);
;   BLOAD(a0, b0, 0); BLOAD(a1, b1, 1);
;   __syncthreads();
;   BSTORE(a0, b0, 0);
;   BLOAD(a0, b0, 2);
;   __syncthreads();
; #pragma unroll
;   for (int kt = 0; kt < nk; kt += 2) {
;     BCOMP(0);
;     BSTORE(a1, b1, 1);
;     if (kt + 3 < nk) BLOAD(a1, b1, kt + 3);
;     __syncthreads();
;     BCOMP(1);
;     if (kt + 2 < nk) { BSTORE(a0, b0, 0); if (kt + 4 < nk) BLOAD(a0, b0, kt + 4); }
;     __syncthreads();
;   }
.Lbr_gate_k:
	s_waitcnt vmcnt(8)
	s_barrier
	ds_read_b128 v[208:211], v240 offset:0
	ds_read_b128 v[224:227], v241 offset:0
	ds_read_b128 v[228:231], v241 offset:1024
	ds_read_b128 v[232:235], v241 offset:2048
	ds_read_b128 v[236:239], v241 offset:3072
	s_add_u32 m0, s52, 0xc000
	s_add_u32 s28, s28, 0x100000
	s_addc_u32 s29, s29, 0
	global_load_lds_dwordx4 v251, s[28:29]
	global_load_lds_dwordx4 v251, s[28:29] offset:1024
	s_add_u32 m0, s53, 0xc000
	s_add_u32 s30, s30, 0x30000
	s_addc_u32 s31, s31, 0
	global_load_lds_dwordx4 v251, s[30:31]
	global_load_lds_dwordx4 v251, s[30:31] offset:1024
	ds_read_b128 v[212:215], v240 offset:1024
	ds_read_b128 v[216:219], v240 offset:2048
	ds_read_b128 v[220:223], v240 offset:3072
	s_waitcnt lgkmcnt(6)
	v_mfma_f32_16x16x32_bf16 v[2:5], v[224:227], v[208:211], v[2:5]
	s_waitcnt lgkmcnt(5)
	v_mfma_f32_16x16x32_bf16 v[6:9], v[228:231], v[208:211], v[6:9]
	s_waitcnt lgkmcnt(4)
	v_mfma_f32_16x16x32_bf16 v[10:13], v[232:235], v[208:211], v[10:13]
	s_waitcnt lgkmcnt(3)
	v_mfma_f32_16x16x32_bf16 v[14:17], v[236:239], v[208:211], v[14:17]
	s_waitcnt lgkmcnt(2)
	v_mfma_f32_16x16x32_bf16 v[18:21], v[224:227], v[212:215], v[18:21]
	v_mfma_f32_16x16x32_bf16 v[22:25], v[228:231], v[212:215], v[22:25]
	v_mfma_f32_16x16x32_bf16 v[26:29], v[232:235], v[212:215], v[26:29]
	v_mfma_f32_16x16x32_bf16 v[30:33], v[236:239], v[212:215], v[30:33]
	s_waitcnt lgkmcnt(1)
	v_mfma_f32_16x16x32_bf16 v[34:37], v[224:227], v[216:219], v[34:37]
	v_mfma_f32_16x16x32_bf16 v[38:41], v[228:231], v[216:219], v[38:41]
	v_mfma_f32_16x16x32_bf16 v[42:45], v[232:235], v[216:219], v[42:45]
	v_mfma_f32_16x16x32_bf16 v[46:49], v[236:239], v[216:219], v[46:49]
	s_waitcnt lgkmcnt(0)
	v_mfma_f32_16x16x32_bf16 v[50:53], v[224:227], v[220:223], v[50:53]
	v_mfma_f32_16x16x32_bf16 v[54:57], v[228:231], v[220:223], v[54:57]
	v_mfma_f32_16x16x32_bf16 v[58:61], v[232:235], v[220:223], v[58:61]
	v_mfma_f32_16x16x32_bf16 v[62:65], v[236:239], v[220:223], v[62:65]
	s_waitcnt vmcnt(8)
	s_barrier
	ds_read_b128 v[208:211], v240 offset:16384
	ds_read_b128 v[224:227], v241 offset:16384
	ds_read_b128 v[228:231], v241 offset:17408
	ds_read_b128 v[232:235], v241 offset:18432
	ds_read_b128 v[236:239], v241 offset:19456
	s_add_u32 m0, s52, 0x0
	s_add_u32 s28, s28, 0x100000
	s_addc_u32 s29, s29, 0
	global_load_lds_dwordx4 v251, s[28:29]
	global_load_lds_dwordx4 v251, s[28:29] offset:1024
	s_add_u32 m0, s53, 0x0
	s_add_u32 s30, s30, 0x30000
	s_addc_u32 s31, s31, 0
	global_load_lds_dwordx4 v251, s[30:31]
	global_load_lds_dwordx4 v251, s[30:31] offset:1024
	ds_read_b128 v[212:215], v240 offset:17408
	ds_read_b128 v[216:219], v240 offset:18432
	ds_read_b128 v[220:223], v240 offset:19456
	s_waitcnt lgkmcnt(6)
	v_mfma_f32_16x16x32_bf16 v[2:5], v[224:227], v[208:211], v[2:5]
	s_waitcnt lgkmcnt(5)
	v_mfma_f32_16x16x32_bf16 v[6:9], v[228:231], v[208:211], v[6:9]
	s_waitcnt lgkmcnt(4)
	v_mfma_f32_16x16x32_bf16 v[10:13], v[232:235], v[208:211], v[10:13]
	s_waitcnt lgkmcnt(3)
	v_mfma_f32_16x16x32_bf16 v[14:17], v[236:239], v[208:211], v[14:17]
	s_waitcnt lgkmcnt(2)
	v_mfma_f32_16x16x32_bf16 v[18:21], v[224:227], v[212:215], v[18:21]
	v_mfma_f32_16x16x32_bf16 v[22:25], v[228:231], v[212:215], v[22:25]
	v_mfma_f32_16x16x32_bf16 v[26:29], v[232:235], v[212:215], v[26:29]
	v_mfma_f32_16x16x32_bf16 v[30:33], v[236:239], v[212:215], v[30:33]
	s_waitcnt lgkmcnt(1)
	v_mfma_f32_16x16x32_bf16 v[34:37], v[224:227], v[216:219], v[34:37]
	v_mfma_f32_16x16x32_bf16 v[38:41], v[228:231], v[216:219], v[38:41]
	v_mfma_f32_16x16x32_bf16 v[42:45], v[232:235], v[216:219], v[42:45]
	v_mfma_f32_16x16x32_bf16 v[46:49], v[236:239], v[216:219], v[46:49]
	s_waitcnt lgkmcnt(0)
	v_mfma_f32_16x16x32_bf16 v[50:53], v[224:227], v[220:223], v[50:53]
	v_mfma_f32_16x16x32_bf16 v[54:57], v[228:231], v[220:223], v[54:57]
	v_mfma_f32_16x16x32_bf16 v[58:61], v[232:235], v[220:223], v[58:61]
	v_mfma_f32_16x16x32_bf16 v[62:65], v[236:239], v[220:223], v[62:65]
	s_waitcnt vmcnt(8)
	s_barrier
	ds_read_b128 v[208:211], v240 offset:32768
	ds_read_b128 v[224:227], v241 offset:32768
	ds_read_b128 v[228:231], v241 offset:33792
	ds_read_b128 v[232:235], v241 offset:34816
	ds_read_b128 v[236:239], v241 offset:35840
	s_add_u32 m0, s52, 0x4000
	s_add_u32 s28, s28, 0x100000
	s_addc_u32 s29, s29, 0
	global_load_lds_dwordx4 v251, s[28:29]
	global_load_lds_dwordx4 v251, s[28:29] offset:1024
	s_add_u32 m0, s53, 0x4000
	s_add_u32 s30, s30, 0x30000
	s_addc_u32 s31, s31, 0
	global_load_lds_dwordx4 v251, s[30:31]
	global_load_lds_dwordx4 v251, s[30:31] offset:1024
	ds_read_b128 v[212:215], v240 offset:33792
	ds_read_b128 v[216:219], v240 offset:34816
	ds_read_b128 v[220:223], v240 offset:35840
	s_waitcnt lgkmcnt(6)
	v_mfma_f32_16x16x32_bf16 v[2:5], v[224:227], v[208:211], v[2:5]
	s_waitcnt lgkmcnt(5)
	v_mfma_f32_16x16x32_bf16 v[6:9], v[228:231], v[208:211], v[6:9]
	s_waitcnt lgkmcnt(4)
	v_mfma_f32_16x16x32_bf16 v[10:13], v[232:235], v[208:211], v[10:13]
	s_waitcnt lgkmcnt(3)
	v_mfma_f32_16x16x32_bf16 v[14:17], v[236:239], v[208:211], v[14:17]
	s_waitcnt lgkmcnt(2)
	v_mfma_f32_16x16x32_bf16 v[18:21], v[224:227], v[212:215], v[18:21]
	v_mfma_f32_16x16x32_bf16 v[22:25], v[228:231], v[212:215], v[22:25]
	v_mfma_f32_16x16x32_bf16 v[26:29], v[232:235], v[212:215], v[26:29]
	v_mfma_f32_16x16x32_bf16 v[30:33], v[236:239], v[212:215], v[30:33]
	s_waitcnt lgkmcnt(1)
	v_mfma_f32_16x16x32_bf16 v[34:37], v[224:227], v[216:219], v[34:37]
	v_mfma_f32_16x16x32_bf16 v[38:41], v[228:231], v[216:219], v[38:41]
	v_mfma_f32_16x16x32_bf16 v[42:45], v[232:235], v[216:219], v[42:45]
	v_mfma_f32_16x16x32_bf16 v[46:49], v[236:239], v[216:219], v[46:49]
	s_waitcnt lgkmcnt(0)
	v_mfma_f32_16x16x32_bf16 v[50:53], v[224:227], v[220:223], v[50:53]
	v_mfma_f32_16x16x32_bf16 v[54:57], v[228:231], v[220:223], v[54:57]
	v_mfma_f32_16x16x32_bf16 v[58:61], v[232:235], v[220:223], v[58:61]
	v_mfma_f32_16x16x32_bf16 v[62:65], v[236:239], v[220:223], v[62:65]
	s_waitcnt vmcnt(8)
	s_barrier
; #define BLOAD(A_, B_, kt) do { _Pragma("unroll") for (int i = 0; i < 4; ++i) { \
;     A_[i] = *(const u32x4*)((const char*)Ap + (aoff + (unsigned)(32 * i * lda + (kt) * 64) * 2u)); B_[i] = *(const u32x4*)((const char*)Wt + (woff + (unsigned)(32 * i * K + (kt) * 64) * 2u)); } } while (0)
; #define BLOAD(A_, B_, kt) do { _Pragma("unroll") for (int i = 0; i < 4; ++i) { \
;     A_[i] = *(const u32x4*)((const char*)Ap + (aoff + (unsigned)(32 * i * lda + (kt) * 64) * 2u)); B_[i] = *(const u32x4*)((const char*)Wt + (woff + (unsigned)(32 * i * K + (kt) * 64) * 2u)); } } while (0)
; #define BSTORE(A_, B_, buf) do { _Pragma("unroll") for (int i = 0; i < 4; ++i) { \
;     *(u32x4*)&As[(buf) * GBUF + (srow + 32 * i) * LDT + sc8] = A_[i]; \
;     *(u32x4*)&Bs[(buf) * GBUF + (srow + 32 * i) * LDT + sc8] = B_[i]; } } while (0)
; template <bool ROWNORM, int NK>
; DI void gemm_main_bf(const u16* __restrict__ Ap, int lda, const u16* __restrict__ Wt, f32x16 (&acc)[2][2], char* smem, float* rinv_s) {
;     ...
;   __builtin_amdgcn_s_setprio(0);
;   BLOAD(a0, b0, 0); BLOAD(a1, b1, 1);
;   __syncthreads();
;   BSTORE(a0, b0, 0);
;   BLOAD(a0, b0, 2);
;   __syncthreads();
; #pragma unroll
;   for (int kt = 0; kt < nk; kt += 2) {
;     BCOMP(0);
;     BSTORE(a1, b1, 1);
;     if (kt + 3 < nk) BLOAD(a1, b1, kt + 3);
;     __syncthreads();
;     BCOMP(1);
;     if (kt + 2 < nk) { BSTORE(a0, b0, 0); if (kt + 4 < nk) BLOAD(a0, b0, kt + 4); }
;     __syncthreads();
;   }
	ds_read_b128 v[208:211], v240 offset:49152
	ds_read_b128 v[224:227], v241 offset:49152
	ds_read_b128 v[228:231], v241 offset:50176
	ds_read_b128 v[232:235], v241 offset:51200
	ds_read_b128 v[236:239], v241 offset:52224
	s_add_u32 m0, s52, 0x8000
	s_add_u32 s28, s28, 0x100000
	s_addc_u32 s29, s29, 0
	global_load_lds_dwordx4 v251, s[28:29]
	global_load_lds_dwordx4 v251, s[28:29] offset:1024
	s_add_u32 m0, s53, 0x8000
	s_add_u32 s30, s30, 0x30000
	s_addc_u32 s31, s31, 0
	global_load_lds_dwordx4 v251, s[30:31]
	global_load_lds_dwordx4 v251, s[30:31] offset:1024
	ds_read_b128 v[212:215], v240 offset:50176
	ds_read_b128 v[216:219], v240 offset:51200
	ds_read_b128 v[220:223], v240 offset:52224
	s_waitcnt lgkmcnt(6)
	v_mfma_f32_16x16x32_bf16 v[2:5], v[224:227], v[208:211], v[2:5]
	s_waitcnt lgkmcnt(5)
	v_mfma_f32_16x16x32_bf16 v[6:9], v[228:231], v[208:211], v[6:9]
	s_waitcnt lgkmcnt(4)
	v_mfma_f32_16x16x32_bf16 v[10:13], v[232:235], v[208:211], v[10:13]
	s_waitcnt lgkmcnt(3)
	v_mfma_f32_16x16x32_bf16 v[14:17], v[236:239], v[208:211], v[14:17]
	s_waitcnt lgkmcnt(2)
	v_mfma_f32_16x16x32_bf16 v[18:21], v[224:227], v[212:215], v[18:21]
	v_mfma_f32_16x16x32_bf16 v[22:25], v[228:231], v[212:215], v[22:25]
	v_mfma_f32_16x16x32_bf16 v[26:29], v[232:235], v[212:215], v[26:29]
	v_mfma_f32_16x16x32_bf16 v[30:33], v[236:239], v[212:215], v[30:33]
	s_waitcnt lgkmcnt(1)
	v_mfma_f32_16x16x32_bf16 v[34:37], v[224:227], v[216:219], v[34:37]
	v_mfma_f32_16x16x32_bf16 v[38:41], v[228:231], v[216:219], v[38:41]
	v_mfma_f32_16x16x32_bf16 v[42:45], v[232:235], v[216:219], v[42:45]
	v_mfma_f32_16x16x32_bf16 v[46:49], v[236:239], v[216:219], v[46:49]
	s_waitcnt lgkmcnt(0)
	v_mfma_f32_16x16x32_bf16 v[50:53], v[224:227], v[220:223], v[50:53]
	v_mfma_f32_16x16x32_bf16 v[54:57], v[228:231], v[220:223], v[54:57]
	v_mfma_f32_16x16x32_bf16 v[58:61], v[232:235], v[220:223], v[58:61]
	v_mfma_f32_16x16x32_bf16 v[62:65], v[236:239], v[220:223], v[62:65]
	s_sub_u32 s74, s74, 1
	s_cmp_lg_u32 s74, 0
	s_cbranch_scc1 .Lbr_gate_k
	s_waitcnt vmcnt(8)
	s_barrier
	ds_read_b128 v[208:211], v240 offset:0
	ds_read_b128 v[224:227], v241 offset:0
	ds_read_b128 v[228:231], v241 offset:1024
	ds_read_b128 v[232:235], v241 offset:2048
	ds_read_b128 v[236:239], v241 offset:3072
	s_add_u32 m0, s52, 0xc000
	s_add_u32 s28, s28, 0x100000
	s_addc_u32 s29, s29, 0
	global_load_lds_dwordx4 v251, s[28:29]
	global_load_lds_dwordx4 v251, s[28:29] offset:1024
	s_add_u32 m0, s53, 0xc000
	s_add_u32 s30, s30, 0x30000
	s_addc_u32 s31, s31, 0
	global_load_lds_dwordx4 v251, s[30:31]
	global_load_lds_dwordx4 v251, s[30:31] offset:1024
	ds_read_b128 v[212:215], v240 offset:1024
	ds_read_b128 v[216:219], v240 offset:2048
	ds_read_b128 v[220:223], v240 offset:3072
	s_waitcnt lgkmcnt(6)
	v_mfma_f32_16x16x32_bf16 v[2:5], v[224:227], v[208:211], v[2:5]
	s_waitcnt lgkmcnt(5)
	v_mfma_f32_16x16x32_bf16 v[6:9], v[228:231], v[208:211], v[6:9]
	s_waitcnt lgkmcnt(4)
	v_mfma_f32_16x16x32_bf16 v[10:13], v[232:235], v[208:211], v[10:13]
	s_waitcnt lgkmcnt(3)
	v_mfma_f32_16x16x32_bf16 v[14:17], v[236:239], v[208:211], v[14:17]
	s_waitcnt lgkmcnt(2)
	v_mfma_f32_16x16x32_bf16 v[18:21], v[224:227], v[212:215], v[18:21]
	v_mfma_f32_16x16x32_bf16 v[22:25], v[228:231], v[212:215], v[22:25]
	v_mfma_f32_16x16x32_bf16 v[26:29], v[232:235], v[212:215], v[26:29]
	v_mfma_f32_16x16x32_bf16 v[30:33], v[236:239], v[212:215], v[30:33]
	s_waitcnt lgkmcnt(1)
	v_mfma_f32_16x16x32_bf16 v[34:37], v[224:227], v[216:219], v[34:37]
	v_mfma_f32_16x16x32_bf16 v[38:41], v[228:231], v[216:219], v[38:41]
	v_mfma_f32_16x16x32_bf16 v[42:45], v[232:235], v[216:219], v[42:45]
	v_mfma_f32_16x16x32_bf16 v[46:49], v[236:239], v[216:219], v[46:49]
	s_waitcnt lgkmcnt(0)
	v_mfma_f32_16x16x32_bf16 v[50:53], v[224:227], v[220:223], v[50:53]
	v_mfma_f32_16x16x32_bf16 v[54:57], v[228:231], v[220:223], v[54:57]
	v_mfma_f32_16x16x32_bf16 v[58:61], v[232:235], v[220:223], v[58:61]
	v_mfma_f32_16x16x32_bf16 v[62:65], v[236:239], v[220:223], v[62:65]
	s_waitcnt vmcnt(8)
	s_barrier
	ds_read_b128 v[208:211], v240 offset:16384
	ds_read_b128 v[224:227], v241 offset:16384
	ds_read_b128 v[228:231], v241 offset:17408
	ds_read_b128 v[232:235], v241 offset:18432
	ds_read_b128 v[236:239], v241 offset:19456
	ds_read_b128 v[212:215], v240 offset:17408
	ds_read_b128 v[216:219], v240 offset:18432
	ds_read_b128 v[220:223], v240 offset:19456
	s_waitcnt lgkmcnt(6)
	v_mfma_f32_16x16x32_bf16 v[2:5], v[224:227], v[208:211], v[2:5]
	s_waitcnt lgkmcnt(5)
	v_mfma_f32_16x16x32_bf16 v[6:9], v[228:231], v[208:211], v[6:9]
	s_waitcnt lgkmcnt(4)
	v_mfma_f32_16x16x32_bf16 v[10:13], v[232:235], v[208:211], v[10:13]
	s_waitcnt lgkmcnt(3)
	v_mfma_f32_16x16x32_bf16 v[14:17], v[236:239], v[208:211], v[14:17]
	s_waitcnt lgkmcnt(2)
	v_mfma_f32_16x16x32_bf16 v[18:21], v[224:227], v[212:215], v[18:21]
	v_mfma_f32_16x16x32_bf16 v[22:25], v[228:231], v[212:215], v[22:25]
	v_mfma_f32_16x16x32_bf16 v[26:29], v[232:235], v[212:215], v[26:29]
	v_mfma_f32_16x16x32_bf16 v[30:33], v[236:239], v[212:215], v[30:33]
	s_waitcnt lgkmcnt(1)
	v_mfma_f32_16x16x32_bf16 v[34:37], v[224:227], v[216:219], v[34:37]
	v_mfma_f32_16x16x32_bf16 v[38:41], v[228:231], v[216:219], v[38:41]
	v_mfma_f32_16x16x32_bf16 v[42:45], v[232:235], v[216:219], v[42:45]
	v_mfma_f32_16x16x32_bf16 v[46:49], v[236:239], v[216:219], v[46:49]
	s_waitcnt lgkmcnt(0)
	v_mfma_f32_16x16x32_bf16 v[50:53], v[224:227], v[220:223], v[50:53]
	v_mfma_f32_16x16x32_bf16 v[54:57], v[228:231], v[220:223], v[54:57]
	v_mfma_f32_16x16x32_bf16 v[58:61], v[232:235], v[220:223], v[58:61]
	v_mfma_f32_16x16x32_bf16 v[62:65], v[236:239], v[220:223], v[62:65]
	s_waitcnt vmcnt(4)
	s_barrier
; DI unsigned pk2(float a, float b) { f2_t v = {a, b}; bf2_t r = __builtin_convertvector(v, bf2_t); return __builtin_bit_cast(unsigned, r); }
; DI void tile_branch(const Params& p, int l, int tile, char* smem) {
;     ...
;       __syncthreads();
; #pragma unroll
;       for (int mt = 0; mt < 2; ++mt)
; #pragma unroll
;         for (int g4 = 0; g4 < 4; ++g4) {
;           const f32x4 r4 = *(const f32x4*)&rinv_s[wm * 64 + mt * 32 + 8 * g4 + 4 * hi];
; #pragma unroll
;           for (int nt = 0; nt < 2; ++nt) {
;             const float s0 = 1.f / (1.f + __expf(-accg[mt][nt][4 * g4 + 0] * r4[0])), s1 = 1.f / (1.f + __expf(-accg[mt][nt][4 * g4 + 1] * r4[1]));
;             const float s2 = 1.f / (1.f + __expf(-accg[mt][nt][4 * g4 + 2] * r4[2])), s3 = 1.f / (1.f + __expf(-accg[mt][nt][4 * g4 + 3] * r4[3]));
;             gpk[mt][nt][2 * g4] = pk2(s0, s1); gpk[mt][nt][2 * g4 + 1] = pk2(s2, s3);
;           }
;         }
;     }
;     f32x16 acc[2][2]; zero_acc(acc);
;     gemm_main_bf<false, 8>((const u16*)(p.ws + OFF_BR) + (size_t)(br * CT + m0) * 512, 512,
;                             (const u16*)(p.ws + OFF_WBR + (l * 3 + br) * SZ_WBR) + (size_t)n0 * 512, acc, smem, nullptr);
	ds_read_b128 v[208:211], v240 offset:32768
	ds_read_b128 v[224:227], v241 offset:32768
	ds_read_b128 v[228:231], v241 offset:33792
	ds_read_b128 v[232:235], v241 offset:34816
	ds_read_b128 v[236:239], v241 offset:35840
	ds_read_b128 v[212:215], v240 offset:33792
	ds_read_b128 v[216:219], v240 offset:34816
	ds_read_b128 v[220:223], v240 offset:35840
	s_waitcnt lgkmcnt(6)
	v_mfma_f32_16x16x32_bf16 v[2:5], v[224:227], v[208:211], v[2:5]
	s_waitcnt lgkmcnt(5)
	v_mfma_f32_16x16x32_bf16 v[6:9], v[228:231], v[208:211], v[6:9]
	s_waitcnt lgkmcnt(4)
	v_mfma_f32_16x16x32_bf16 v[10:13], v[232:235], v[208:211], v[10:13]
	s_waitcnt lgkmcnt(3)
	v_mfma_f32_16x16x32_bf16 v[14:17], v[236:239], v[208:211], v[14:17]
	s_waitcnt lgkmcnt(2)
	v_mfma_f32_16x16x32_bf16 v[18:21], v[224:227], v[212:215], v[18:21]
	v_mfma_f32_16x16x32_bf16 v[22:25], v[228:231], v[212:215], v[22:25]
	v_mfma_f32_16x16x32_bf16 v[26:29], v[232:235], v[212:215], v[26:29]
	v_mfma_f32_16x16x32_bf16 v[30:33], v[236:239], v[212:215], v[30:33]
	s_waitcnt lgkmcnt(1)
	v_mfma_f32_16x16x32_bf16 v[34:37], v[224:227], v[216:219], v[34:37]
	v_mfma_f32_16x16x32_bf16 v[38:41], v[228:231], v[216:219], v[38:41]
	v_mfma_f32_16x16x32_bf16 v[42:45], v[232:235], v[216:219], v[42:45]
	v_mfma_f32_16x16x32_bf16 v[46:49], v[236:239], v[216:219], v[46:49]
	s_waitcnt lgkmcnt(0)
	v_mfma_f32_16x16x32_bf16 v[50:53], v[224:227], v[220:223], v[50:53]
	v_mfma_f32_16x16x32_bf16 v[54:57], v[228:231], v[220:223], v[54:57]
	v_mfma_f32_16x16x32_bf16 v[58:61], v[232:235], v[220:223], v[58:61]
	v_mfma_f32_16x16x32_bf16 v[62:65], v[236:239], v[220:223], v[62:65]
	s_waitcnt vmcnt(0)
	s_barrier
	ds_read_b128 v[208:211], v240 offset:49152
	ds_read_b128 v[224:227], v241 offset:49152
	ds_read_b128 v[228:231], v241 offset:50176
	ds_read_b128 v[232:235], v241 offset:51200
	ds_read_b128 v[236:239], v241 offset:52224
	ds_read_b128 v[212:215], v240 offset:50176
	ds_read_b128 v[216:219], v240 offset:51200
	ds_read_b128 v[220:223], v240 offset:52224
	s_waitcnt lgkmcnt(6)
	v_mfma_f32_16x16x32_bf16 v[2:5], v[224:227], v[208:211], v[2:5]
	s_waitcnt lgkmcnt(5)
	v_mfma_f32_16x16x32_bf16 v[6:9], v[228:231], v[208:211], v[6:9]
	s_waitcnt lgkmcnt(4)
	v_mfma_f32_16x16x32_bf16 v[10:13], v[232:235], v[208:211], v[10:13]
	s_waitcnt lgkmcnt(3)
	v_mfma_f32_16x16x32_bf16 v[14:17], v[236:239], v[208:211], v[14:17]
	s_waitcnt lgkmcnt(2)
	v_mfma_f32_16x16x32_bf16 v[18:21], v[224:227], v[212:215], v[18:21]
	v_mfma_f32_16x16x32_bf16 v[22:25], v[228:231], v[212:215], v[22:25]
	v_mfma_f32_16x16x32_bf16 v[26:29], v[232:235], v[212:215], v[26:29]
	v_mfma_f32_16x16x32_bf16 v[30:33], v[236:239], v[212:215], v[30:33]
	s_waitcnt lgkmcnt(1)
	v_mfma_f32_16x16x32_bf16 v[34:37], v[224:227], v[216:219], v[34:37]
	v_mfma_f32_16x16x32_bf16 v[38:41], v[228:231], v[216:219], v[38:41]
	v_mfma_f32_16x16x32_bf16 v[42:45], v[232:235], v[216:219], v[42:45]
	v_mfma_f32_16x16x32_bf16 v[46:49], v[236:239], v[216:219], v[46:49]
	s_waitcnt lgkmcnt(0)
	v_mfma_f32_16x16x32_bf16 v[50:53], v[224:227], v[220:223], v[50:53]
	v_mfma_f32_16x16x32_bf16 v[54:57], v[228:231], v[220:223], v[54:57]
	v_mfma_f32_16x16x32_bf16 v[58:61], v[232:235], v[220:223], v[58:61]
	v_mfma_f32_16x16x32_bf16 v[62:65], v[236:239], v[220:223], v[62:65]
	s_mov_b64 s[28:29], s[48:49]
	s_mov_b64 s[30:31], s[50:51]
	s_add_u32 m0, s52, 0x0
	s_nop 0
	global_load_lds_dwordx4 v244, s[28:29]
	global_load_lds_dwordx4 v245, s[28:29] offset:1024
	s_add_u32 m0, s53, 0x0
	s_nop 0
	global_load_lds_dwordx4 v251, s[30:31]
	global_load_lds_dwordx4 v251, s[30:31] offset:1024
	s_add_u32 m0, s52, 0x4000
	s_add_u32 s28, s28, 0x40
	s_addc_u32 s29, s29, 0
	global_load_lds_dwordx4 v244, s[28:29]
	global_load_lds_dwordx4 v245, s[28:29] offset:1024
	s_add_u32 m0, s53, 0x4000
	s_add_u32 s30, s30, 0x10000
	s_addc_u32 s31, s31, 0
	global_load_lds_dwordx4 v251, s[30:31]
	global_load_lds_dwordx4 v251, s[30:31] offset:1024
	s_add_u32 m0, s52, 0x8000
	s_add_u32 s28, s28, 0x40
	s_addc_u32 s29, s29, 0
	global_load_lds_dwordx4 v244, s[28:29]
	global_load_lds_dwordx4 v245, s[28:29] offset:1024
	s_add_u32 m0, s53, 0x8000
	s_add_u32 s30, s30, 0x10000
	s_addc_u32 s31, s31, 0
	global_load_lds_dwordx4 v251, s[30:31]
	global_load_lds_dwordx4 v251, s[30:31] offset:1024
	ds_read_b32 v162, v250 offset:0
	ds_read_b32 v163, v250 offset:64
	ds_read_b32 v164, v250 offset:128
	ds_read_b32 v165, v250 offset:192
	s_waitcnt lgkmcnt(0)
; DI unsigned pk2(float a, float b) { f2_t v = {a, b}; bf2_t r = __builtin_convertvector(v, bf2_t); return __builtin_bit_cast(unsigned, r); }
; DI void tile_branch(const Params& p, int l, int tile, char* smem) {
;     ...
; #pragma unroll
;       for (int mt = 0; mt < 2; ++mt)
; #pragma unroll
;         for (int g4 = 0; g4 < 4; ++g4) {
;           const f32x4 r4 = *(const f32x4*)&rinv_s[wm * 64 + mt * 32 + 8 * g4 + 4 * hi];
; #pragma unroll
;           for (int nt = 0; nt < 2; ++nt) {
;             const float s0 = 1.f / (1.f + __expf(-accg[mt][nt][4 * g4 + 0] * r4[0])), s1 = 1.f / (1.f + __expf(-accg[mt][nt][4 * g4 + 1] * r4[1]));
;             const float s2 = 1.f / (1.f + __expf(-accg[mt][nt][4 * g4 + 2] * r4[2])), s3 = 1.f / (1.f + __expf(-accg[mt][nt][4 * g4 + 3] * r4[3]));
;             gpk[mt][nt][2 * g4] = pk2(s0, s1); gpk[mt][nt][2 * g4 + 1] = pk2(s2, s3);
;           }
;         }
	v_mul_f32_e32 v162, 0xbfb8aa3b, v162
	v_mul_f32_e32 v163, 0xbfb8aa3b, v163
	v_mul_f32_e32 v164, 0xbfb8aa3b, v164
	v_mul_f32_e32 v165, 0xbfb8aa3b, v165
	v_mul_f32_e32 v166, v162, v2
	v_mul_f32_e32 v167, v162, v3
	v_mul_f32_e32 v168, v162, v4
	v_mul_f32_e32 v169, v162, v5
	v_exp_f32_e32 v166, v166
	v_exp_f32_e32 v167, v167
	v_exp_f32_e32 v168, v168
	v_exp_f32_e32 v169, v169
	v_add_f32_e32 v166, 1.0, v166
	v_add_f32_e32 v167, 1.0, v167
	v_add_f32_e32 v168, 1.0, v168
	v_add_f32_e32 v169, 1.0, v169
	v_rcp_f32_e32 v166, v166
	v_rcp_f32_e32 v167, v167
	v_rcp_f32_e32 v168, v168
	v_rcp_f32_e32 v169, v169
	v_cvt_pk_bf16_f32 v130, v166, v167
	v_cvt_pk_bf16_f32 v131, v168, v169
	v_mul_f32_e32 v166, v162, v6
	v_mul_f32_e32 v167, v162, v7
	v_mul_f32_e32 v168, v162, v8
	v_mul_f32_e32 v169, v162, v9
	v_exp_f32_e32 v166, v166
	v_exp_f32_e32 v167, v167
	v_exp_f32_e32 v168, v168
	v_exp_f32_e32 v169, v169
	v_add_f32_e32 v166, 1.0, v166
	v_add_f32_e32 v167, 1.0, v167
	v_add_f32_e32 v168, 1.0, v168
	v_add_f32_e32 v169, 1.0, v169
	v_rcp_f32_e32 v166, v166
	v_rcp_f32_e32 v167, v167
	v_rcp_f32_e32 v168, v168
	v_rcp_f32_e32 v169, v169
	v_cvt_pk_bf16_f32 v132, v166, v167
	v_cvt_pk_bf16_f32 v133, v168, v169
	v_mul_f32_e32 v166, v162, v10
	v_mul_f32_e32 v167, v162, v11
	v_mul_f32_e32 v168, v162, v12
	v_mul_f32_e32 v169, v162, v13
	v_exp_f32_e32 v166, v166
	v_exp_f32_e32 v167, v167
	v_exp_f32_e32 v168, v168
	v_exp_f32_e32 v169, v169
	v_add_f32_e32 v166, 1.0, v166
	v_add_f32_e32 v167, 1.0, v167
	v_add_f32_e32 v168, 1.0, v168
	v_add_f32_e32 v169, 1.0, v169
	v_rcp_f32_e32 v166, v166
	v_rcp_f32_e32 v167, v167
	v_rcp_f32_e32 v168, v168
	v_rcp_f32_e32 v169, v169
	v_cvt_pk_bf16_f32 v134, v166, v167
	v_cvt_pk_bf16_f32 v135, v168, v169
	v_mul_f32_e32 v166, v162, v14
	v_mul_f32_e32 v167, v162, v15
	v_mul_f32_e32 v168, v162, v16
	v_mul_f32_e32 v169, v162, v17
	v_exp_f32_e32 v166, v166
	v_exp_f32_e32 v167, v167
	v_exp_f32_e32 v168, v168
	v_exp_f32_e32 v169, v169
	v_add_f32_e32 v166, 1.0, v166
	v_add_f32_e32 v167, 1.0, v167
	v_add_f32_e32 v168, 1.0, v168
	v_add_f32_e32 v169, 1.0, v169
	v_rcp_f32_e32 v166, v166
	v_rcp_f32_e32 v167, v167
	v_rcp_f32_e32 v168, v168
	v_rcp_f32_e32 v169, v169
	v_cvt_pk_bf16_f32 v136, v166, v167
	v_cvt_pk_bf16_f32 v137, v168, v169
	v_mul_f32_e32 v166, v163, v18
	v_mul_f32_e32 v167, v163, v19
	v_mul_f32_e32 v168, v163, v20
	v_mul_f32_e32 v169, v163, v21
	v_exp_f32_e32 v166, v166
	v_exp_f32_e32 v167, v167
	v_exp_f32_e32 v168, v168
	v_exp_f32_e32 v169, v169
	v_add_f32_e32 v166, 1.0, v166
	v_add_f32_e32 v167, 1.0, v167
	v_add_f32_e32 v168, 1.0, v168
	v_add_f32_e32 v169, 1.0, v169
	v_rcp_f32_e32 v166, v166
	v_rcp_f32_e32 v167, v167
	v_rcp_f32_e32 v168, v168
	v_rcp_f32_e32 v169, v169
	v_cvt_pk_bf16_f32 v138, v166, v167
	v_cvt_pk_bf16_f32 v139, v168, v169
	v_mul_f32_e32 v166, v163, v22
	v_mul_f32_e32 v167, v163, v23
	v_mul_f32_e32 v168, v163, v24
	v_mul_f32_e32 v169, v163, v25
	v_exp_f32_e32 v166, v166
	v_exp_f32_e32 v167, v167
	v_exp_f32_e32 v168, v168
	v_exp_f32_e32 v169, v169
	v_add_f32_e32 v166, 1.0, v166
	v_add_f32_e32 v167, 1.0, v167
	v_add_f32_e32 v168, 1.0, v168
	v_add_f32_e32 v169, 1.0, v169
	v_rcp_f32_e32 v166, v166
	v_rcp_f32_e32 v167, v167
	v_rcp_f32_e32 v168, v168
	v_rcp_f32_e32 v169, v169
	v_cvt_pk_bf16_f32 v140, v166, v167
	v_cvt_pk_bf16_f32 v141, v168, v169
	v_mul_f32_e32 v166, v163, v26
	v_mul_f32_e32 v167, v163, v27
	v_mul_f32_e32 v168, v163, v28
	v_mul_f32_e32 v169, v163, v29
	v_exp_f32_e32 v166, v166
	v_exp_f32_e32 v167, v167
	v_exp_f32_e32 v168, v168
	v_exp_f32_e32 v169, v169
	v_add_f32_e32 v166, 1.0, v166
	v_add_f32_e32 v167, 1.0, v167
	v_add_f32_e32 v168, 1.0, v168
	v_add_f32_e32 v169, 1.0, v169
	v_rcp_f32_e32 v166, v166
	v_rcp_f32_e32 v167, v167
	v_rcp_f32_e32 v168, v168
	v_rcp_f32_e32 v169, v169
	v_cvt_pk_bf16_f32 v142, v166, v167
	v_cvt_pk_bf16_f32 v143, v168, v169
	v_mul_f32_e32 v166, v163, v30
	v_mul_f32_e32 v167, v163, v31
	v_mul_f32_e32 v168, v163, v32
	v_mul_f32_e32 v169, v163, v33
	v_exp_f32_e32 v166, v166
	v_exp_f32_e32 v167, v167
	v_exp_f32_e32 v168, v168
	v_exp_f32_e32 v169, v169
	v_add_f32_e32 v166, 1.0, v166
	v_add_f32_e32 v167, 1.0, v167
	v_add_f32_e32 v168, 1.0, v168
	v_add_f32_e32 v169, 1.0, v169
	v_rcp_f32_e32 v166, v166
	v_rcp_f32_e32 v167, v167
	v_rcp_f32_e32 v168, v168
	v_rcp_f32_e32 v169, v169
	v_cvt_pk_bf16_f32 v144, v166, v167
	v_cvt_pk_bf16_f32 v145, v168, v169
	v_mul_f32_e32 v166, v164, v34
	v_mul_f32_e32 v167, v164, v35
	v_mul_f32_e32 v168, v164, v36
	v_mul_f32_e32 v169, v164, v37
	v_exp_f32_e32 v166, v166
	v_exp_f32_e32 v167, v167
	v_exp_f32_e32 v168, v168
	v_exp_f32_e32 v169, v169
	v_add_f32_e32 v166, 1.0, v166
	v_add_f32_e32 v167, 1.0, v167
	v_add_f32_e32 v168, 1.0, v168
	v_add_f32_e32 v169, 1.0, v169
	v_rcp_f32_e32 v166, v166
	v_rcp_f32_e32 v167, v167
	v_rcp_f32_e32 v168, v168
	v_rcp_f32_e32 v169, v169
	v_cvt_pk_bf16_f32 v146, v166, v167
	v_cvt_pk_bf16_f32 v147, v168, v169
	v_mul_f32_e32 v166, v164, v38
	v_mul_f32_e32 v167, v164, v39
	v_mul_f32_e32 v168, v164, v40
	v_mul_f32_e32 v169, v164, v41
	v_exp_f32_e32 v166, v166
	v_exp_f32_e32 v167, v167
	v_exp_f32_e32 v168, v168
	v_exp_f32_e32 v169, v169
	v_add_f32_e32 v166, 1.0, v166
	v_add_f32_e32 v167, 1.0, v167
	v_add_f32_e32 v168, 1.0, v168
	v_add_f32_e32 v169, 1.0, v169
	v_rcp_f32_e32 v166, v166
	v_rcp_f32_e32 v167, v167
	v_rcp_f32_e32 v168, v168
	v_rcp_f32_e32 v169, v169
	v_cvt_pk_bf16_f32 v148, v166, v167
	v_cvt_pk_bf16_f32 v149, v168, v169
	v_mul_f32_e32 v166, v164, v42
	v_mul_f32_e32 v167, v164, v43
	v_mul_f32_e32 v168, v164, v44
	v_mul_f32_e32 v169, v164, v45
	v_exp_f32_e32 v166, v166
	v_exp_f32_e32 v167, v167
	v_exp_f32_e32 v168, v168
	v_exp_f32_e32 v169, v169
; DI unsigned pk2(float a, float b) { f2_t v = {a, b}; bf2_t r = __builtin_convertvector(v, bf2_t); return __builtin_bit_cast(unsigned, r); }
; DI void tile_branch(const Params& p, int l, int tile, char* smem) {
;     ...
; #pragma unroll
;       for (int mt = 0; mt < 2; ++mt)
; #pragma unroll
;         for (int g4 = 0; g4 < 4; ++g4) {
;           const f32x4 r4 = *(const f32x4*)&rinv_s[wm * 64 + mt * 32 + 8 * g4 + 4 * hi];
; #pragma unroll
;           for (int nt = 0; nt < 2; ++nt) {
;             const float s0 = 1.f / (1.f + __expf(-accg[mt][nt][4 * g4 + 0] * r4[0])), s1 = 1.f / (1.f + __expf(-accg[mt][nt][4 * g4 + 1] * r4[1]));
;             const float s2 = 1.f / (1.f + __expf(-accg[mt][nt][4 * g4 + 2] * r4[2])), s3 = 1.f / (1.f + __expf(-accg[mt][nt][4 * g4 + 3] * r4[3]));
;             gpk[mt][nt][2 * g4] = pk2(s0, s1); gpk[mt][nt][2 * g4 + 1] = pk2(s2, s3);
;           }
;         }
;     }
;     f32x16 acc[2][2]; zero_acc(acc);
	v_add_f32_e32 v166, 1.0, v166
	v_add_f32_e32 v167, 1.0, v167
	v_add_f32_e32 v168, 1.0, v168
	v_add_f32_e32 v169, 1.0, v169
	v_rcp_f32_e32 v166, v166
	v_rcp_f32_e32 v167, v167
	v_rcp_f32_e32 v168, v168
	v_rcp_f32_e32 v169, v169
	v_cvt_pk_bf16_f32 v150, v166, v167
	v_cvt_pk_bf16_f32 v151, v168, v169
	v_mul_f32_e32 v166, v164, v46
	v_mul_f32_e32 v167, v164, v47
	v_mul_f32_e32 v168, v164, v48
	v_mul_f32_e32 v169, v164, v49
	v_exp_f32_e32 v166, v166
	v_exp_f32_e32 v167, v167
	v_exp_f32_e32 v168, v168
	v_exp_f32_e32 v169, v169
	v_add_f32_e32 v166, 1.0, v166
	v_add_f32_e32 v167, 1.0, v167
	v_add_f32_e32 v168, 1.0, v168
	v_add_f32_e32 v169, 1.0, v169
	v_rcp_f32_e32 v166, v166
	v_rcp_f32_e32 v167, v167
	v_rcp_f32_e32 v168, v168
	v_rcp_f32_e32 v169, v169
	v_cvt_pk_bf16_f32 v152, v166, v167
	v_cvt_pk_bf16_f32 v153, v168, v169
	v_mul_f32_e32 v166, v165, v50
	v_mul_f32_e32 v167, v165, v51
	v_mul_f32_e32 v168, v165, v52
	v_mul_f32_e32 v169, v165, v53
	v_exp_f32_e32 v166, v166
	v_exp_f32_e32 v167, v167
	v_exp_f32_e32 v168, v168
	v_exp_f32_e32 v169, v169
	v_add_f32_e32 v166, 1.0, v166
	v_add_f32_e32 v167, 1.0, v167
	v_add_f32_e32 v168, 1.0, v168
	v_add_f32_e32 v169, 1.0, v169
	v_rcp_f32_e32 v166, v166
	v_rcp_f32_e32 v167, v167
	v_rcp_f32_e32 v168, v168
	v_rcp_f32_e32 v169, v169
	v_cvt_pk_bf16_f32 v154, v166, v167
	v_cvt_pk_bf16_f32 v155, v168, v169
	v_mul_f32_e32 v166, v165, v54
	v_mul_f32_e32 v167, v165, v55
	v_mul_f32_e32 v168, v165, v56
	v_mul_f32_e32 v169, v165, v57
	v_exp_f32_e32 v166, v166
	v_exp_f32_e32 v167, v167
	v_exp_f32_e32 v168, v168
	v_exp_f32_e32 v169, v169
	v_add_f32_e32 v166, 1.0, v166
	v_add_f32_e32 v167, 1.0, v167
	v_add_f32_e32 v168, 1.0, v168
	v_add_f32_e32 v169, 1.0, v169
	v_rcp_f32_e32 v166, v166
	v_rcp_f32_e32 v167, v167
	v_rcp_f32_e32 v168, v168
	v_rcp_f32_e32 v169, v169
	v_cvt_pk_bf16_f32 v156, v166, v167
	v_cvt_pk_bf16_f32 v157, v168, v169
	v_mul_f32_e32 v166, v165, v58
	v_mul_f32_e32 v167, v165, v59
	v_mul_f32_e32 v168, v165, v60
	v_mul_f32_e32 v169, v165, v61
	v_exp_f32_e32 v166, v166
	v_exp_f32_e32 v167, v167
	v_exp_f32_e32 v168, v168
	v_exp_f32_e32 v169, v169
	v_add_f32_e32 v166, 1.0, v166
	v_add_f32_e32 v167, 1.0, v167
	v_add_f32_e32 v168, 1.0, v168
	v_add_f32_e32 v169, 1.0, v169
	v_rcp_f32_e32 v166, v166
	v_rcp_f32_e32 v167, v167
	v_rcp_f32_e32 v168, v168
	v_rcp_f32_e32 v169, v169
	v_cvt_pk_bf16_f32 v158, v166, v167
	v_cvt_pk_bf16_f32 v159, v168, v169
	v_mul_f32_e32 v166, v165, v62
	v_mul_f32_e32 v167, v165, v63
	v_mul_f32_e32 v168, v165, v64
	v_mul_f32_e32 v169, v165, v65
	v_exp_f32_e32 v166, v166
	v_exp_f32_e32 v167, v167
	v_exp_f32_e32 v168, v168
	v_exp_f32_e32 v169, v169
	v_add_f32_e32 v166, 1.0, v166
	v_add_f32_e32 v167, 1.0, v167
	v_add_f32_e32 v168, 1.0, v168
	v_add_f32_e32 v169, 1.0, v169
	v_rcp_f32_e32 v166, v166
	v_rcp_f32_e32 v167, v167
	v_rcp_f32_e32 v168, v168
	v_rcp_f32_e32 v169, v169
	v_cvt_pk_bf16_f32 v160, v166, v167
	v_cvt_pk_bf16_f32 v161, v168, v169
	v_mov_b32_e32 v2, 0
	v_mov_b32_e32 v3, 0
	v_mov_b32_e32 v4, 0
	v_mov_b32_e32 v5, 0
	v_mov_b32_e32 v6, 0
	v_mov_b32_e32 v7, 0
	v_mov_b32_e32 v8, 0
	v_mov_b32_e32 v9, 0
	v_mov_b32_e32 v10, 0
	v_mov_b32_e32 v11, 0
	v_mov_b32_e32 v12, 0
	v_mov_b32_e32 v13, 0
	v_mov_b32_e32 v14, 0
	v_mov_b32_e32 v15, 0
	v_mov_b32_e32 v16, 0
	v_mov_b32_e32 v17, 0
	v_mov_b32_e32 v18, 0
	v_mov_b32_e32 v19, 0
	v_mov_b32_e32 v20, 0
	v_mov_b32_e32 v21, 0
	v_mov_b32_e32 v22, 0
	v_mov_b32_e32 v23, 0
	v_mov_b32_e32 v24, 0
	v_mov_b32_e32 v25, 0
	v_mov_b32_e32 v26, 0
	v_mov_b32_e32 v27, 0
	v_mov_b32_e32 v28, 0
	v_mov_b32_e32 v29, 0
	v_mov_b32_e32 v30, 0
	v_mov_b32_e32 v31, 0
	v_mov_b32_e32 v32, 0
	v_mov_b32_e32 v33, 0
	v_mov_b32_e32 v34, 0
	v_mov_b32_e32 v35, 0
	v_mov_b32_e32 v36, 0
	v_mov_b32_e32 v37, 0
	v_mov_b32_e32 v38, 0
	v_mov_b32_e32 v39, 0
	v_mov_b32_e32 v40, 0
	v_mov_b32_e32 v41, 0
	v_mov_b32_e32 v42, 0
	v_mov_b32_e32 v43, 0
	v_mov_b32_e32 v44, 0
	v_mov_b32_e32 v45, 0
	v_mov_b32_e32 v46, 0
	v_mov_b32_e32 v47, 0
	v_mov_b32_e32 v48, 0
	v_mov_b32_e32 v49, 0
	v_mov_b32_e32 v50, 0
	v_mov_b32_e32 v51, 0
	v_mov_b32_e32 v52, 0
	v_mov_b32_e32 v53, 0
	v_mov_b32_e32 v54, 0
	v_mov_b32_e32 v55, 0
	v_mov_b32_e32 v56, 0
	v_mov_b32_e32 v57, 0
	v_mov_b32_e32 v58, 0
	v_mov_b32_e32 v59, 0
	v_mov_b32_e32 v60, 0
	v_mov_b32_e32 v61, 0
	v_mov_b32_e32 v62, 0
	v_mov_b32_e32 v63, 0
	v_mov_b32_e32 v64, 0
	v_mov_b32_e32 v65, 0
	s_mov_b32 s74, 3
; #define BLOAD(A_, B_, kt) do { _Pragma("unroll") for (int i = 0; i < 4; ++i) { \
;     A_[i] = *(const u32x4*)((const char*)Ap + (aoff + (unsigned)(32 * i * lda + (kt) * 64) * 2u)); B_[i] = *(const u32x4*)((const char*)Wt + (woff + (unsigned)(32 * i * K + (kt) * 64) * 2u)); } } while (0)
; #define BLOAD(A_, B_, kt) do { _Pragma("unroll") for (int i = 0; i < 4; ++i) { \
;     A_[i] = *(const u32x4*)((const char*)Ap + (aoff + (unsigned)(32 * i * lda + (kt) * 64) * 2u)); B_[i] = *(const u32x4*)((const char*)Wt + (woff + (unsigned)(32 * i * K + (kt) * 64) * 2u)); } } while (0)
; #define BSTORE(A_, B_, buf) do { _Pragma("unroll") for (int i = 0; i < 4; ++i) { \
;     *(u32x4*)&As[(buf) * GBUF + (srow + 32 * i) * LDT + sc8] = A_[i]; \
;     *(u32x4*)&Bs[(buf) * GBUF + (srow + 32 * i) * LDT + sc8] = B_[i]; } } while (0)
; template <bool ROWNORM, int NK>
; DI void gemm_main_bf(const u16* __restrict__ Ap, int lda, const u16* __restrict__ Wt, f32x16 (&acc)[2][2], char* smem, float* rinv_s) {
;     ...
;   __builtin_amdgcn_s_setprio(0);
;   BLOAD(a0, b0, 0); BLOAD(a1, b1, 1);
;   __syncthreads();
;   BSTORE(a0, b0, 0);
;   BLOAD(a0, b0, 2);
;   __syncthreads();
; #pragma unroll
;   for (int kt = 0; kt < nk; kt += 2) {
;     BCOMP(0);
;     BSTORE(a1, b1, 1);
;     if (kt + 3 < nk) BLOAD(a1, b1, kt + 3);
;     __syncthreads();
;     BCOMP(1);
;     if (kt + 2 < nk) { BSTORE(a0, b0, 0); if (kt + 4 < nk) BLOAD(a0, b0, kt + 4); }
;     __syncthreads();
;   }
; DI void tile_branch(const Params& p, int l, int tile, char* smem) {
;     ...
;     gemm_main_bf<false, 8>((const u16*)(p.ws + OFF_BR) + (size_t)(br * CT + m0) * 512, 512,
;                             (const u16*)(p.ws + OFF_WBR + (l * 3 + br) * SZ_WBR) + (size_t)n0 * 512, acc, smem, nullptr);
.Lbr_proj_k:
	s_waitcnt vmcnt(8)
	s_barrier
	ds_read_b128 v[208:211], v240 offset:0
	ds_read_b128 v[224:227], v241 offset:0
	ds_read_b128 v[228:231], v241 offset:1024
	ds_read_b128 v[232:235], v241 offset:2048
	ds_read_b128 v[236:239], v241 offset:3072
	s_add_u32 m0, s52, 0xc000
	s_add_u32 s28, s28, 0x40
	s_addc_u32 s29, s29, 0
	global_load_lds_dwordx4 v244, s[28:29]
	global_load_lds_dwordx4 v245, s[28:29] offset:1024
	s_add_u32 m0, s53, 0xc000
	s_add_u32 s30, s30, 0x10000
	s_addc_u32 s31, s31, 0
	global_load_lds_dwordx4 v251, s[30:31]
	global_load_lds_dwordx4 v251, s[30:31] offset:1024
	ds_read_b128 v[212:215], v240 offset:1024
	ds_read_b128 v[216:219], v240 offset:2048
	ds_read_b128 v[220:223], v240 offset:3072
	s_waitcnt lgkmcnt(6)
	v_mfma_f32_16x16x32_bf16 v[2:5], v[224:227], v[208:211], v[2:5]
	s_waitcnt lgkmcnt(5)
	v_mfma_f32_16x16x32_bf16 v[6:9], v[228:231], v[208:211], v[6:9]
	s_waitcnt lgkmcnt(4)
	v_mfma_f32_16x16x32_bf16 v[10:13], v[232:235], v[208:211], v[10:13]
	s_waitcnt lgkmcnt(3)
	v_mfma_f32_16x16x32_bf16 v[14:17], v[236:239], v[208:211], v[14:17]
	s_waitcnt lgkmcnt(2)
	v_mfma_f32_16x16x32_bf16 v[18:21], v[224:227], v[212:215], v[18:21]
	v_mfma_f32_16x16x32_bf16 v[22:25], v[228:231], v[212:215], v[22:25]
	v_mfma_f32_16x16x32_bf16 v[26:29], v[232:235], v[212:215], v[26:29]
	v_mfma_f32_16x16x32_bf16 v[30:33], v[236:239], v[212:215], v[30:33]
	s_waitcnt lgkmcnt(1)
	v_mfma_f32_16x16x32_bf16 v[34:37], v[224:227], v[216:219], v[34:37]
	v_mfma_f32_16x16x32_bf16 v[38:41], v[228:231], v[216:219], v[38:41]
	v_mfma_f32_16x16x32_bf16 v[42:45], v[232:235], v[216:219], v[42:45]
	v_mfma_f32_16x16x32_bf16 v[46:49], v[236:239], v[216:219], v[46:49]
	s_waitcnt lgkmcnt(0)
	v_mfma_f32_16x16x32_bf16 v[50:53], v[224:227], v[220:223], v[50:53]
	v_mfma_f32_16x16x32_bf16 v[54:57], v[228:231], v[220:223], v[54:57]
	v_mfma_f32_16x16x32_bf16 v[58:61], v[232:235], v[220:223], v[58:61]
	v_mfma_f32_16x16x32_bf16 v[62:65], v[236:239], v[220:223], v[62:65]
	s_waitcnt vmcnt(8)
	s_barrier
	ds_read_b128 v[208:211], v240 offset:16384
	ds_read_b128 v[224:227], v241 offset:16384
	ds_read_b128 v[228:231], v241 offset:17408
	ds_read_b128 v[232:235], v241 offset:18432
	ds_read_b128 v[236:239], v241 offset:19456
	s_add_u32 m0, s52, 0x0
	s_add_u32 s28, s28, 0x40
	s_addc_u32 s29, s29, 0
	global_load_lds_dwordx4 v244, s[28:29]
	global_load_lds_dwordx4 v245, s[28:29] offset:1024
	s_add_u32 m0, s53, 0x0
	s_add_u32 s30, s30, 0x10000
	s_addc_u32 s31, s31, 0
	global_load_lds_dwordx4 v251, s[30:31]
	global_load_lds_dwordx4 v251, s[30:31] offset:1024
	ds_read_b128 v[212:215], v240 offset:17408
	ds_read_b128 v[216:219], v240 offset:18432
	ds_read_b128 v[220:223], v240 offset:19456
	s_waitcnt lgkmcnt(6)
	v_mfma_f32_16x16x32_bf16 v[2:5], v[224:227], v[208:211], v[2:5]
	s_waitcnt lgkmcnt(5)
	v_mfma_f32_16x16x32_bf16 v[6:9], v[228:231], v[208:211], v[6:9]
	s_waitcnt lgkmcnt(4)
	v_mfma_f32_16x16x32_bf16 v[10:13], v[232:235], v[208:211], v[10:13]
	s_waitcnt lgkmcnt(3)
	v_mfma_f32_16x16x32_bf16 v[14:17], v[236:239], v[208:211], v[14:17]
	s_waitcnt lgkmcnt(2)
	v_mfma_f32_16x16x32_bf16 v[18:21], v[224:227], v[212:215], v[18:21]
	v_mfma_f32_16x16x32_bf16 v[22:25], v[228:231], v[212:215], v[22:25]
	v_mfma_f32_16x16x32_bf16 v[26:29], v[232:235], v[212:215], v[26:29]
	v_mfma_f32_16x16x32_bf16 v[30:33], v[236:239], v[212:215], v[30:33]
	s_waitcnt lgkmcnt(1)
	v_mfma_f32_16x16x32_bf16 v[34:37], v[224:227], v[216:219], v[34:37]
	v_mfma_f32_16x16x32_bf16 v[38:41], v[228:231], v[216:219], v[38:41]
	v_mfma_f32_16x16x32_bf16 v[42:45], v[232:235], v[216:219], v[42:45]
	v_mfma_f32_16x16x32_bf16 v[46:49], v[236:239], v[216:219], v[46:49]
	s_waitcnt lgkmcnt(0)
	v_mfma_f32_16x16x32_bf16 v[50:53], v[224:227], v[220:223], v[50:53]
	v_mfma_f32_16x16x32_bf16 v[54:57], v[228:231], v[220:223], v[54:57]
	v_mfma_f32_16x16x32_bf16 v[58:61], v[232:235], v[220:223], v[58:61]
	v_mfma_f32_16x16x32_bf16 v[62:65], v[236:239], v[220:223], v[62:65]
	s_waitcnt vmcnt(8)
	s_barrier
	ds_read_b128 v[208:211], v240 offset:32768
	ds_read_b128 v[224:227], v241 offset:32768
	ds_read_b128 v[228:231], v241 offset:33792
	ds_read_b128 v[232:235], v241 offset:34816
	ds_read_b128 v[236:239], v241 offset:35840
	s_add_u32 m0, s52, 0x4000
	s_add_u32 s28, s28, 0x40
	s_addc_u32 s29, s29, 0
	global_load_lds_dwordx4 v244, s[28:29]
	global_load_lds_dwordx4 v245, s[28:29] offset:1024
	s_add_u32 m0, s53, 0x4000
	s_add_u32 s30, s30, 0x10000
	s_addc_u32 s31, s31, 0
	global_load_lds_dwordx4 v251, s[30:31]
	global_load_lds_dwordx4 v251, s[30:31] offset:1024
	ds_read_b128 v[212:215], v240 offset:33792
	ds_read_b128 v[216:219], v240 offset:34816
	ds_read_b128 v[220:223], v240 offset:35840
	s_waitcnt lgkmcnt(6)
	v_mfma_f32_16x16x32_bf16 v[2:5], v[224:227], v[208:211], v[2:5]
	s_waitcnt lgkmcnt(5)
	v_mfma_f32_16x16x32_bf16 v[6:9], v[228:231], v[208:211], v[6:9]
	s_waitcnt lgkmcnt(4)
	v_mfma_f32_16x16x32_bf16 v[10:13], v[232:235], v[208:211], v[10:13]
	s_waitcnt lgkmcnt(3)
	v_mfma_f32_16x16x32_bf16 v[14:17], v[236:239], v[208:211], v[14:17]
	s_waitcnt lgkmcnt(2)
	v_mfma_f32_16x16x32_bf16 v[18:21], v[224:227], v[212:215], v[18:21]
	v_mfma_f32_16x16x32_bf16 v[22:25], v[228:231], v[212:215], v[22:25]
	v_mfma_f32_16x16x32_bf16 v[26:29], v[232:235], v[212:215], v[26:29]
	v_mfma_f32_16x16x32_bf16 v[30:33], v[236:239], v[212:215], v[30:33]
	s_waitcnt lgkmcnt(1)
	v_mfma_f32_16x16x32_bf16 v[34:37], v[224:227], v[216:219], v[34:37]
	v_mfma_f32_16x16x32_bf16 v[38:41], v[228:231], v[216:219], v[38:41]
	v_mfma_f32_16x16x32_bf16 v[42:45], v[232:235], v[216:219], v[42:45]
	v_mfma_f32_16x16x32_bf16 v[46:49], v[236:239], v[216:219], v[46:49]
	s_waitcnt lgkmcnt(0)
	v_mfma_f32_16x16x32_bf16 v[50:53], v[224:227], v[220:223], v[50:53]
	v_mfma_f32_16x16x32_bf16 v[54:57], v[228:231], v[220:223], v[54:57]
	v_mfma_f32_16x16x32_bf16 v[58:61], v[232:235], v[220:223], v[58:61]
	v_mfma_f32_16x16x32_bf16 v[62:65], v[236:239], v[220:223], v[62:65]
	s_waitcnt vmcnt(8)
	s_barrier
; #define BLOAD(A_, B_, kt) do { _Pragma("unroll") for (int i = 0; i < 4; ++i) { \
;     A_[i] = *(const u32x4*)((const char*)Ap + (aoff + (unsigned)(32 * i * lda + (kt) * 64) * 2u)); B_[i] = *(const u32x4*)((const char*)Wt + (woff + (unsigned)(32 * i * K + (kt) * 64) * 2u)); } } while (0)
; #define BLOAD(A_, B_, kt) do { _Pragma("unroll") for (int i = 0; i < 4; ++i) { \
;     A_[i] = *(const u32x4*)((const char*)Ap + (aoff + (unsigned)(32 * i * lda + (kt) * 64) * 2u)); B_[i] = *(const u32x4*)((const char*)Wt + (woff + (unsigned)(32 * i * K + (kt) * 64) * 2u)); } } while (0)
; #define BSTORE(A_, B_, buf) do { _Pragma("unroll") for (int i = 0; i < 4; ++i) { \
;     *(u32x4*)&As[(buf) * GBUF + (srow + 32 * i) * LDT + sc8] = A_[i]; \
;     *(u32x4*)&Bs[(buf) * GBUF + (srow + 32 * i) * LDT + sc8] = B_[i]; } } while (0)
; template <bool ROWNORM, int NK>
; DI void gemm_main_bf(const u16* __restrict__ Ap, int lda, const u16* __restrict__ Wt, f32x16 (&acc)[2][2], char* smem, float* rinv_s) {
;     ...
;   __builtin_amdgcn_s_setprio(0);
;   BLOAD(a0, b0, 0); BLOAD(a1, b1, 1);
;   __syncthreads();
;   BSTORE(a0, b0, 0);
;   BLOAD(a0, b0, 2);
;   __syncthreads();
; #pragma unroll
;   for (int kt = 0; kt < nk; kt += 2) {
;     BCOMP(0);
;     BSTORE(a1, b1, 1);
;     if (kt + 3 < nk) BLOAD(a1, b1, kt + 3);
;     __syncthreads();
;     BCOMP(1);
;     if (kt + 2 < nk) { BSTORE(a0, b0, 0); if (kt + 4 < nk) BLOAD(a0, b0, kt + 4); }
;     __syncthreads();
;   }
	ds_read_b128 v[208:211], v240 offset:49152
	ds_read_b128 v[224:227], v241 offset:49152
	ds_read_b128 v[228:231], v241 offset:50176
	ds_read_b128 v[232:235], v241 offset:51200
	ds_read_b128 v[236:239], v241 offset:52224
	s_add_u32 m0, s52, 0x8000
	s_add_u32 s28, s28, 0x40
	s_addc_u32 s29, s29, 0
	global_load_lds_dwordx4 v244, s[28:29]
	global_load_lds_dwordx4 v245, s[28:29] offset:1024
	s_add_u32 m0, s53, 0x8000
	s_add_u32 s30, s30, 0x10000
	s_addc_u32 s31, s31, 0
	global_load_lds_dwordx4 v251, s[30:31]
	global_load_lds_dwordx4 v251, s[30:31] offset:1024
	ds_read_b128 v[212:215], v240 offset:50176
	ds_read_b128 v[216:219], v240 offset:51200
	ds_read_b128 v[220:223], v240 offset:52224
	s_waitcnt lgkmcnt(6)
	v_mfma_f32_16x16x32_bf16 v[2:5], v[224:227], v[208:211], v[2:5]
	s_waitcnt lgkmcnt(5)
	v_mfma_f32_16x16x32_bf16 v[6:9], v[228:231], v[208:211], v[6:9]
	s_waitcnt lgkmcnt(4)
	v_mfma_f32_16x16x32_bf16 v[10:13], v[232:235], v[208:211], v[10:13]
	s_waitcnt lgkmcnt(3)
	v_mfma_f32_16x16x32_bf16 v[14:17], v[236:239], v[208:211], v[14:17]
	s_waitcnt lgkmcnt(2)
	v_mfma_f32_16x16x32_bf16 v[18:21], v[224:227], v[212:215], v[18:21]
	v_mfma_f32_16x16x32_bf16 v[22:25], v[228:231], v[212:215], v[22:25]
	v_mfma_f32_16x16x32_bf16 v[26:29], v[232:235], v[212:215], v[26:29]
	v_mfma_f32_16x16x32_bf16 v[30:33], v[236:239], v[212:215], v[30:33]
	s_waitcnt lgkmcnt(1)
	v_mfma_f32_16x16x32_bf16 v[34:37], v[224:227], v[216:219], v[34:37]
	v_mfma_f32_16x16x32_bf16 v[38:41], v[228:231], v[216:219], v[38:41]
	v_mfma_f32_16x16x32_bf16 v[42:45], v[232:235], v[216:219], v[42:45]
	v_mfma_f32_16x16x32_bf16 v[46:49], v[236:239], v[216:219], v[46:49]
	s_waitcnt lgkmcnt(0)
	v_mfma_f32_16x16x32_bf16 v[50:53], v[224:227], v[220:223], v[50:53]
	v_mfma_f32_16x16x32_bf16 v[54:57], v[228:231], v[220:223], v[54:57]
	v_mfma_f32_16x16x32_bf16 v[58:61], v[232:235], v[220:223], v[58:61]
	v_mfma_f32_16x16x32_bf16 v[62:65], v[236:239], v[220:223], v[62:65]
	s_sub_u32 s74, s74, 1
	s_cmp_lg_u32 s74, 0
	s_cbranch_scc1 .Lbr_proj_k
	s_waitcnt vmcnt(8)
	s_barrier
	ds_read_b128 v[208:211], v240 offset:0
	ds_read_b128 v[224:227], v241 offset:0
	ds_read_b128 v[228:231], v241 offset:1024
	ds_read_b128 v[232:235], v241 offset:2048
	ds_read_b128 v[236:239], v241 offset:3072
	s_add_u32 m0, s52, 0xc000
	s_add_u32 s28, s28, 0x40
	s_addc_u32 s29, s29, 0
	global_load_lds_dwordx4 v244, s[28:29]
	global_load_lds_dwordx4 v245, s[28:29] offset:1024
	s_add_u32 m0, s53, 0xc000
	s_add_u32 s30, s30, 0x10000
	s_addc_u32 s31, s31, 0
	global_load_lds_dwordx4 v251, s[30:31]
	global_load_lds_dwordx4 v251, s[30:31] offset:1024
	ds_read_b128 v[212:215], v240 offset:1024
	ds_read_b128 v[216:219], v240 offset:2048
	ds_read_b128 v[220:223], v240 offset:3072
	s_waitcnt lgkmcnt(6)
	v_mfma_f32_16x16x32_bf16 v[2:5], v[224:227], v[208:211], v[2:5]
	s_waitcnt lgkmcnt(5)
	v_mfma_f32_16x16x32_bf16 v[6:9], v[228:231], v[208:211], v[6:9]
	s_waitcnt lgkmcnt(4)
	v_mfma_f32_16x16x32_bf16 v[10:13], v[232:235], v[208:211], v[10:13]
	s_waitcnt lgkmcnt(3)
	v_mfma_f32_16x16x32_bf16 v[14:17], v[236:239], v[208:211], v[14:17]
	s_waitcnt lgkmcnt(2)
	v_mfma_f32_16x16x32_bf16 v[18:21], v[224:227], v[212:215], v[18:21]
	v_mfma_f32_16x16x32_bf16 v[22:25], v[228:231], v[212:215], v[22:25]
	v_mfma_f32_16x16x32_bf16 v[26:29], v[232:235], v[212:215], v[26:29]
	v_mfma_f32_16x16x32_bf16 v[30:33], v[236:239], v[212:215], v[30:33]
	s_waitcnt lgkmcnt(1)
	v_mfma_f32_16x16x32_bf16 v[34:37], v[224:227], v[216:219], v[34:37]
	v_mfma_f32_16x16x32_bf16 v[38:41], v[228:231], v[216:219], v[38:41]
	v_mfma_f32_16x16x32_bf16 v[42:45], v[232:235], v[216:219], v[42:45]
	v_mfma_f32_16x16x32_bf16 v[46:49], v[236:239], v[216:219], v[46:49]
	s_waitcnt lgkmcnt(0)
	v_mfma_f32_16x16x32_bf16 v[50:53], v[224:227], v[220:223], v[50:53]
	v_mfma_f32_16x16x32_bf16 v[54:57], v[228:231], v[220:223], v[54:57]
	v_mfma_f32_16x16x32_bf16 v[58:61], v[232:235], v[220:223], v[58:61]
	v_mfma_f32_16x16x32_bf16 v[62:65], v[236:239], v[220:223], v[62:65]
	s_waitcnt vmcnt(8)
	s_barrier
	ds_read_b128 v[208:211], v240 offset:16384
	ds_read_b128 v[224:227], v241 offset:16384
	ds_read_b128 v[228:231], v241 offset:17408
	ds_read_b128 v[232:235], v241 offset:18432
	ds_read_b128 v[236:239], v241 offset:19456
	ds_read_b128 v[212:215], v240 offset:17408
	ds_read_b128 v[216:219], v240 offset:18432
	ds_read_b128 v[220:223], v240 offset:19456
	s_waitcnt lgkmcnt(6)
	v_mfma_f32_16x16x32_bf16 v[2:5], v[224:227], v[208:211], v[2:5]
	s_waitcnt lgkmcnt(5)
	v_mfma_f32_16x16x32_bf16 v[6:9], v[228:231], v[208:211], v[6:9]
	s_waitcnt lgkmcnt(4)
	v_mfma_f32_16x16x32_bf16 v[10:13], v[232:235], v[208:211], v[10:13]
	s_waitcnt lgkmcnt(3)
	v_mfma_f32_16x16x32_bf16 v[14:17], v[236:239], v[208:211], v[14:17]
	s_waitcnt lgkmcnt(2)
	v_mfma_f32_16x16x32_bf16 v[18:21], v[224:227], v[212:215], v[18:21]
	v_mfma_f32_16x16x32_bf16 v[22:25], v[228:231], v[212:215], v[22:25]
	v_mfma_f32_16x16x32_bf16 v[26:29], v[232:235], v[212:215], v[26:29]
	v_mfma_f32_16x16x32_bf16 v[30:33], v[236:239], v[212:215], v[30:33]
	s_waitcnt lgkmcnt(1)
	v_mfma_f32_16x16x32_bf16 v[34:37], v[224:227], v[216:219], v[34:37]
	v_mfma_f32_16x16x32_bf16 v[38:41], v[228:231], v[216:219], v[38:41]
	v_mfma_f32_16x16x32_bf16 v[42:45], v[232:235], v[216:219], v[42:45]
	v_mfma_f32_16x16x32_bf16 v[46:49], v[236:239], v[216:219], v[46:49]
	s_waitcnt lgkmcnt(0)
	v_mfma_f32_16x16x32_bf16 v[50:53], v[224:227], v[220:223], v[50:53]
	v_mfma_f32_16x16x32_bf16 v[54:57], v[228:231], v[220:223], v[54:57]
	v_mfma_f32_16x16x32_bf16 v[58:61], v[232:235], v[220:223], v[58:61]
	v_mfma_f32_16x16x32_bf16 v[62:65], v[236:239], v[220:223], v[62:65]
	s_waitcnt vmcnt(4)
	s_barrier
; DI void tile_branch(const Params& p, int l, int tile, char* smem) {
;     ...
;   for (int br = 0; br < 3; ++br) {
;     unsigned gpk[2][2][8];
;     {
;       f32x16 accg[2][2]; zero_acc(accg);
;       gemm_main_bf<false, 16>((const u16*)(p.ws + OFF_XB) + (size_t)m0 * 1024, 1024,
;                               (const u16*)(p.ws + OFF_WIN + l * SZ_WIN) + (size_t)(5760 + br * 1024 + n0) * 1024, accg, smem, nullptr);
;     ...
;     gemm_main_bf<false, 8>((const u16*)(p.ws + OFF_BR) + (size_t)(br * CT + m0) * 512, 512,
	ds_read_b128 v[208:211], v240 offset:32768
	ds_read_b128 v[224:227], v241 offset:32768
	ds_read_b128 v[228:231], v241 offset:33792
	ds_read_b128 v[232:235], v241 offset:34816
	ds_read_b128 v[236:239], v241 offset:35840
	ds_read_b128 v[212:215], v240 offset:33792
	ds_read_b128 v[216:219], v240 offset:34816
	ds_read_b128 v[220:223], v240 offset:35840
	s_waitcnt lgkmcnt(6)
	v_mfma_f32_16x16x32_bf16 v[2:5], v[224:227], v[208:211], v[2:5]
	s_waitcnt lgkmcnt(5)
	v_mfma_f32_16x16x32_bf16 v[6:9], v[228:231], v[208:211], v[6:9]
	s_waitcnt lgkmcnt(4)
	v_mfma_f32_16x16x32_bf16 v[10:13], v[232:235], v[208:211], v[10:13]
	s_waitcnt lgkmcnt(3)
	v_mfma_f32_16x16x32_bf16 v[14:17], v[236:239], v[208:211], v[14:17]
	s_waitcnt lgkmcnt(2)
	v_mfma_f32_16x16x32_bf16 v[18:21], v[224:227], v[212:215], v[18:21]
	v_mfma_f32_16x16x32_bf16 v[22:25], v[228:231], v[212:215], v[22:25]
	v_mfma_f32_16x16x32_bf16 v[26:29], v[232:235], v[212:215], v[26:29]
	v_mfma_f32_16x16x32_bf16 v[30:33], v[236:239], v[212:215], v[30:33]
	s_waitcnt lgkmcnt(1)
	v_mfma_f32_16x16x32_bf16 v[34:37], v[224:227], v[216:219], v[34:37]
	v_mfma_f32_16x16x32_bf16 v[38:41], v[228:231], v[216:219], v[38:41]
	v_mfma_f32_16x16x32_bf16 v[42:45], v[232:235], v[216:219], v[42:45]
	v_mfma_f32_16x16x32_bf16 v[46:49], v[236:239], v[216:219], v[46:49]
	s_waitcnt lgkmcnt(0)
	v_mfma_f32_16x16x32_bf16 v[50:53], v[224:227], v[220:223], v[50:53]
	v_mfma_f32_16x16x32_bf16 v[54:57], v[228:231], v[220:223], v[54:57]
	v_mfma_f32_16x16x32_bf16 v[58:61], v[232:235], v[220:223], v[58:61]
	v_mfma_f32_16x16x32_bf16 v[62:65], v[236:239], v[220:223], v[62:65]
	s_waitcnt vmcnt(0)
	s_barrier
	ds_read_b128 v[208:211], v240 offset:49152
	ds_read_b128 v[224:227], v241 offset:49152
	ds_read_b128 v[228:231], v241 offset:50176
	ds_read_b128 v[232:235], v241 offset:51200
	ds_read_b128 v[236:239], v241 offset:52224
	ds_read_b128 v[212:215], v240 offset:50176
	ds_read_b128 v[216:219], v240 offset:51200
	ds_read_b128 v[220:223], v240 offset:52224
	s_waitcnt lgkmcnt(6)
	v_mfma_f32_16x16x32_bf16 v[2:5], v[224:227], v[208:211], v[2:5]
	s_waitcnt lgkmcnt(5)
	v_mfma_f32_16x16x32_bf16 v[6:9], v[228:231], v[208:211], v[6:9]
	s_waitcnt lgkmcnt(4)
	v_mfma_f32_16x16x32_bf16 v[10:13], v[232:235], v[208:211], v[10:13]
	s_waitcnt lgkmcnt(3)
	v_mfma_f32_16x16x32_bf16 v[14:17], v[236:239], v[208:211], v[14:17]
	s_waitcnt lgkmcnt(2)
	v_mfma_f32_16x16x32_bf16 v[18:21], v[224:227], v[212:215], v[18:21]
	v_mfma_f32_16x16x32_bf16 v[22:25], v[228:231], v[212:215], v[22:25]
	v_mfma_f32_16x16x32_bf16 v[26:29], v[232:235], v[212:215], v[26:29]
	v_mfma_f32_16x16x32_bf16 v[30:33], v[236:239], v[212:215], v[30:33]
	s_waitcnt lgkmcnt(1)
	v_mfma_f32_16x16x32_bf16 v[34:37], v[224:227], v[216:219], v[34:37]
	v_mfma_f32_16x16x32_bf16 v[38:41], v[228:231], v[216:219], v[38:41]
	v_mfma_f32_16x16x32_bf16 v[42:45], v[232:235], v[216:219], v[42:45]
	v_mfma_f32_16x16x32_bf16 v[46:49], v[236:239], v[216:219], v[46:49]
	s_waitcnt lgkmcnt(0)
	v_mfma_f32_16x16x32_bf16 v[50:53], v[224:227], v[220:223], v[50:53]
	v_mfma_f32_16x16x32_bf16 v[54:57], v[228:231], v[220:223], v[54:57]
	v_mfma_f32_16x16x32_bf16 v[58:61], v[232:235], v[220:223], v[58:61]
	v_mfma_f32_16x16x32_bf16 v[62:65], v[236:239], v[220:223], v[62:65]
	s_add_u32 s46, s46, 0x10000
	s_addc_u32 s47, s47, 0
	s_add_u32 s48, s48, 0x1000000
	s_addc_u32 s49, s49, 0
	s_add_u32 s50, s50, 0x100000
	s_addc_u32 s51, s51, 0
	s_cmp_eq_u32 s75, 2
	s_cbranch_scc1 .Lbr_noprol
	s_mov_b64 s[28:29], s[44:45]
	s_mov_b64 s[30:31], s[46:47]
	s_add_u32 m0, s52, 0x0
	s_nop 0
	global_load_lds_dwordx4 v251, s[28:29]
	global_load_lds_dwordx4 v251, s[28:29] offset:1024
	s_add_u32 m0, s53, 0x0
	s_nop 0
	global_load_lds_dwordx4 v251, s[30:31]
	global_load_lds_dwordx4 v251, s[30:31] offset:1024
	s_add_u32 m0, s52, 0x4000
	s_add_u32 s28, s28, 0x100000
	s_addc_u32 s29, s29, 0
	global_load_lds_dwordx4 v251, s[28:29]
	global_load_lds_dwordx4 v251, s[28:29] offset:1024
	s_add_u32 m0, s53, 0x4000
	s_add_u32 s30, s30, 0x30000
	s_addc_u32 s31, s31, 0
	global_load_lds_dwordx4 v251, s[30:31]
	global_load_lds_dwordx4 v251, s[30:31] offset:1024
	s_add_u32 m0, s52, 0x8000
	s_add_u32 s28, s28, 0x100000
	s_addc_u32 s29, s29, 0
	global_load_lds_dwordx4 v251, s[28:29]
	global_load_lds_dwordx4 v251, s[28:29] offset:1024
	s_add_u32 m0, s53, 0x8000
	s_add_u32 s30, s30, 0x30000
	s_addc_u32 s31, s31, 0
	global_load_lds_dwordx4 v251, s[30:31]
	global_load_lds_dwordx4 v251, s[30:31] offset:1024

; DI RowSS rowss_load(const float* ps, int m0) { const int tid = TID(); const float* q = ps + (size_t)(m0 + (tid >> 1)) * 16 + (tid & 1) * 8; RowSS r; r.a = *(const f32x4*)q; r.b = *(const f32x4*)(q + 4); return r; }
; DI void tile_inproj(const Params& p, int l, const Chunk& ck, int tile, int next, PF& pf, char* smem) {
;   float* Cs = (float*)smem; float* rinv_s = (float*)(smem + SMEM_CS);
;   const int mi = tile & (MTN - 1), nj = tile >> MTS; const int ni = (nj < 45) ? nj : 69; const int m0 = mi * 128;
;   const u16* Ap; const u16* Wt; inproj_ptrs(p, l, tile, Ap, Wt);
;   f32x16 acc[2][2]; zero_acc(acc);
;   const RowSS rss = rowss_load((const float*)(p.ws + OFF_PSIN), m0);
;   gemm_run<16>(pf, Ap, 1024, Wt, acc, smem);
;   if (next >= 0) { const u16* An; const u16* Wn; inproj_ptrs(p, l, next, An, Wn); gemm_issue(pf, An, 1024, Wn, 1024); }
.LBB1_384:
	s_mov_b32 s0, s16
	s_add_i32 s16, s16, s78
	s_cmpk_gt_i32 s16, 0x16ff
	s_cselect_b64 s[28:29], -1, 0
	s_cmpk_lt_i32 s16, 0x1700
	s_cselect_b32 s34, s16, -1
	s_ashr_i32 s0, s0, 7
	s_cmp_lt_i32 s0, 45
	s_cselect_b64 s[36:37], -1, 0
	s_and_b64 s[30:31], s[36:37], exec
	v_mov_b32_e32 v0, v172
	s_cselect_b32 s30, s0, 0x45
	s_and_b32 s79, s75, 0x3f80
	s_and_b32 s0, s43, 0xfe0000
	s_waitcnt lgkmcnt(0)
	v_ashrrev_i32_e32 v2, 1, v0
	v_add_u32_e32 v2, s79, v2
	v_ashrrev_i32_e32 v3, 31, v2
	v_lshlrev_b64 v[2:3], 6, v[2:3]
	v_lshlrev_b32_e32 v0, 5, v0
	v_lshl_add_u64 v[2:3], s[20:21], 0, v[2:3]
	v_and_b32_e32 v0, 32, v0
	v_lshl_add_u64 v[2:3], v[2:3], 0, v[0:1]
	global_load_dwordx4 v[130:133], v[2:3], off offset:16
	global_load_dwordx4 v[134:137], v[2:3], off
	s_lshr_b32 s0, s0, 4
	s_add_u32 s40, s17, s0
	s_addc_u32 s41, s42, 0
	s_ashr_i32 s31, s30, 31
	s_lshl_b64 s[56:57], s[30:31], 18
	s_add_u32 vcc_lo, s52, s56
	s_addc_u32 vcc_hi, s53, s57
	s_setprio 0
	s_waitcnt lgkmcnt(0)
	s_cmp_lg_u32 s14, 0
	s_cbranch_scc1 .Linp_pass1
	s_mov_b64 s[48:49], s[40:41]
	s_lshl_b32 s15, s30, 13
	s_add_u32 s50, s52, s15
	s_addc_u32 s51, s53, 0
	s_mov_b32 s13, 0x5a000
	v_and_b32_e32 v144, 63, v172
	v_lshrrev_b32_e32 v145, 6, v172
	v_bfe_u32 v146, v144, 4, 2
	v_lshrrev_b32_e32 v147, 1, v146
	v_xor_b32_e32 v146, v146, v147
	v_and_b32_e32 v146, 1, v146
	v_lshl_or_b32 v146, v146, 1, v147
	v_xor_b32_e32 v146, v146, v144
	v_and_b32_e32 v146, 3, v146
	v_lshlrev_b32_e32 v146, 4, v146
	v_lshrrev_b32_e32 v147, 2, v144
	v_lshl_add_u32 v138, v145, 5, v147
	v_lshl_add_u32 v138, v138, 6, v146
	v_mov_b32_e32 v139, v138
	v_lshl_add_u32 v140, v145, 6, v147
	v_lshl_add_u32 v140, v140, 6, v146
	v_mov_b32_e32 v141, v140
	v_mov_b32_e32 v142, v140
	v_mov_b32_e32 v143, v140
	v_readfirstlane_b32 s46, v145
	s_lshl_b32 s47, s46, 12
	s_lshl_b32 s46, s46, 11
	s_add_u32 s47, s47, 0x2000
	v_bfe_u32 v146, v144, 2, 2
	v_lshrrev_b32_e32 v147, 1, v146
	v_xor_b32_e32 v146, v146, v147
	v_and_b32_e32 v146, 1, v146
	v_lshl_or_b32 v146, v146, 1, v147
	v_lshrrev_b32_e32 v147, 4, v144
	v_xor_b32_e32 v146, v146, v147
	v_lshlrev_b32_e32 v146, 4, v146
	v_and_b32_e32 v144, 15, v144
	v_lshl_add_u32 v144, v144, 6, v146
	v_lshrrev_b32_e32 v146, 1, v145
	v_and_b32_e32 v147, 1, v145
	v_lshl_add_u32 v126, v146, 12, v144
	v_lshl_add_u32 v128, v147, 12, v144
	v_add_u32_e32 v128, 0x2000, v128
	s_cmp_eq_u32 s30, 44
	s_cselect_b32 s15, 1, 0
	s_cmp_ge_u32 s46, 0x1000
	s_cselect_b32 s15, s15, 0
	s_cmp_lg_u32 s15, 0
	s_cbranch_scc0 .Linp_nokr
	s_add_u32 s50, s52, 0x113e000
	s_addc_u32 s51, s53, 0
	s_mov_b32 s13, 0x2000
.Linp_nokr:
	s_barrier
	v_mov_b32_e32 v2, 0
	v_mov_b32_e32 v3, 0
	v_mov_b32_e32 v4, 0
	v_mov_b32_e32 v5, 0
	v_mov_b32_e32 v6, 0
	v_mov_b32_e32 v7, 0
	v_mov_b32_e32 v8, 0
	v_mov_b32_e32 v9, 0
	v_mov_b32_e32 v10, 0
	v_mov_b32_e32 v11, 0
	v_mov_b32_e32 v12, 0
	v_mov_b32_e32 v13, 0
	v_mov_b32_e32 v14, 0
	v_mov_b32_e32 v15, 0
	v_mov_b32_e32 v16, 0
	v_mov_b32_e32 v17, 0
	v_mov_b32_e32 v18, 0
	v_mov_b32_e32 v19, 0
	v_mov_b32_e32 v20, 0
	v_mov_b32_e32 v21, 0
	v_mov_b32_e32 v22, 0
	v_mov_b32_e32 v23, 0
	v_mov_b32_e32 v24, 0
	v_mov_b32_e32 v25, 0
	v_mov_b32_e32 v26, 0
	v_mov_b32_e32 v27, 0
	v_mov_b32_e32 v28, 0
	v_mov_b32_e32 v29, 0
	v_mov_b32_e32 v30, 0
	v_mov_b32_e32 v31, 0
	v_mov_b32_e32 v32, 0
	v_mov_b32_e32 v33, 0
	v_mov_b32_e32 v34, 0
	v_mov_b32_e32 v35, 0
	v_mov_b32_e32 v36, 0
	v_mov_b32_e32 v37, 0
	v_mov_b32_e32 v38, 0
	v_mov_b32_e32 v39, 0
	v_mov_b32_e32 v40, 0
	v_mov_b32_e32 v41, 0
	v_mov_b32_e32 v42, 0
	v_mov_b32_e32 v43, 0
	v_mov_b32_e32 v44, 0
	v_mov_b32_e32 v45, 0
	v_mov_b32_e32 v46, 0
	v_mov_b32_e32 v47, 0
	v_mov_b32_e32 v48, 0
	v_mov_b32_e32 v49, 0
	v_mov_b32_e32 v50, 0
	v_mov_b32_e32 v51, 0
	v_mov_b32_e32 v52, 0
	v_mov_b32_e32 v53, 0
	v_mov_b32_e32 v54, 0
	v_mov_b32_e32 v55, 0
	v_mov_b32_e32 v56, 0
	v_mov_b32_e32 v57, 0
	v_mov_b32_e32 v58, 0
	v_mov_b32_e32 v59, 0
	v_mov_b32_e32 v60, 0
	v_mov_b32_e32 v61, 0
	v_mov_b32_e32 v62, 0
	v_mov_b32_e32 v63, 0
	v_mov_b32_e32 v64, 0
	v_mov_b32_e32 v65, 0
	v_mov_b32_e32 v74, 0
	v_mov_b32_e32 v75, 0
	v_mov_b32_e32 v76, 0
	v_mov_b32_e32 v77, 0
	v_mov_b32_e32 v78, 0
	v_mov_b32_e32 v79, 0
	v_mov_b32_e32 v80, 0
	v_mov_b32_e32 v81, 0
	v_mov_b32_e32 v82, 0
	v_mov_b32_e32 v83, 0
	v_mov_b32_e32 v84, 0
	v_mov_b32_e32 v85, 0
	v_mov_b32_e32 v86, 0
	v_mov_b32_e32 v87, 0
	v_mov_b32_e32 v88, 0
	v_mov_b32_e32 v89, 0
	v_mov_b32_e32 v90, 0
	v_mov_b32_e32 v91, 0
	v_mov_b32_e32 v92, 0
	v_mov_b32_e32 v93, 0
	v_mov_b32_e32 v94, 0
	v_mov_b32_e32 v95, 0
	v_mov_b32_e32 v96, 0
	v_mov_b32_e32 v97, 0
	v_mov_b32_e32 v98, 0
	v_mov_b32_e32 v99, 0
	v_mov_b32_e32 v100, 0
	v_mov_b32_e32 v101, 0
	v_mov_b32_e32 v102, 0
	v_mov_b32_e32 v103, 0
	v_mov_b32_e32 v104, 0
	v_mov_b32_e32 v105, 0
	v_mov_b32_e32 v106, 0
	v_mov_b32_e32 v107, 0
	v_mov_b32_e32 v108, 0
	v_mov_b32_e32 v109, 0
	v_mov_b32_e32 v110, 0
	v_mov_b32_e32 v111, 0
	v_mov_b32_e32 v112, 0
	v_mov_b32_e32 v113, 0
	v_mov_b32_e32 v114, 0
	v_mov_b32_e32 v115, 0
	v_mov_b32_e32 v116, 0
	v_mov_b32_e32 v117, 0
	v_mov_b32_e32 v118, 0
	v_mov_b32_e32 v119, 0
	v_mov_b32_e32 v120, 0
	v_mov_b32_e32 v121, 0
	v_mov_b32_e32 v208, 0
	v_mov_b32_e32 v209, 0
	v_mov_b32_e32 v210, 0
	v_mov_b32_e32 v211, 0
	v_mov_b32_e32 v212, 0
	v_mov_b32_e32 v213, 0
	v_mov_b32_e32 v214, 0
	v_mov_b32_e32 v215, 0
	v_mov_b32_e32 v216, 0
	v_mov_b32_e32 v217, 0
	v_mov_b32_e32 v218, 0
	v_mov_b32_e32 v219, 0
	v_mov_b32_e32 v220, 0
	v_mov_b32_e32 v221, 0
	v_mov_b32_e32 v222, 0
	v_mov_b32_e32 v223, 0
	s_add_u32 m0, s46, 0x0
	s_nop 0
	global_load_lds_dwordx4 v138, s[48:49]
	global_load_lds_dwordx4 v139, s[48:49] offset:1024
	s_add_u32 m0, s47, 0x0
	s_nop 0
	global_load_lds_dwordx4 v140, s[50:51]
	global_load_lds_dwordx4 v141, s[50:51] offset:1024
	global_load_lds_dwordx4 v142, s[50:51] offset:2048
	global_load_lds_dwordx4 v143, s[50:51] offset:3072
	s_add_u32 m0, s46, 0x6000
	s_add_u32 s48, s48, 0x100000
	s_addc_u32 s49, s49, 0
	global_load_lds_dwordx4 v138, s[48:49]
	global_load_lds_dwordx4 v139, s[48:49] offset:1024
	s_add_u32 m0, s47, 0x6000
	s_add_u32 s50, s50, s13
	s_addc_u32 s51, s51, 0
	global_load_lds_dwordx4 v140, s[50:51]
	global_load_lds_dwordx4 v141, s[50:51] offset:1024
	global_load_lds_dwordx4 v142, s[50:51] offset:2048
	global_load_lds_dwordx4 v143, s[50:51] offset:3072
	s_mov_b32 s12, 10
; #define BLOAD(A_, B_, kt) do { _Pragma("unroll") for (int i = 0; i < 4; ++i) { \
;     A_[i] = *(const u32x4*)((const char*)Ap + (aoff + (unsigned)(32 * i * lda + (kt) * 64) * 2u)); B_[i] = *(const u32x4*)((const char*)Wt + (woff + (unsigned)(32 * i * K + (kt) * 64) * 2u)); } } while (0)
; #define BLOAD(A_, B_, kt) do { _Pragma("unroll") for (int i = 0; i < 4; ++i) { \
;     A_[i] = *(const u32x4*)((const char*)Ap + (aoff + (unsigned)(32 * i * lda + (kt) * 64) * 2u)); B_[i] = *(const u32x4*)((const char*)Wt + (woff + (unsigned)(32 * i * K + (kt) * 64) * 2u)); } } while (0)
; #define BSTORE(A_, B_, buf) do { _Pragma("unroll") for (int i = 0; i < 4; ++i) { \
;     *(u32x4*)&As[(buf) * GBUF + (srow + 32 * i) * LDT + sc8] = A_[i]; \
;     *(u32x4*)&Bs[(buf) * GBUF + (srow + 32 * i) * LDT + sc8] = B_[i]; } } while (0)
; template <int NK>
; DI void gemm_run(PF& pf, const u16* __restrict__ Ap, int lda, const u16* __restrict__ Wt, f32x16 (&acc)[2][2], char* smem) {
;     ...
;   __builtin_amdgcn_s_setprio(0);
;   __syncthreads();
;   BSTORE(pf.a0, pf.b0, 0);
;   BLOAD(pf.a0, pf.b0, 2);
;   __syncthreads();
; #pragma unroll
;   for (int kt = 0; kt < nk; kt += 2) {
;     BCOMP(0);
;     BSTORE(pf.a1, pf.b1, 1);
;     if (kt + 3 < nk) BLOAD(pf.a1, pf.b1, kt + 3);
;     __syncthreads();
;     BCOMP(1);
;     if (kt + 2 < nk) { BSTORE(pf.a0, pf.b0, 0); if (kt + 4 < nk) BLOAD(pf.a0, pf.b0, kt + 4); }
;     __syncthreads();
;   }
.Linp_kloop:
	s_waitcnt vmcnt(6)
	s_barrier
	ds_read_b128 v[224:227], v126 offset:0
	ds_read_b128 v[240:243], v128 offset:0
	ds_read_b128 v[244:247], v128 offset:1024
	ds_read_b128 v[248:251], v128 offset:2048
	ds_read_b128 v[156:159], v128 offset:3072
	s_add_u32 m0, s46, 0xc000
	s_add_u32 s48, s48, 0x100000
	s_addc_u32 s49, s49, 0
	global_load_lds_dwordx4 v138, s[48:49]
	global_load_lds_dwordx4 v139, s[48:49] offset:1024
	s_add_u32 m0, s47, 0xc000
	s_add_u32 s50, s50, s13
	s_addc_u32 s51, s51, 0
	global_load_lds_dwordx4 v140, s[50:51]
	global_load_lds_dwordx4 v141, s[50:51] offset:1024
	global_load_lds_dwordx4 v142, s[50:51] offset:2048
	global_load_lds_dwordx4 v143, s[50:51] offset:3072
	ds_read_b128 v[228:231], v126 offset:1024
	ds_read_b128 v[232:235], v126 offset:2048
	ds_read_b128 v[236:239], v126 offset:3072
	ds_read_b128 v[160:163], v128 offset:8192
	ds_read_b128 v[164:167], v128 offset:9216
	ds_read_b128 v[168:171], v128 offset:10240
	ds_read_b128 v[122:125], v128 offset:11264
	s_waitcnt lgkmcnt(10)
	v_mfma_f32_16x16x32_bf16 v[2:5], v[224:227], v[240:243], v[2:5]
	s_waitcnt lgkmcnt(9)
	v_mfma_f32_16x16x32_bf16 v[6:9], v[224:227], v[244:247], v[6:9]
	s_waitcnt lgkmcnt(8)
	v_mfma_f32_16x16x32_bf16 v[10:13], v[224:227], v[248:251], v[10:13]
	s_waitcnt lgkmcnt(7)
	v_mfma_f32_16x16x32_bf16 v[14:17], v[224:227], v[156:159], v[14:17]
	s_waitcnt lgkmcnt(6)
	v_mfma_f32_16x16x32_bf16 v[18:21], v[228:231], v[240:243], v[18:21]
	v_mfma_f32_16x16x32_bf16 v[22:25], v[228:231], v[244:247], v[22:25]
	v_mfma_f32_16x16x32_bf16 v[26:29], v[228:231], v[248:251], v[26:29]
	v_mfma_f32_16x16x32_bf16 v[30:33], v[228:231], v[156:159], v[30:33]
	s_waitcnt lgkmcnt(5)
	v_mfma_f32_16x16x32_bf16 v[34:37], v[232:235], v[240:243], v[34:37]
	v_mfma_f32_16x16x32_bf16 v[38:41], v[232:235], v[244:247], v[38:41]
	v_mfma_f32_16x16x32_bf16 v[42:45], v[232:235], v[248:251], v[42:45]
	v_mfma_f32_16x16x32_bf16 v[46:49], v[232:235], v[156:159], v[46:49]
	s_waitcnt lgkmcnt(4)
	v_mfma_f32_16x16x32_bf16 v[50:53], v[236:239], v[240:243], v[50:53]
	v_mfma_f32_16x16x32_bf16 v[54:57], v[236:239], v[244:247], v[54:57]
	v_mfma_f32_16x16x32_bf16 v[58:61], v[236:239], v[248:251], v[58:61]
	v_mfma_f32_16x16x32_bf16 v[62:65], v[236:239], v[156:159], v[62:65]
	s_waitcnt lgkmcnt(3)
	v_mfma_f32_16x16x32_bf16 v[74:77], v[224:227], v[160:163], v[74:77]
	s_waitcnt lgkmcnt(2)
	v_mfma_f32_16x16x32_bf16 v[78:81], v[224:227], v[164:167], v[78:81]
	s_waitcnt lgkmcnt(1)
	v_mfma_f32_16x16x32_bf16 v[82:85], v[224:227], v[168:171], v[82:85]
	s_waitcnt lgkmcnt(0)
	v_mfma_f32_16x16x32_bf16 v[86:89], v[224:227], v[122:125], v[86:89]
	v_mfma_f32_16x16x32_bf16 v[90:93], v[228:231], v[160:163], v[90:93]
	v_mfma_f32_16x16x32_bf16 v[94:97], v[228:231], v[164:167], v[94:97]
	v_mfma_f32_16x16x32_bf16 v[98:101], v[228:231], v[168:171], v[98:101]
	v_mfma_f32_16x16x32_bf16 v[102:105], v[228:231], v[122:125], v[102:105]
	v_mfma_f32_16x16x32_bf16 v[106:109], v[232:235], v[160:163], v[106:109]
	v_mfma_f32_16x16x32_bf16 v[110:113], v[232:235], v[164:167], v[110:113]
	v_mfma_f32_16x16x32_bf16 v[114:117], v[232:235], v[168:171], v[114:117]
	v_mfma_f32_16x16x32_bf16 v[118:121], v[232:235], v[122:125], v[118:121]
	v_mfma_f32_16x16x32_bf16 v[208:211], v[236:239], v[160:163], v[208:211]
	v_mfma_f32_16x16x32_bf16 v[212:215], v[236:239], v[164:167], v[212:215]
	v_mfma_f32_16x16x32_bf16 v[216:219], v[236:239], v[168:171], v[216:219]
	v_mfma_f32_16x16x32_bf16 v[220:223], v[236:239], v[122:125], v[220:223]
	s_waitcnt vmcnt(6)
	s_barrier
	ds_read_b128 v[224:227], v126 offset:24576
	ds_read_b128 v[240:243], v128 offset:24576
	ds_read_b128 v[244:247], v128 offset:25600
	ds_read_b128 v[248:251], v128 offset:26624
	ds_read_b128 v[156:159], v128 offset:27648
	s_add_u32 m0, s46, 0x0
	s_add_u32 s48, s48, 0x100000
	s_addc_u32 s49, s49, 0
	global_load_lds_dwordx4 v138, s[48:49]
	global_load_lds_dwordx4 v139, s[48:49] offset:1024
	s_add_u32 m0, s47, 0x0
	s_add_u32 s50, s50, s13
	s_addc_u32 s51, s51, 0
	global_load_lds_dwordx4 v140, s[50:51]
	global_load_lds_dwordx4 v141, s[50:51] offset:1024
	global_load_lds_dwordx4 v142, s[50:51] offset:2048
	global_load_lds_dwordx4 v143, s[50:51] offset:3072
	ds_read_b128 v[228:231], v126 offset:25600
	ds_read_b128 v[232:235], v126 offset:26624
	ds_read_b128 v[236:239], v126 offset:27648
	ds_read_b128 v[160:163], v128 offset:32768
	ds_read_b128 v[164:167], v128 offset:33792
	ds_read_b128 v[168:171], v128 offset:34816
	ds_read_b128 v[122:125], v128 offset:35840
	s_waitcnt lgkmcnt(10)
	v_mfma_f32_16x16x32_bf16 v[2:5], v[224:227], v[240:243], v[2:5]
	s_waitcnt lgkmcnt(9)
	v_mfma_f32_16x16x32_bf16 v[6:9], v[224:227], v[244:247], v[6:9]
	s_waitcnt lgkmcnt(8)
	v_mfma_f32_16x16x32_bf16 v[10:13], v[224:227], v[248:251], v[10:13]
	s_waitcnt lgkmcnt(7)
	v_mfma_f32_16x16x32_bf16 v[14:17], v[224:227], v[156:159], v[14:17]
	s_waitcnt lgkmcnt(6)
	v_mfma_f32_16x16x32_bf16 v[18:21], v[228:231], v[240:243], v[18:21]
	v_mfma_f32_16x16x32_bf16 v[22:25], v[228:231], v[244:247], v[22:25]
	v_mfma_f32_16x16x32_bf16 v[26:29], v[228:231], v[248:251], v[26:29]
	v_mfma_f32_16x16x32_bf16 v[30:33], v[228:231], v[156:159], v[30:33]
	s_waitcnt lgkmcnt(5)
	v_mfma_f32_16x16x32_bf16 v[34:37], v[232:235], v[240:243], v[34:37]
	v_mfma_f32_16x16x32_bf16 v[38:41], v[232:235], v[244:247], v[38:41]
	v_mfma_f32_16x16x32_bf16 v[42:45], v[232:235], v[248:251], v[42:45]
	v_mfma_f32_16x16x32_bf16 v[46:49], v[232:235], v[156:159], v[46:49]
	s_waitcnt lgkmcnt(4)
	v_mfma_f32_16x16x32_bf16 v[50:53], v[236:239], v[240:243], v[50:53]
	v_mfma_f32_16x16x32_bf16 v[54:57], v[236:239], v[244:247], v[54:57]
	v_mfma_f32_16x16x32_bf16 v[58:61], v[236:239], v[248:251], v[58:61]
	v_mfma_f32_16x16x32_bf16 v[62:65], v[236:239], v[156:159], v[62:65]
	s_waitcnt lgkmcnt(3)
	v_mfma_f32_16x16x32_bf16 v[74:77], v[224:227], v[160:163], v[74:77]
	s_waitcnt lgkmcnt(2)
	v_mfma_f32_16x16x32_bf16 v[78:81], v[224:227], v[164:167], v[78:81]
	s_waitcnt lgkmcnt(1)
	v_mfma_f32_16x16x32_bf16 v[82:85], v[224:227], v[168:171], v[82:85]
	s_waitcnt lgkmcnt(0)
	v_mfma_f32_16x16x32_bf16 v[86:89], v[224:227], v[122:125], v[86:89]
	v_mfma_f32_16x16x32_bf16 v[90:93], v[228:231], v[160:163], v[90:93]
	v_mfma_f32_16x16x32_bf16 v[94:97], v[228:231], v[164:167], v[94:97]
	v_mfma_f32_16x16x32_bf16 v[98:101], v[228:231], v[168:171], v[98:101]
	v_mfma_f32_16x16x32_bf16 v[102:105], v[228:231], v[122:125], v[102:105]
	v_mfma_f32_16x16x32_bf16 v[106:109], v[232:235], v[160:163], v[106:109]
	v_mfma_f32_16x16x32_bf16 v[110:113], v[232:235], v[164:167], v[110:113]
	v_mfma_f32_16x16x32_bf16 v[114:117], v[232:235], v[168:171], v[114:117]
	v_mfma_f32_16x16x32_bf16 v[118:121], v[232:235], v[122:125], v[118:121]
	v_mfma_f32_16x16x32_bf16 v[208:211], v[236:239], v[160:163], v[208:211]
	v_mfma_f32_16x16x32_bf16 v[212:215], v[236:239], v[164:167], v[212:215]
	v_mfma_f32_16x16x32_bf16 v[216:219], v[236:239], v[168:171], v[216:219]
	v_mfma_f32_16x16x32_bf16 v[220:223], v[236:239], v[122:125], v[220:223]
	s_waitcnt vmcnt(6)
	s_barrier
; #define BLOAD(A_, B_, kt) do { _Pragma("unroll") for (int i = 0; i < 4; ++i) { \
;     A_[i] = *(const u32x4*)((const char*)Ap + (aoff + (unsigned)(32 * i * lda + (kt) * 64) * 2u)); B_[i] = *(const u32x4*)((const char*)Wt + (woff + (unsigned)(32 * i * K + (kt) * 64) * 2u)); } } while (0)
; #define BLOAD(A_, B_, kt) do { _Pragma("unroll") for (int i = 0; i < 4; ++i) { \
;     A_[i] = *(const u32x4*)((const char*)Ap + (aoff + (unsigned)(32 * i * lda + (kt) * 64) * 2u)); B_[i] = *(const u32x4*)((const char*)Wt + (woff + (unsigned)(32 * i * K + (kt) * 64) * 2u)); } } while (0)
; #define BSTORE(A_, B_, buf) do { _Pragma("unroll") for (int i = 0; i < 4; ++i) { \
;     *(u32x4*)&As[(buf) * GBUF + (srow + 32 * i) * LDT + sc8] = A_[i]; \
;     *(u32x4*)&Bs[(buf) * GBUF + (srow + 32 * i) * LDT + sc8] = B_[i]; } } while (0)
; template <int NK>
; DI void gemm_run(PF& pf, const u16* __restrict__ Ap, int lda, const u16* __restrict__ Wt, f32x16 (&acc)[2][2], char* smem) {
;     ...
;   __builtin_amdgcn_s_setprio(0);
;   __syncthreads();
;   BSTORE(pf.a0, pf.b0, 0);
;   BLOAD(pf.a0, pf.b0, 2);
;   __syncthreads();
; #pragma unroll
;   for (int kt = 0; kt < nk; kt += 2) {
;     BCOMP(0);
;     BSTORE(pf.a1, pf.b1, 1);
;     if (kt + 3 < nk) BLOAD(pf.a1, pf.b1, kt + 3);
;     __syncthreads();
;     BCOMP(1);
;     if (kt + 2 < nk) { BSTORE(pf.a0, pf.b0, 0); if (kt + 4 < nk) BLOAD(pf.a0, pf.b0, kt + 4); }
;     __syncthreads();
;   }
	ds_read_b128 v[224:227], v126 offset:49152
	ds_read_b128 v[240:243], v128 offset:49152
	ds_read_b128 v[244:247], v128 offset:50176
	ds_read_b128 v[248:251], v128 offset:51200
	ds_read_b128 v[156:159], v128 offset:52224
	s_add_u32 m0, s46, 0x6000
	s_add_u32 s48, s48, 0x100000
	s_addc_u32 s49, s49, 0
	global_load_lds_dwordx4 v138, s[48:49]
	global_load_lds_dwordx4 v139, s[48:49] offset:1024
	s_add_u32 m0, s47, 0x6000
	s_add_u32 s50, s50, s13
	s_addc_u32 s51, s51, 0
	global_load_lds_dwordx4 v140, s[50:51]
	global_load_lds_dwordx4 v141, s[50:51] offset:1024
	global_load_lds_dwordx4 v142, s[50:51] offset:2048
	global_load_lds_dwordx4 v143, s[50:51] offset:3072
	ds_read_b128 v[228:231], v126 offset:50176
	ds_read_b128 v[232:235], v126 offset:51200
	ds_read_b128 v[236:239], v126 offset:52224
	ds_read_b128 v[160:163], v128 offset:57344
	ds_read_b128 v[164:167], v128 offset:58368
	ds_read_b128 v[168:171], v128 offset:59392
	ds_read_b128 v[122:125], v128 offset:60416
	s_waitcnt lgkmcnt(10)
	v_mfma_f32_16x16x32_bf16 v[2:5], v[224:227], v[240:243], v[2:5]
	s_waitcnt lgkmcnt(9)
	v_mfma_f32_16x16x32_bf16 v[6:9], v[224:227], v[244:247], v[6:9]
	s_waitcnt lgkmcnt(8)
	v_mfma_f32_16x16x32_bf16 v[10:13], v[224:227], v[248:251], v[10:13]
	s_waitcnt lgkmcnt(7)
	v_mfma_f32_16x16x32_bf16 v[14:17], v[224:227], v[156:159], v[14:17]
	s_waitcnt lgkmcnt(6)
	v_mfma_f32_16x16x32_bf16 v[18:21], v[228:231], v[240:243], v[18:21]
	v_mfma_f32_16x16x32_bf16 v[22:25], v[228:231], v[244:247], v[22:25]
	v_mfma_f32_16x16x32_bf16 v[26:29], v[228:231], v[248:251], v[26:29]
	v_mfma_f32_16x16x32_bf16 v[30:33], v[228:231], v[156:159], v[30:33]
	s_waitcnt lgkmcnt(5)
	v_mfma_f32_16x16x32_bf16 v[34:37], v[232:235], v[240:243], v[34:37]
	v_mfma_f32_16x16x32_bf16 v[38:41], v[232:235], v[244:247], v[38:41]
	v_mfma_f32_16x16x32_bf16 v[42:45], v[232:235], v[248:251], v[42:45]
	v_mfma_f32_16x16x32_bf16 v[46:49], v[232:235], v[156:159], v[46:49]
	s_waitcnt lgkmcnt(4)
	v_mfma_f32_16x16x32_bf16 v[50:53], v[236:239], v[240:243], v[50:53]
	v_mfma_f32_16x16x32_bf16 v[54:57], v[236:239], v[244:247], v[54:57]
	v_mfma_f32_16x16x32_bf16 v[58:61], v[236:239], v[248:251], v[58:61]
	v_mfma_f32_16x16x32_bf16 v[62:65], v[236:239], v[156:159], v[62:65]
	s_waitcnt lgkmcnt(3)
	v_mfma_f32_16x16x32_bf16 v[74:77], v[224:227], v[160:163], v[74:77]
	s_waitcnt lgkmcnt(2)
	v_mfma_f32_16x16x32_bf16 v[78:81], v[224:227], v[164:167], v[78:81]
	s_waitcnt lgkmcnt(1)
	v_mfma_f32_16x16x32_bf16 v[82:85], v[224:227], v[168:171], v[82:85]
	s_waitcnt lgkmcnt(0)
	v_mfma_f32_16x16x32_bf16 v[86:89], v[224:227], v[122:125], v[86:89]
	v_mfma_f32_16x16x32_bf16 v[90:93], v[228:231], v[160:163], v[90:93]
	v_mfma_f32_16x16x32_bf16 v[94:97], v[228:231], v[164:167], v[94:97]
	v_mfma_f32_16x16x32_bf16 v[98:101], v[228:231], v[168:171], v[98:101]
	v_mfma_f32_16x16x32_bf16 v[102:105], v[228:231], v[122:125], v[102:105]
	v_mfma_f32_16x16x32_bf16 v[106:109], v[232:235], v[160:163], v[106:109]
	v_mfma_f32_16x16x32_bf16 v[110:113], v[232:235], v[164:167], v[110:113]
	v_mfma_f32_16x16x32_bf16 v[114:117], v[232:235], v[168:171], v[114:117]
	v_mfma_f32_16x16x32_bf16 v[118:121], v[232:235], v[122:125], v[118:121]
	v_mfma_f32_16x16x32_bf16 v[208:211], v[236:239], v[160:163], v[208:211]
	v_mfma_f32_16x16x32_bf16 v[212:215], v[236:239], v[164:167], v[212:215]
	v_mfma_f32_16x16x32_bf16 v[216:219], v[236:239], v[168:171], v[216:219]
	v_mfma_f32_16x16x32_bf16 v[220:223], v[236:239], v[122:125], v[220:223]
	s_sub_u32 s12, s12, 1
	s_cmp_lg_u32 s12, 0
	s_cbranch_scc1 .Linp_kloop
	s_waitcnt vmcnt(6)
	s_barrier
; #define BLOAD(A_, B_, kt) do { _Pragma("unroll") for (int i = 0; i < 4; ++i) { \
;     A_[i] = *(const u32x4*)((const char*)Ap + (aoff + (unsigned)(32 * i * lda + (kt) * 64) * 2u)); B_[i] = *(const u32x4*)((const char*)Wt + (woff + (unsigned)(32 * i * K + (kt) * 64) * 2u)); } } while (0)
; #define BLOAD(A_, B_, kt) do { _Pragma("unroll") for (int i = 0; i < 4; ++i) { \
;     A_[i] = *(const u32x4*)((const char*)Ap + (aoff + (unsigned)(32 * i * lda + (kt) * 64) * 2u)); B_[i] = *(const u32x4*)((const char*)Wt + (woff + (unsigned)(32 * i * K + (kt) * 64) * 2u)); } } while (0)
; #define BSTORE(A_, B_, buf) do { _Pragma("unroll") for (int i = 0; i < 4; ++i) { \
;     *(u32x4*)&As[(buf) * GBUF + (srow + 32 * i) * LDT + sc8] = A_[i]; \
;     *(u32x4*)&Bs[(buf) * GBUF + (srow + 32 * i) * LDT + sc8] = B_[i]; } } while (0)
; template <int NK>
; DI void gemm_run(PF& pf, const u16* __restrict__ Ap, int lda, const u16* __restrict__ Wt, f32x16 (&acc)[2][2], char* smem) {
;     ...
;   for (int kt = 0; kt < nk; kt += 2) {
;     BCOMP(0);
;     BSTORE(pf.a1, pf.b1, 1);
;     if (kt + 3 < nk) BLOAD(pf.a1, pf.b1, kt + 3);
;     __syncthreads();
;     BCOMP(1);
;     if (kt + 2 < nk) { BSTORE(pf.a0, pf.b0, 0); if (kt + 4 < nk) BLOAD(pf.a0, pf.b0, kt + 4); }
;     __syncthreads();
;   }
	ds_read_b128 v[224:227], v126 offset:0
	ds_read_b128 v[240:243], v128 offset:0
	ds_read_b128 v[244:247], v128 offset:1024
	ds_read_b128 v[248:251], v128 offset:2048
	ds_read_b128 v[156:159], v128 offset:3072
	ds_read_b128 v[228:231], v126 offset:1024
	ds_read_b128 v[232:235], v126 offset:2048
	ds_read_b128 v[236:239], v126 offset:3072
	ds_read_b128 v[160:163], v128 offset:8192
	ds_read_b128 v[164:167], v128 offset:9216
	ds_read_b128 v[168:171], v128 offset:10240
	ds_read_b128 v[122:125], v128 offset:11264
	s_waitcnt lgkmcnt(10)
	v_mfma_f32_16x16x32_bf16 v[2:5], v[224:227], v[240:243], v[2:5]
	s_waitcnt lgkmcnt(9)
	v_mfma_f32_16x16x32_bf16 v[6:9], v[224:227], v[244:247], v[6:9]
	s_waitcnt lgkmcnt(8)
	v_mfma_f32_16x16x32_bf16 v[10:13], v[224:227], v[248:251], v[10:13]
	s_waitcnt lgkmcnt(7)
	v_mfma_f32_16x16x32_bf16 v[14:17], v[224:227], v[156:159], v[14:17]
	s_waitcnt lgkmcnt(6)
	v_mfma_f32_16x16x32_bf16 v[18:21], v[228:231], v[240:243], v[18:21]
	v_mfma_f32_16x16x32_bf16 v[22:25], v[228:231], v[244:247], v[22:25]
	v_mfma_f32_16x16x32_bf16 v[26:29], v[228:231], v[248:251], v[26:29]
	v_mfma_f32_16x16x32_bf16 v[30:33], v[228:231], v[156:159], v[30:33]
	s_waitcnt lgkmcnt(5)
	v_mfma_f32_16x16x32_bf16 v[34:37], v[232:235], v[240:243], v[34:37]
	v_mfma_f32_16x16x32_bf16 v[38:41], v[232:235], v[244:247], v[38:41]
	v_mfma_f32_16x16x32_bf16 v[42:45], v[232:235], v[248:251], v[42:45]
	v_mfma_f32_16x16x32_bf16 v[46:49], v[232:235], v[156:159], v[46:49]
	s_waitcnt lgkmcnt(4)
	v_mfma_f32_16x16x32_bf16 v[50:53], v[236:239], v[240:243], v[50:53]
	v_mfma_f32_16x16x32_bf16 v[54:57], v[236:239], v[244:247], v[54:57]
	v_mfma_f32_16x16x32_bf16 v[58:61], v[236:239], v[248:251], v[58:61]
	v_mfma_f32_16x16x32_bf16 v[62:65], v[236:239], v[156:159], v[62:65]
	s_waitcnt lgkmcnt(3)
	v_mfma_f32_16x16x32_bf16 v[74:77], v[224:227], v[160:163], v[74:77]
	s_waitcnt lgkmcnt(2)
	v_mfma_f32_16x16x32_bf16 v[78:81], v[224:227], v[164:167], v[78:81]
	s_waitcnt lgkmcnt(1)
	v_mfma_f32_16x16x32_bf16 v[82:85], v[224:227], v[168:171], v[82:85]
	s_waitcnt lgkmcnt(0)
	v_mfma_f32_16x16x32_bf16 v[86:89], v[224:227], v[122:125], v[86:89]
	v_mfma_f32_16x16x32_bf16 v[90:93], v[228:231], v[160:163], v[90:93]
	v_mfma_f32_16x16x32_bf16 v[94:97], v[228:231], v[164:167], v[94:97]
	v_mfma_f32_16x16x32_bf16 v[98:101], v[228:231], v[168:171], v[98:101]
	v_mfma_f32_16x16x32_bf16 v[102:105], v[228:231], v[122:125], v[102:105]
	v_mfma_f32_16x16x32_bf16 v[106:109], v[232:235], v[160:163], v[106:109]
	v_mfma_f32_16x16x32_bf16 v[110:113], v[232:235], v[164:167], v[110:113]
	v_mfma_f32_16x16x32_bf16 v[114:117], v[232:235], v[168:171], v[114:117]
	v_mfma_f32_16x16x32_bf16 v[118:121], v[232:235], v[122:125], v[118:121]
	v_mfma_f32_16x16x32_bf16 v[208:211], v[236:239], v[160:163], v[208:211]
	v_mfma_f32_16x16x32_bf16 v[212:215], v[236:239], v[164:167], v[212:215]
	v_mfma_f32_16x16x32_bf16 v[216:219], v[236:239], v[168:171], v[216:219]
	v_mfma_f32_16x16x32_bf16 v[220:223], v[236:239], v[122:125], v[220:223]
	s_waitcnt vmcnt(0)
	s_barrier
	ds_read_b128 v[224:227], v126 offset:24576
	ds_read_b128 v[240:243], v128 offset:24576
	ds_read_b128 v[244:247], v128 offset:25600
	ds_read_b128 v[248:251], v128 offset:26624
	ds_read_b128 v[156:159], v128 offset:27648
	ds_read_b128 v[228:231], v126 offset:25600
	ds_read_b128 v[232:235], v126 offset:26624
	ds_read_b128 v[236:239], v126 offset:27648
	ds_read_b128 v[160:163], v128 offset:32768
	ds_read_b128 v[164:167], v128 offset:33792
	ds_read_b128 v[168:171], v128 offset:34816
	ds_read_b128 v[122:125], v128 offset:35840
	s_waitcnt lgkmcnt(10)
	v_mfma_f32_16x16x32_bf16 v[2:5], v[224:227], v[240:243], v[2:5]
	s_waitcnt lgkmcnt(9)
	v_mfma_f32_16x16x32_bf16 v[6:9], v[224:227], v[244:247], v[6:9]
	s_waitcnt lgkmcnt(8)
	v_mfma_f32_16x16x32_bf16 v[10:13], v[224:227], v[248:251], v[10:13]
	s_waitcnt lgkmcnt(7)
	v_mfma_f32_16x16x32_bf16 v[14:17], v[224:227], v[156:159], v[14:17]
	s_waitcnt lgkmcnt(6)
	v_mfma_f32_16x16x32_bf16 v[18:21], v[228:231], v[240:243], v[18:21]
	v_mfma_f32_16x16x32_bf16 v[22:25], v[228:231], v[244:247], v[22:25]
	v_mfma_f32_16x16x32_bf16 v[26:29], v[228:231], v[248:251], v[26:29]
	v_mfma_f32_16x16x32_bf16 v[30:33], v[228:231], v[156:159], v[30:33]
	s_waitcnt lgkmcnt(5)
	v_mfma_f32_16x16x32_bf16 v[34:37], v[232:235], v[240:243], v[34:37]
	v_mfma_f32_16x16x32_bf16 v[38:41], v[232:235], v[244:247], v[38:41]
	v_mfma_f32_16x16x32_bf16 v[42:45], v[232:235], v[248:251], v[42:45]
	v_mfma_f32_16x16x32_bf16 v[46:49], v[232:235], v[156:159], v[46:49]
	s_waitcnt lgkmcnt(4)
	v_mfma_f32_16x16x32_bf16 v[50:53], v[236:239], v[240:243], v[50:53]
	v_mfma_f32_16x16x32_bf16 v[54:57], v[236:239], v[244:247], v[54:57]
	v_mfma_f32_16x16x32_bf16 v[58:61], v[236:239], v[248:251], v[58:61]
	v_mfma_f32_16x16x32_bf16 v[62:65], v[236:239], v[156:159], v[62:65]
	s_waitcnt lgkmcnt(3)
	v_mfma_f32_16x16x32_bf16 v[74:77], v[224:227], v[160:163], v[74:77]
	s_waitcnt lgkmcnt(2)
	v_mfma_f32_16x16x32_bf16 v[78:81], v[224:227], v[164:167], v[78:81]
	s_waitcnt lgkmcnt(1)
	v_mfma_f32_16x16x32_bf16 v[82:85], v[224:227], v[168:171], v[82:85]
	s_waitcnt lgkmcnt(0)
	v_mfma_f32_16x16x32_bf16 v[86:89], v[224:227], v[122:125], v[86:89]
	v_mfma_f32_16x16x32_bf16 v[90:93], v[228:231], v[160:163], v[90:93]
	v_mfma_f32_16x16x32_bf16 v[94:97], v[228:231], v[164:167], v[94:97]
	v_mfma_f32_16x16x32_bf16 v[98:101], v[228:231], v[168:171], v[98:101]
	v_mfma_f32_16x16x32_bf16 v[102:105], v[228:231], v[122:125], v[102:105]
	v_mfma_f32_16x16x32_bf16 v[106:109], v[232:235], v[160:163], v[106:109]
	v_mfma_f32_16x16x32_bf16 v[110:113], v[232:235], v[164:167], v[110:113]
	v_mfma_f32_16x16x32_bf16 v[114:117], v[232:235], v[168:171], v[114:117]
	v_mfma_f32_16x16x32_bf16 v[118:121], v[232:235], v[122:125], v[118:121]
	v_mfma_f32_16x16x32_bf16 v[208:211], v[236:239], v[160:163], v[208:211]
	v_mfma_f32_16x16x32_bf16 v[212:215], v[236:239], v[164:167], v[212:215]
	v_mfma_f32_16x16x32_bf16 v[216:219], v[236:239], v[168:171], v[216:219]
	v_mfma_f32_16x16x32_bf16 v[220:223], v[236:239], v[122:125], v[220:223]
	s_barrier
	s_branch .Linp_post
